# s_setprio 1 moved in front of the pre-MFMA s_barrier (32 sites) so the first MFMA is the first instruction after the barrier releases; on top of v64
# baseline (speedup 1.0000x reference)
;     __host__ __device__ __forceinline__ bool next(int i, Unit& u) const { const int vv = vid + (i / 5) * G; if (vv >= 256) return false; u.pm = vv >> 2; u.pn = (vv & 3) + 4 * (i % 5); return true; }
; #define PG8_STAGE(bufoff, gbase, voff) do { _Pragma("unroll") for (int _i = 0; _i < 2; ++_i) \
;         __builtin_amdgcn_global_load_lds((const unsigned*)((const char*)(gbase) + (voff)[_i]), (PG8_LAS unsigned*)(lds + (bufoff) + ldsw + _i * 8192), 16, 0, 0); } while (0)
; #define PG8_LDA(dst, b, h) do { _Pragma("unroll") for (int m = 0; m < 4; ++m) _Pragma("unroll") for (int k = 0; k < 2; ++k) dst[m][k] = *(const PG8_LAS bf16x8*)(lds + PG8_SA(b, h) + aoff + m * 2048 + k * 1024); } while (0)
; #define PG8_LDB(dst, b, h) do { _Pragma("unroll") for (int n = 0; n < 2; ++n) _Pragma("unroll") for (int k = 0; k < 2; ++k) dst[n][k] = *(const PG8_LAS bf16x8*)(lds + PG8_SB(b, h) + boff + n * 2048 + k * 1024); } while (0)
; #define PG8_WAIT_V(n) asm volatile("s_waitcnt vmcnt(" #n ")" ::: "memory")
; #define PG8_WAIT_L(n) asm volatile("s_waitcnt lgkmcnt(" #n ")" ::: "memory")
; #define PG8_BAR __builtin_amdgcn_s_barrier()
;     ...
;     for (;;) {
;         const bool has_next = S.next(ui + 1, nxt);
;         const char* nA = has_next ? (const char*)g.A + (size_t)nxt.pm * tstepA + (size_t)nxt.pn * APN + kofA : cA; const char* nB = has_next ? (const char*)g.Bt + (size_t)nxt.pn * tstepB + S.b_off(nxt) + kofB : cB;
;         for (int t = 0; t < nt; t += 2) {
;             const bool last = (t == nt - 2);
;             const char* a1 = cA + (ptrdiff_t)(t + 1) * kstepA;
;             const char* a2 = last ? nA : cA + (ptrdiff_t)(t + 2) * kstepA; const char* b2 = last ? nB : cB + (ptrdiff_t)(t + 2) * kstep;
;             const char* a3 = a2 + kstepA; const char* b3 = b2 + kstep;
;             if (last && has_next) S.a_ready(nxt);
;             if constexpr (SP2) {
;             PG8_LDB(B0, 0, 0); PG8_LDB(B1, 0, 1); PG8_SCHED; PG8_LDA(At, 0, 0); PG8_STAGE(PG8_SA(1, 1), a1 + hstepA, voffA);
;             PG8_WAIT_V(8); PG8_WAIT_L(0); PG8_BAR; PG8_MMA(0, 0, At, B0); PG8_MMA(0, 1, At, B1); PG8_BAR; PG8_SCHED;
;             PG8_LDA(At, 0, 1); PG8_STAGE(PG8_SB(0, 0), b2, voffB); PG8_STAGE(PG8_SB(0, 1), b2 + hstepB, voffB); PG8_STAGE(PG8_SA(0, 0), a2, voffA);
;             PG8_WAIT_V(8); PG8_WAIT_L(0); PG8_BAR; PG8_MMA(1, 0, At, B0); PG8_MMA(1, 1, At, B1); PG8_BAR; PG8_SCHED;
.LBB0_97:
	s_mov_b64 s[30:31], s[6:7]
	s_ashr_i32 s6, s14, 2
	s_and_b32 s6, s6, -8
	s_and_b32 s7, s14, 7
	s_mov_b32 s20, s58
	s_mov_b32 s21, s57
	v_cmp_lt_i64_e64 s[4:5], s[14:15], v[138:139]
	s_bfe_u32 s57, s14, 0x20003
	s_or_b32 s58, s6, s7
	s_and_b64 s[6:7], s[4:5], exec
	s_cselect_b32 s24, s58, s20
	s_cselect_b32 s6, s57, s21
	s_ashr_i32 s25, s24, 31
	s_lshl_b64 s[20:21], s[24:25], 20
	s_add_u32 s20, s2, s20
	s_addc_u32 s21, s3, s21
	s_ashr_i32 s7, s6, 31
	s_lshl_b64 s[6:7], s[6:7], 17
	s_add_u32 s20, s20, s6
	s_addc_u32 s21, s21, s7
	s_and_b64 s[28:29], s[4:5], exec
	ds_read_b128 v[0:3], v141
	ds_read_b128 v[4:7], v141 offset:1024
	ds_read_b128 v[8:11], v141 offset:2048
	ds_read_b128 v[12:15], v141 offset:3072
	ds_read_b128 v[16:19], v142
	ds_read_b128 v[20:23], v142 offset:1024
	ds_read_b128 v[24:27], v142 offset:2048
	ds_read_b128 v[28:31], v142 offset:3072
	s_cselect_b32 s29, s21, s27
	s_cselect_b32 s28, s20, s26
	s_add_u32 s25, s33, s6
	s_addc_u32 s34, s36, s7
	s_ashr_i32 s6, s24, 3
	s_ashr_i32 s7, s6, 31
	s_lshl_b64 s[6:7], s[6:7], 19
	s_add_u32 s6, s25, s6
	s_addc_u32 s7, s34, s7
	s_and_b64 s[24:25], s[4:5], exec
	s_cselect_b32 s25, s7, s31
	s_cselect_b32 s24, s6, s30
	s_add_u32 s60, s26, 0x10000
	s_addc_u32 s61, s27, 0
	s_add_u32 s34, s26, 0x18000
	s_addc_u32 s35, s27, 0
	s_add_u32 s62, s26, 0xc000
	s_addc_u32 s63, s27, 0
	s_mov_b32 m0, s46
	ds_read_b128 v[32:35], v143
	ds_read_b128 v[36:39], v143 offset:1024
	ds_read_b128 v[40:43], v143 offset:2048
	ds_read_b128 v[44:47], v143 offset:3072
	ds_read_b128 v[48:51], v143 offset:4096
	ds_read_b128 v[52:55], v143 offset:5120
	ds_read_b128 v[56:59], v143 offset:6144
	ds_read_b128 v[60:63], v143 offset:7168
	global_load_lds_dwordx4 v134, s[62:63]
	v_lshl_add_u64 v[64:65], s[62:63], 0, v[130:131]
	s_mov_b32 m0, s47
	s_nop 0
	global_load_lds_dwordx4 v[64:65], off
	s_waitcnt vmcnt(8)
	s_waitcnt lgkmcnt(0)
	s_setprio 1
	s_barrier
	v_mfma_f32_16x16x32_bf16 v[64:67], v[0:3], v[32:35], 0
	v_mfma_f32_16x16x32_bf16 v[64:67], v[4:7], v[36:39], v[64:67]
	v_mfma_f32_16x16x32_bf16 v[68:71], v[8:11], v[32:35], 0
	v_mfma_f32_16x16x32_bf16 v[68:71], v[12:15], v[36:39], v[68:71]
	v_mfma_f32_16x16x32_bf16 v[72:75], v[0:3], v[40:43], 0
	v_mfma_f32_16x16x32_bf16 v[72:75], v[4:7], v[44:47], v[72:75]
	v_mfma_f32_16x16x32_bf16 v[76:79], v[8:11], v[40:43], 0
	v_mfma_f32_16x16x32_bf16 v[76:79], v[12:15], v[44:47], v[76:79]
	v_mfma_f32_16x16x32_bf16 v[80:83], v[0:3], v[48:51], 0
	v_mfma_f32_16x16x32_bf16 v[80:83], v[4:7], v[52:55], v[80:83]
	v_mfma_f32_16x16x32_bf16 v[84:87], v[8:11], v[48:51], 0
	v_mfma_f32_16x16x32_bf16 v[84:87], v[12:15], v[52:55], v[84:87]
	v_mfma_f32_16x16x32_bf16 v[88:91], v[0:3], v[56:59], 0
	v_mfma_f32_16x16x32_bf16 v[88:91], v[4:7], v[60:63], v[88:91]
	v_mfma_f32_16x16x32_bf16 v[92:95], v[8:11], v[56:59], 0
	v_mfma_f32_16x16x32_bf16 v[92:95], v[12:15], v[60:63], v[92:95]
	s_setprio 0
	s_setprio 1
	v_mfma_f32_16x16x32_bf16 v[96:99], v[16:19], v[32:35], 0
	v_mfma_f32_16x16x32_bf16 v[96:99], v[20:23], v[36:39], v[96:99]
	v_mfma_f32_16x16x32_bf16 v[32:35], v[24:27], v[32:35], 0
	v_mfma_f32_16x16x32_bf16 v[32:35], v[28:31], v[36:39], v[32:35]
	v_mfma_f32_16x16x32_bf16 v[36:39], v[16:19], v[40:43], 0
	v_mfma_f32_16x16x32_bf16 v[36:39], v[20:23], v[44:47], v[36:39]
	v_mfma_f32_16x16x32_bf16 v[40:43], v[24:27], v[40:43], 0
	v_mfma_f32_16x16x32_bf16 v[40:43], v[28:31], v[44:47], v[40:43]
	v_mfma_f32_16x16x32_bf16 v[44:47], v[16:19], v[48:51], 0
	v_mfma_f32_16x16x32_bf16 v[44:47], v[20:23], v[52:55], v[44:47]
	v_mfma_f32_16x16x32_bf16 v[48:51], v[24:27], v[48:51], 0
	v_mfma_f32_16x16x32_bf16 v[48:51], v[28:31], v[52:55], v[48:51]
	v_mfma_f32_16x16x32_bf16 v[52:55], v[16:19], v[56:59], 0
	v_mfma_f32_16x16x32_bf16 v[52:55], v[20:23], v[60:63], v[52:55]
	v_mfma_f32_16x16x32_bf16 v[56:59], v[24:27], v[56:59], 0
	v_mfma_f32_16x16x32_bf16 v[56:59], v[28:31], v[60:63], v[56:59]
	s_setprio 0
	s_barrier
	v_lshl_add_u64 v[210:211], s[30:31], 0, v[132:133]
	s_mov_b32 m0, s48
	v_lshl_add_u64 v[146:147], v[210:211], 0, s[16:17]
	v_lshl_add_u64 v[212:213], s[30:31], 0, v[128:129]
	s_add_u32 s62, s30, 0x10100
	ds_read_b128 v[60:63], v143 offset:16384
	ds_read_b128 v[100:103], v143 offset:17408
	ds_read_b128 v[104:107], v143 offset:18432
	ds_read_b128 v[108:111], v143 offset:19456
	ds_read_b128 v[112:115], v143 offset:20480
	ds_read_b128 v[116:119], v143 offset:21504
	ds_read_b128 v[120:123], v143 offset:22528
	ds_read_b128 v[124:127], v143 offset:23552
	global_load_lds_dwordx4 v[146:147], off
	v_lshl_add_u64 v[146:147], v[212:213], 0, s[16:17]
	s_mov_b32 m0, s50
	s_addc_u32 s63, s31, 0
	global_load_lds_dwordx4 v[146:147], off
	s_mov_b32 m0, s51
	s_nop 0
	global_load_lds_dwordx4 v132, s[62:63]
	s_mov_b32 m0, s52
	s_nop 0
	global_load_lds_dwordx4 v128, s[62:63]
	s_mov_b32 m0, s23
	s_nop 0
	global_load_lds_dwordx4 v134, s[60:61]
	v_lshl_add_u64 v[146:147], s[60:61], 0, v[130:131]
	s_mov_b32 m0, s37
	s_nop 0
	global_load_lds_dwordx4 v[146:147], off
	s_waitcnt vmcnt(8)
	s_waitcnt lgkmcnt(0)
	s_setprio 1
	s_barrier
; #define PG8_STAGE(bufoff, gbase, voff) do { _Pragma("unroll") for (int _i = 0; _i < 2; ++_i) \
;         __builtin_amdgcn_global_load_lds((const unsigned*)((const char*)(gbase) + (voff)[_i]), (PG8_LAS unsigned*)(lds + (bufoff) + ldsw + _i * 8192), 16, 0, 0); } while (0)
; #define PG8_LDA(dst, b, h) do { _Pragma("unroll") for (int m = 0; m < 4; ++m) _Pragma("unroll") for (int k = 0; k < 2; ++k) dst[m][k] = *(const PG8_LAS bf16x8*)(lds + PG8_SA(b, h) + aoff + m * 2048 + k * 1024); } while (0)
; #define PG8_LDB(dst, b, h) do { _Pragma("unroll") for (int n = 0; n < 2; ++n) _Pragma("unroll") for (int k = 0; k < 2; ++k) dst[n][k] = *(const PG8_LAS bf16x8*)(lds + PG8_SB(b, h) + boff + n * 2048 + k * 1024); } while (0)
; #define PG8_MMA(ai, bj, At, Bt) do { __builtin_amdgcn_s_setprio(1); _Pragma("unroll") for (int m = 0; m < 4; ++m) _Pragma("unroll") for (int n = 0; n < 2; ++n) _Pragma("unroll") for (int k = 0; k < 2; ++k) \
;         acc[ai][bj][m][n] = __builtin_amdgcn_mfma_f32_16x16x32_bf16(Bt[n][k], At[m][k], acc[ai][bj][m][n], 0, 0, 0); __builtin_amdgcn_s_setprio(0); } while (0)
; #define PG8_WAIT_V(n) asm volatile("s_waitcnt vmcnt(" #n ")" ::: "memory")
; #define PG8_WAIT_L(n) asm volatile("s_waitcnt lgkmcnt(" #n ")" ::: "memory")
; #define PG8_BAR __builtin_amdgcn_s_barrier()
; #define PG8_SCHED __builtin_amdgcn_sched_barrier(0)
;     ...
;             PG8_WAIT_V(8); PG8_WAIT_L(0); PG8_BAR; PG8_MMA(0, 0, At, B0); PG8_MMA(0, 1, At, B1); PG8_BAR; PG8_SCHED;
;             PG8_LDA(At, 0, 1); PG8_STAGE(PG8_SB(0, 0), b2, voffB); PG8_STAGE(PG8_SB(0, 1), b2 + hstepB, voffB); PG8_STAGE(PG8_SA(0, 0), a2, voffA);
;             PG8_WAIT_V(8); PG8_WAIT_L(0); PG8_BAR; PG8_MMA(1, 0, At, B0); PG8_MMA(1, 1, At, B1); PG8_BAR; PG8_SCHED;
;             PG8_LDB(B0, 1, 0); PG8_LDB(B1, 1, 1); PG8_SCHED; PG8_LDA(At, 1, 0); PG8_STAGE(PG8_SA(0, 1), a2 + hstepA, voffA);
;             PG8_WAIT_V(8); PG8_WAIT_L(0); PG8_BAR; PG8_MMA(0, 0, At, B0); PG8_MMA(0, 1, At, B1); PG8_BAR; PG8_SCHED;
	v_mfma_f32_16x16x32_bf16 v[146:149], v[0:3], v[60:63], 0
	v_mfma_f32_16x16x32_bf16 v[146:149], v[4:7], v[100:103], v[146:149]
	v_mfma_f32_16x16x32_bf16 v[154:157], v[0:3], v[104:107], 0
	v_mfma_f32_16x16x32_bf16 v[154:157], v[4:7], v[108:111], v[154:157]
	v_mfma_f32_16x16x32_bf16 v[162:165], v[0:3], v[112:115], 0
	v_mfma_f32_16x16x32_bf16 v[162:165], v[4:7], v[116:119], v[162:165]
	v_mfma_f32_16x16x32_bf16 v[0:3], v[0:3], v[120:123], 0
	v_mfma_f32_16x16x32_bf16 v[0:3], v[4:7], v[124:127], v[0:3]
	v_mfma_f32_16x16x32_bf16 v[4:7], v[8:11], v[120:123], 0
	v_mfma_f32_16x16x32_bf16 v[4:7], v[12:15], v[124:127], v[4:7]
	v_mfma_f32_16x16x32_bf16 v[150:153], v[8:11], v[60:63], 0
	v_mfma_f32_16x16x32_bf16 v[150:153], v[12:15], v[100:103], v[150:153]
	v_mfma_f32_16x16x32_bf16 v[158:161], v[8:11], v[104:107], 0
	v_mfma_f32_16x16x32_bf16 v[158:161], v[12:15], v[108:111], v[158:161]
	v_mfma_f32_16x16x32_bf16 v[166:169], v[8:11], v[112:115], 0
	v_mfma_f32_16x16x32_bf16 v[166:169], v[12:15], v[116:119], v[166:169]
	s_setprio 0
	s_setprio 1
	v_mfma_f32_16x16x32_bf16 v[8:11], v[16:19], v[60:63], 0
	v_mfma_f32_16x16x32_bf16 v[8:11], v[20:23], v[100:103], v[8:11]
	v_mfma_f32_16x16x32_bf16 v[12:15], v[24:27], v[60:63], 0
	v_mfma_f32_16x16x32_bf16 v[12:15], v[28:31], v[100:103], v[12:15]
	v_mfma_f32_16x16x32_bf16 v[60:63], v[16:19], v[104:107], 0
	v_mfma_f32_16x16x32_bf16 v[60:63], v[20:23], v[108:111], v[60:63]
	v_mfma_f32_16x16x32_bf16 v[100:103], v[24:27], v[104:107], 0
	v_mfma_f32_16x16x32_bf16 v[100:103], v[28:31], v[108:111], v[100:103]
	v_mfma_f32_16x16x32_bf16 v[104:107], v[16:19], v[112:115], 0
	v_mfma_f32_16x16x32_bf16 v[104:107], v[20:23], v[116:119], v[104:107]
	v_mfma_f32_16x16x32_bf16 v[16:19], v[16:19], v[120:123], 0
	v_mfma_f32_16x16x32_bf16 v[16:19], v[20:23], v[124:127], v[16:19]
	v_mfma_f32_16x16x32_bf16 v[108:111], v[24:27], v[112:115], 0
	v_mfma_f32_16x16x32_bf16 v[108:111], v[28:31], v[116:119], v[108:111]
	v_mfma_f32_16x16x32_bf16 v[20:23], v[24:27], v[120:123], 0
	v_mfma_f32_16x16x32_bf16 v[20:23], v[28:31], v[124:127], v[20:23]
	s_setprio 0
	s_barrier
	ds_read_b128 v[24:27], v144
	ds_read_b128 v[28:31], v144 offset:1024
	ds_read_b128 v[112:115], v144 offset:2048
	ds_read_b128 v[116:119], v144 offset:3072
	ds_read_b128 v[120:123], v145
	ds_read_b128 v[124:127], v145 offset:1024
	ds_read_b128 v[170:173], v145 offset:2048
	ds_read_b128 v[174:177], v145 offset:3072
	s_add_u32 s60, s26, 0x14000
	s_addc_u32 s61, s27, 0
	s_mov_b32 m0, s39
	ds_read_b128 v[178:181], v143 offset:32768
	ds_read_b128 v[182:185], v143 offset:33792
	ds_read_b128 v[186:189], v143 offset:34816
	ds_read_b128 v[190:193], v143 offset:35840
	ds_read_b128 v[194:197], v143 offset:36864
	ds_read_b128 v[198:201], v143 offset:37888
	ds_read_b128 v[202:205], v143 offset:38912
	ds_read_b128 v[206:209], v143 offset:39936
	global_load_lds_dwordx4 v134, s[60:61]
	v_lshl_add_u64 v[214:215], s[60:61], 0, v[130:131]
	s_mov_b32 m0, s40
	s_nop 0
	global_load_lds_dwordx4 v[214:215], off
	s_waitcnt vmcnt(8)
	s_waitcnt lgkmcnt(0)
	s_setprio 1
	s_barrier
	v_mfma_f32_16x16x32_bf16 v[64:67], v[24:27], v[178:181], v[64:67]
	v_mfma_f32_16x16x32_bf16 v[64:67], v[28:31], v[182:185], v[64:67]
	v_mfma_f32_16x16x32_bf16 v[68:71], v[116:119], v[182:185], v[68:71]
	v_mfma_f32_16x16x32_bf16 v[68:71], v[112:115], v[178:181], v[68:71]
	v_mfma_f32_16x16x32_bf16 v[76:79], v[112:115], v[186:189], v[76:79]
	v_mfma_f32_16x16x32_bf16 v[76:79], v[116:119], v[190:193], v[76:79]
	v_mfma_f32_16x16x32_bf16 v[72:75], v[28:31], v[190:193], v[72:75]
	v_mfma_f32_16x16x32_bf16 v[72:75], v[24:27], v[186:189], v[72:75]
	v_mfma_f32_16x16x32_bf16 v[80:83], v[24:27], v[194:197], v[80:83]
	v_mfma_f32_16x16x32_bf16 v[80:83], v[28:31], v[198:201], v[80:83]
	v_mfma_f32_16x16x32_bf16 v[84:87], v[116:119], v[198:201], v[84:87]
	v_mfma_f32_16x16x32_bf16 v[84:87], v[112:115], v[194:197], v[84:87]
	v_mfma_f32_16x16x32_bf16 v[92:95], v[112:115], v[202:205], v[92:95]
	v_mfma_f32_16x16x32_bf16 v[92:95], v[116:119], v[206:209], v[92:95]
	v_mfma_f32_16x16x32_bf16 v[88:91], v[28:31], v[206:209], v[88:91]
	v_mfma_f32_16x16x32_bf16 v[88:91], v[24:27], v[202:205], v[88:91]
	s_setprio 0
	s_setprio 1
	v_mfma_f32_16x16x32_bf16 v[96:99], v[120:123], v[178:181], v[96:99]
	v_mfma_f32_16x16x32_bf16 v[96:99], v[124:127], v[182:185], v[96:99]
	v_mfma_f32_16x16x32_bf16 v[32:35], v[174:177], v[182:185], v[32:35]
	v_mfma_f32_16x16x32_bf16 v[32:35], v[170:173], v[178:181], v[32:35]
	v_mfma_f32_16x16x32_bf16 v[40:43], v[170:173], v[186:189], v[40:43]
	v_mfma_f32_16x16x32_bf16 v[40:43], v[174:177], v[190:193], v[40:43]
	v_mfma_f32_16x16x32_bf16 v[36:39], v[124:127], v[190:193], v[36:39]
	v_mfma_f32_16x16x32_bf16 v[36:39], v[120:123], v[186:189], v[36:39]
	v_mfma_f32_16x16x32_bf16 v[44:47], v[120:123], v[194:197], v[44:47]
	v_mfma_f32_16x16x32_bf16 v[44:47], v[124:127], v[198:201], v[44:47]
	v_mfma_f32_16x16x32_bf16 v[48:51], v[174:177], v[198:201], v[48:51]
	v_mfma_f32_16x16x32_bf16 v[48:51], v[170:173], v[194:197], v[48:51]
	v_mfma_f32_16x16x32_bf16 v[56:59], v[170:173], v[202:205], v[56:59]
	v_mfma_f32_16x16x32_bf16 v[56:59], v[174:177], v[206:209], v[56:59]
	v_mfma_f32_16x16x32_bf16 v[52:55], v[124:127], v[206:209], v[52:55]
	v_mfma_f32_16x16x32_bf16 v[52:55], v[120:123], v[202:205], v[52:55]
	s_setprio 0
	s_barrier
; #define PG8_STAGE(bufoff, gbase, voff) do { _Pragma("unroll") for (int _i = 0; _i < 2; ++_i) \
;         __builtin_amdgcn_global_load_lds((const unsigned*)((const char*)(gbase) + (voff)[_i]), (PG8_LAS unsigned*)(lds + (bufoff) + ldsw + _i * 8192), 16, 0, 0); } while (0)
; #define PG8_LDA(dst, b, h) do { _Pragma("unroll") for (int m = 0; m < 4; ++m) _Pragma("unroll") for (int k = 0; k < 2; ++k) dst[m][k] = *(const PG8_LAS bf16x8*)(lds + PG8_SA(b, h) + aoff + m * 2048 + k * 1024); } while (0)
; #define PG8_LDB(dst, b, h) do { _Pragma("unroll") for (int n = 0; n < 2; ++n) _Pragma("unroll") for (int k = 0; k < 2; ++k) dst[n][k] = *(const PG8_LAS bf16x8*)(lds + PG8_SB(b, h) + boff + n * 2048 + k * 1024); } while (0)
; #define PG8_MMA(ai, bj, At, Bt) do { __builtin_amdgcn_s_setprio(1); _Pragma("unroll") for (int m = 0; m < 4; ++m) _Pragma("unroll") for (int n = 0; n < 2; ++n) _Pragma("unroll") for (int k = 0; k < 2; ++k) \
;         acc[ai][bj][m][n] = __builtin_amdgcn_mfma_f32_16x16x32_bf16(Bt[n][k], At[m][k], acc[ai][bj][m][n], 0, 0, 0); __builtin_amdgcn_s_setprio(0); } while (0)
; #define PG8_WAIT_V(n) asm volatile("s_waitcnt vmcnt(" #n ")" ::: "memory")
; #define PG8_WAIT_L(n) asm volatile("s_waitcnt lgkmcnt(" #n ")" ::: "memory")
; #define PG8_BAR __builtin_amdgcn_s_barrier()
; #define PG8_SCHED __builtin_amdgcn_sched_barrier(0)
;     ...
;             PG8_LDB(B0, 0, 0); PG8_LDB(B1, 0, 1); PG8_SCHED; PG8_LDA(At, 0, 0); PG8_STAGE(PG8_SA(1, 1), a1 + hstepA, voffA);
;             PG8_WAIT_V(8); PG8_WAIT_L(0); PG8_BAR; PG8_MMA(0, 0, At, B0); PG8_MMA(0, 1, At, B1); PG8_BAR; PG8_SCHED;
;     ...
;             PG8_WAIT_V(8); PG8_WAIT_L(0); PG8_BAR; PG8_MMA(0, 0, At, B0); PG8_MMA(0, 1, At, B1); PG8_BAR; PG8_SCHED;
;             PG8_LDA(At, 1, 1); PG8_STAGE(PG8_SB(1, 0), b3, voffB); PG8_STAGE(PG8_SB(1, 1), b3 + hstepB, voffB); PG8_STAGE(PG8_SA(1, 0), a3, voffA);
;             PG8_WAIT_V(8); PG8_WAIT_L(0); PG8_BAR; PG8_MMA(1, 0, At, B0); PG8_MMA(1, 1, At, B1); PG8_BAR; PG8_SCHED;
	s_mov_b32 m0, s53
	v_lshl_add_u64 v[210:211], v[210:211], 0, s[18:19]
	s_add_u32 s30, s30, 0x10180
	ds_read_b128 v[178:181], v143 offset:49152
	ds_read_b128 v[182:185], v143 offset:50176
	ds_read_b128 v[186:189], v143 offset:51200
	ds_read_b128 v[190:193], v143 offset:52224
	ds_read_b128 v[194:197], v143 offset:53248
	ds_read_b128 v[198:201], v143 offset:54272
	ds_read_b128 v[202:205], v143 offset:55296
	ds_read_b128 v[206:209], v143 offset:56320
	global_load_lds_dwordx4 v[210:211], off
	v_lshl_add_u64 v[210:211], v[212:213], 0, s[18:19]
	s_mov_b32 m0, s54
	s_addc_u32 s31, s31, 0
	global_load_lds_dwordx4 v[210:211], off
	s_mov_b32 m0, s55
	s_nop 0
	global_load_lds_dwordx4 v132, s[30:31]
	s_mov_b32 m0, s56
	s_nop 0
	global_load_lds_dwordx4 v128, s[30:31]
	s_mov_b32 m0, s42
	s_nop 0
	global_load_lds_dwordx4 v134, s[34:35]
	s_mov_b32 m0, s43
	s_nop 0
	global_load_lds_dwordx4 v130, s[34:35]
	s_waitcnt vmcnt(8)
	s_waitcnt lgkmcnt(0)
	s_setprio 1
	s_barrier
	v_mfma_f32_16x16x32_bf16 v[0:3], v[24:27], v[202:205], v[0:3]
	v_mfma_f32_16x16x32_bf16 v[0:3], v[28:31], v[206:209], v[0:3]
	v_mfma_f32_16x16x32_bf16 v[4:7], v[116:119], v[206:209], v[4:7]
	v_mfma_f32_16x16x32_bf16 v[4:7], v[112:115], v[202:205], v[4:7]
	v_mfma_f32_16x16x32_bf16 v[150:153], v[112:115], v[178:181], v[150:153]
	v_mfma_f32_16x16x32_bf16 v[150:153], v[116:119], v[182:185], v[150:153]
	v_mfma_f32_16x16x32_bf16 v[146:149], v[28:31], v[182:185], v[146:149]
	v_mfma_f32_16x16x32_bf16 v[146:149], v[24:27], v[178:181], v[146:149]
	v_mfma_f32_16x16x32_bf16 v[154:157], v[24:27], v[186:189], v[154:157]
	v_mfma_f32_16x16x32_bf16 v[154:157], v[28:31], v[190:193], v[154:157]
	v_mfma_f32_16x16x32_bf16 v[158:161], v[116:119], v[190:193], v[158:161]
	v_mfma_f32_16x16x32_bf16 v[158:161], v[112:115], v[186:189], v[158:161]
	v_mfma_f32_16x16x32_bf16 v[166:169], v[112:115], v[194:197], v[166:169]
	v_mfma_f32_16x16x32_bf16 v[166:169], v[116:119], v[198:201], v[166:169]
	v_mfma_f32_16x16x32_bf16 v[162:165], v[28:31], v[198:201], v[162:165]
	v_mfma_f32_16x16x32_bf16 v[162:165], v[24:27], v[194:197], v[162:165]
	s_setprio 0
	s_setprio 1
	v_mfma_f32_16x16x32_bf16 v[8:11], v[120:123], v[178:181], v[8:11]
	v_mfma_f32_16x16x32_bf16 v[8:11], v[124:127], v[182:185], v[8:11]
	v_mfma_f32_16x16x32_bf16 v[12:15], v[170:173], v[178:181], v[12:15]
	v_mfma_f32_16x16x32_bf16 v[12:15], v[174:177], v[182:185], v[12:15]
	v_mfma_f32_16x16x32_bf16 v[24:27], v[120:123], v[186:189], v[60:63]
	v_mfma_f32_16x16x32_bf16 v[24:27], v[124:127], v[190:193], v[24:27]
	v_mfma_f32_16x16x32_bf16 v[28:31], v[170:173], v[186:189], v[100:103]
	v_mfma_f32_16x16x32_bf16 v[28:31], v[174:177], v[190:193], v[28:31]
	v_mfma_f32_16x16x32_bf16 v[60:63], v[120:123], v[194:197], v[104:107]
	v_mfma_f32_16x16x32_bf16 v[60:63], v[124:127], v[198:201], v[60:63]
	v_mfma_f32_16x16x32_bf16 v[100:103], v[170:173], v[194:197], v[108:111]
	v_mfma_f32_16x16x32_bf16 v[100:103], v[174:177], v[198:201], v[100:103]
	v_mfma_f32_16x16x32_bf16 v[16:19], v[120:123], v[202:205], v[16:19]
	v_mfma_f32_16x16x32_bf16 v[16:19], v[124:127], v[206:209], v[16:19]
	v_mfma_f32_16x16x32_bf16 v[20:23], v[170:173], v[202:205], v[20:23]
	v_mfma_f32_16x16x32_bf16 v[20:23], v[174:177], v[206:209], v[20:23]
	s_setprio 0
	s_barrier
	ds_read_b128 v[104:107], v141
	ds_read_b128 v[108:111], v141 offset:1024
	ds_read_b128 v[112:115], v141 offset:2048
	ds_read_b128 v[116:119], v141 offset:3072
	ds_read_b128 v[120:123], v142
	ds_read_b128 v[124:127], v142 offset:1024
	ds_read_b128 v[170:173], v142 offset:2048
	ds_read_b128 v[174:177], v142 offset:3072
	s_add_u32 s30, s28, 0x8000
	s_addc_u32 s31, s29, 0
	s_add_u32 s26, s26, 0x1c000
	s_addc_u32 s27, s27, 0
	s_mov_b32 m0, s46
	ds_read_b128 v[178:181], v143
	ds_read_b128 v[182:185], v143 offset:1024
	ds_read_b128 v[186:189], v143 offset:2048
	ds_read_b128 v[190:193], v143 offset:3072
	ds_read_b128 v[194:197], v143 offset:4096
	ds_read_b128 v[198:201], v143 offset:5120
	ds_read_b128 v[202:205], v143 offset:6144
	ds_read_b128 v[206:209], v143 offset:7168
	global_load_lds_dwordx4 v134, s[26:27]
	v_lshl_add_u64 v[210:211], s[26:27], 0, v[130:131]
	s_mov_b32 m0, s47
	s_nop 0
	global_load_lds_dwordx4 v[210:211], off
	s_waitcnt vmcnt(8)
	s_waitcnt lgkmcnt(0)
	s_setprio 1
	s_barrier
	v_mfma_f32_16x16x32_bf16 v[64:67], v[104:107], v[178:181], v[64:67]
	v_mfma_f32_16x16x32_bf16 v[64:67], v[108:111], v[182:185], v[64:67]
	v_mfma_f32_16x16x32_bf16 v[68:71], v[112:115], v[178:181], v[68:71]
	v_mfma_f32_16x16x32_bf16 v[68:71], v[116:119], v[182:185], v[68:71]
	v_mfma_f32_16x16x32_bf16 v[72:75], v[104:107], v[186:189], v[72:75]
	v_mfma_f32_16x16x32_bf16 v[72:75], v[108:111], v[190:193], v[72:75]
	v_mfma_f32_16x16x32_bf16 v[76:79], v[112:115], v[186:189], v[76:79]
	v_mfma_f32_16x16x32_bf16 v[76:79], v[116:119], v[190:193], v[76:79]
	v_mfma_f32_16x16x32_bf16 v[80:83], v[104:107], v[194:197], v[80:83]
	v_mfma_f32_16x16x32_bf16 v[80:83], v[108:111], v[198:201], v[80:83]
	v_mfma_f32_16x16x32_bf16 v[84:87], v[112:115], v[194:197], v[84:87]
	v_mfma_f32_16x16x32_bf16 v[84:87], v[116:119], v[198:201], v[84:87]
	v_mfma_f32_16x16x32_bf16 v[88:91], v[104:107], v[202:205], v[88:91]
	v_mfma_f32_16x16x32_bf16 v[210:213], v[108:111], v[206:209], v[88:91]
	v_mfma_f32_16x16x32_bf16 v[88:91], v[112:115], v[202:205], v[92:95]
	v_mfma_f32_16x16x32_bf16 v[214:217], v[116:119], v[206:209], v[88:91]
	s_setprio 0
	s_setprio 1
	v_mfma_f32_16x16x32_bf16 v[88:91], v[120:123], v[178:181], v[96:99]
	v_mfma_f32_16x16x32_bf16 v[96:99], v[124:127], v[182:185], v[88:91]
	v_mfma_f32_16x16x32_bf16 v[32:35], v[170:173], v[178:181], v[32:35]
	v_mfma_f32_16x16x32_bf16 v[32:35], v[174:177], v[182:185], v[32:35]
	v_mfma_f32_16x16x32_bf16 v[36:39], v[120:123], v[186:189], v[36:39]
	v_mfma_f32_16x16x32_bf16 v[36:39], v[124:127], v[190:193], v[36:39]
	v_mfma_f32_16x16x32_bf16 v[40:43], v[170:173], v[186:189], v[40:43]
	v_mfma_f32_16x16x32_bf16 v[40:43], v[174:177], v[190:193], v[40:43]
	v_mfma_f32_16x16x32_bf16 v[44:47], v[120:123], v[194:197], v[44:47]
	v_mfma_f32_16x16x32_bf16 v[44:47], v[124:127], v[198:201], v[44:47]
	v_mfma_f32_16x16x32_bf16 v[48:51], v[170:173], v[194:197], v[48:51]
	v_mfma_f32_16x16x32_bf16 v[48:51], v[174:177], v[198:201], v[48:51]
	v_mfma_f32_16x16x32_bf16 v[52:55], v[120:123], v[202:205], v[52:55]
	v_mfma_f32_16x16x32_bf16 v[52:55], v[124:127], v[206:209], v[52:55]
	v_mfma_f32_16x16x32_bf16 v[56:59], v[170:173], v[202:205], v[56:59]
	v_mfma_f32_16x16x32_bf16 v[56:59], v[174:177], v[206:209], v[56:59]
	s_setprio 0
	s_barrier
; #define PG8_STAGE(bufoff, gbase, voff) do { _Pragma("unroll") for (int _i = 0; _i < 2; ++_i) \
;         __builtin_amdgcn_global_load_lds((const unsigned*)((const char*)(gbase) + (voff)[_i]), (PG8_LAS unsigned*)(lds + (bufoff) + ldsw + _i * 8192), 16, 0, 0); } while (0)
; #define PG8_LDA(dst, b, h) do { _Pragma("unroll") for (int m = 0; m < 4; ++m) _Pragma("unroll") for (int k = 0; k < 2; ++k) dst[m][k] = *(const PG8_LAS bf16x8*)(lds + PG8_SA(b, h) + aoff + m * 2048 + k * 1024); } while (0)
; #define PG8_LDB(dst, b, h) do { _Pragma("unroll") for (int n = 0; n < 2; ++n) _Pragma("unroll") for (int k = 0; k < 2; ++k) dst[n][k] = *(const PG8_LAS bf16x8*)(lds + PG8_SB(b, h) + boff + n * 2048 + k * 1024); } while (0)
; #define PG8_MMA(ai, bj, At, Bt) do { __builtin_amdgcn_s_setprio(1); _Pragma("unroll") for (int m = 0; m < 4; ++m) _Pragma("unroll") for (int n = 0; n < 2; ++n) _Pragma("unroll") for (int k = 0; k < 2; ++k) \
;         acc[ai][bj][m][n] = __builtin_amdgcn_mfma_f32_16x16x32_bf16(Bt[n][k], At[m][k], acc[ai][bj][m][n], 0, 0, 0); __builtin_amdgcn_s_setprio(0); } while (0)
; #define PG8_WAIT_V(n) asm volatile("s_waitcnt vmcnt(" #n ")" ::: "memory")
; #define PG8_WAIT_L(n) asm volatile("s_waitcnt lgkmcnt(" #n ")" ::: "memory")
; #define PG8_BAR __builtin_amdgcn_s_barrier()
; #define PG8_SCHED __builtin_amdgcn_sched_barrier(0)
;     ...
;             PG8_WAIT_V(8); PG8_WAIT_L(0); PG8_BAR; PG8_MMA(0, 0, At, B0); PG8_MMA(0, 1, At, B1); PG8_BAR; PG8_SCHED;
;             PG8_LDA(At, 0, 1); PG8_STAGE(PG8_SB(0, 0), b2, voffB); PG8_STAGE(PG8_SB(0, 1), b2 + hstepB, voffB); PG8_STAGE(PG8_SA(0, 0), a2, voffA);
;             PG8_WAIT_V(8); PG8_WAIT_L(0); PG8_BAR; PG8_MMA(1, 0, At, B0); PG8_MMA(1, 1, At, B1); PG8_BAR; PG8_SCHED;
;             PG8_LDB(B0, 1, 0); PG8_LDB(B1, 1, 1); PG8_SCHED; PG8_LDA(At, 1, 0); PG8_STAGE(PG8_SA(0, 1), a2 + hstepA, voffA);
;             PG8_WAIT_V(8); PG8_WAIT_L(0); PG8_BAR; PG8_MMA(0, 0, At, B0); PG8_MMA(0, 1, At, B1); PG8_BAR; PG8_SCHED;
	s_mov_b32 m0, s48
	v_lshl_add_u64 v[246:247], s[24:25], 0, v[132:133]
	s_add_u32 s26, s24, 0x10000
	ds_read_b128 v[88:91], v143 offset:16384
	ds_read_b128 v[92:95], v143 offset:17408
	ds_read_b128 v[178:181], v143 offset:18432
	ds_read_b128 v[182:185], v143 offset:19456
	ds_read_b128 v[186:189], v143 offset:20480
	ds_read_b128 v[190:193], v143 offset:21504
	ds_read_b128 v[194:197], v143 offset:22528
	ds_read_b128 v[198:201], v143 offset:23552
	global_load_lds_dwordx4 v[246:247], off
	v_lshl_add_u64 v[248:249], s[24:25], 0, v[128:129]
	s_mov_b32 m0, s50
	s_addc_u32 s27, s25, 0
	global_load_lds_dwordx4 v[248:249], off
	s_mov_b32 m0, s51
	s_nop 0
	global_load_lds_dwordx4 v132, s[26:27]
	s_mov_b32 m0, s52
	s_nop 0
	global_load_lds_dwordx4 v128, s[26:27]
	s_mov_b32 m0, s23
	s_nop 0
	global_load_lds_dwordx4 v134, s[28:29]
	v_lshl_add_u64 v[202:203], s[28:29], 0, v[130:131]
	s_mov_b32 m0, s37
	s_nop 0
	global_load_lds_dwordx4 v[202:203], off
	s_waitcnt vmcnt(8)
	s_waitcnt lgkmcnt(0)
	s_setprio 1
	s_barrier
	v_mfma_f32_16x16x32_bf16 v[0:3], v[104:107], v[194:197], v[0:3]
	v_mfma_f32_16x16x32_bf16 v[0:3], v[108:111], v[198:201], v[0:3]
	v_mfma_f32_16x16x32_bf16 v[4:7], v[116:119], v[198:201], v[4:7]
	v_mfma_f32_16x16x32_bf16 v[4:7], v[112:115], v[194:197], v[4:7]
	v_mfma_f32_16x16x32_bf16 v[150:153], v[112:115], v[88:91], v[150:153]
	v_mfma_f32_16x16x32_bf16 v[150:153], v[116:119], v[92:95], v[150:153]
	v_mfma_f32_16x16x32_bf16 v[146:149], v[108:111], v[92:95], v[146:149]
	v_mfma_f32_16x16x32_bf16 v[146:149], v[104:107], v[88:91], v[146:149]
	v_mfma_f32_16x16x32_bf16 v[154:157], v[104:107], v[178:181], v[154:157]
	v_mfma_f32_16x16x32_bf16 v[154:157], v[108:111], v[182:185], v[154:157]
	v_mfma_f32_16x16x32_bf16 v[158:161], v[116:119], v[182:185], v[158:161]
	v_mfma_f32_16x16x32_bf16 v[158:161], v[112:115], v[178:181], v[158:161]
	v_mfma_f32_16x16x32_bf16 v[166:169], v[112:115], v[186:189], v[166:169]
	v_mfma_f32_16x16x32_bf16 v[166:169], v[116:119], v[190:193], v[166:169]
	v_mfma_f32_16x16x32_bf16 v[162:165], v[108:111], v[190:193], v[162:165]
	v_mfma_f32_16x16x32_bf16 v[162:165], v[104:107], v[186:189], v[162:165]
	s_setprio 0
	s_setprio 1
	v_mfma_f32_16x16x32_bf16 v[8:11], v[120:123], v[88:91], v[8:11]
	v_mfma_f32_16x16x32_bf16 v[202:205], v[124:127], v[92:95], v[8:11]
	v_mfma_f32_16x16x32_bf16 v[8:11], v[170:173], v[88:91], v[12:15]
	v_mfma_f32_16x16x32_bf16 v[206:209], v[174:177], v[92:95], v[8:11]
	v_mfma_f32_16x16x32_bf16 v[8:11], v[120:123], v[178:181], v[24:27]
	v_mfma_f32_16x16x32_bf16 v[218:221], v[124:127], v[182:185], v[8:11]
	v_mfma_f32_16x16x32_bf16 v[8:11], v[170:173], v[178:181], v[28:31]
	v_mfma_f32_16x16x32_bf16 v[178:181], v[174:177], v[182:185], v[8:11]
	v_mfma_f32_16x16x32_bf16 v[8:11], v[120:123], v[186:189], v[60:63]
	v_mfma_f32_16x16x32_bf16 v[182:185], v[124:127], v[190:193], v[8:11]
	v_mfma_f32_16x16x32_bf16 v[8:11], v[170:173], v[186:189], v[100:103]
	v_mfma_f32_16x16x32_bf16 v[186:189], v[174:177], v[190:193], v[8:11]
	v_mfma_f32_16x16x32_bf16 v[8:11], v[120:123], v[194:197], v[16:19]
	v_mfma_f32_16x16x32_bf16 v[190:193], v[124:127], v[198:201], v[8:11]
	v_mfma_f32_16x16x32_bf16 v[8:11], v[170:173], v[194:197], v[20:23]
	v_mfma_f32_16x16x32_bf16 v[170:173], v[174:177], v[198:201], v[8:11]
	s_setprio 0
	s_barrier
	s_nop 4
	ds_read_b128 v[8:11], v144
	ds_read_b128 v[12:15], v144 offset:1024
	ds_read_b128 v[16:19], v144 offset:2048
	ds_read_b128 v[20:23], v144 offset:3072
	ds_read_b128 v[174:177], v145
	ds_read_b128 v[194:197], v145 offset:1024
	ds_read_b128 v[198:201], v145 offset:2048
	ds_read_b128 v[222:225], v145 offset:3072
	s_add_u32 s26, s28, 0x4000
	s_addc_u32 s27, s29, 0
	s_mov_b32 m0, s39
	ds_read_b128 v[24:27], v143 offset:32768
	ds_read_b128 v[28:31], v143 offset:33792
	ds_read_b128 v[60:63], v143 offset:34816
	ds_read_b128 v[226:229], v143 offset:35840
	ds_read_b128 v[230:233], v143 offset:36864
	ds_read_b128 v[234:237], v143 offset:37888
	ds_read_b128 v[238:241], v143 offset:38912
	ds_read_b128 v[242:245], v143 offset:39936
	global_load_lds_dwordx4 v134, s[26:27]
	v_lshl_add_u64 v[88:89], s[26:27], 0, v[130:131]
	s_mov_b32 m0, s40
	s_nop 0
	global_load_lds_dwordx4 v[88:89], off
	s_waitcnt vmcnt(8)
	s_waitcnt lgkmcnt(0)
	s_setprio 1
	s_barrier
; __device__ __forceinline__ int lane_id_opaque() { int l; asm volatile("v_mbcnt_lo_u32_b32 %0, -1, 0\n\tv_mbcnt_hi_u32_b32 %0, -1, %0" : "=v"(l)); return l; }
; #define PG8_STAGE(bufoff, gbase, voff) do { _Pragma("unroll") for (int _i = 0; _i < 2; ++_i) \
;         __builtin_amdgcn_global_load_lds((const unsigned*)((const char*)(gbase) + (voff)[_i]), (PG8_LAS unsigned*)(lds + (bufoff) + ldsw + _i * 8192), 16, 0, 0); } while (0)
; #define PG8_LDA(dst, b, h) do { _Pragma("unroll") for (int m = 0; m < 4; ++m) _Pragma("unroll") for (int k = 0; k < 2; ++k) dst[m][k] = *(const PG8_LAS bf16x8*)(lds + PG8_SA(b, h) + aoff + m * 2048 + k * 1024); } while (0)
; #define PG8_MMA(ai, bj, At, Bt) do { __builtin_amdgcn_s_setprio(1); _Pragma("unroll") for (int m = 0; m < 4; ++m) _Pragma("unroll") for (int n = 0; n < 2; ++n) _Pragma("unroll") for (int k = 0; k < 2; ++k) \
;         acc[ai][bj][m][n] = __builtin_amdgcn_mfma_f32_16x16x32_bf16(Bt[n][k], At[m][k], acc[ai][bj][m][n], 0, 0, 0); __builtin_amdgcn_s_setprio(0); } while (0)
; #define PG8_WAIT_V(n) asm volatile("s_waitcnt vmcnt(" #n ")" ::: "memory")
; #define PG8_WAIT_L(n) asm volatile("s_waitcnt lgkmcnt(" #n ")" ::: "memory")
; #define PG8_BAR __builtin_amdgcn_s_barrier()
; #define PG8_SCHED __builtin_amdgcn_sched_barrier(0)
;     ...
;             PG8_WAIT_V(8); PG8_WAIT_L(0); PG8_BAR; PG8_MMA(0, 0, At, B0); PG8_MMA(0, 1, At, B1); PG8_BAR; PG8_SCHED;
;             PG8_LDA(At, 1, 1); PG8_STAGE(PG8_SB(1, 0), b3, voffB); PG8_STAGE(PG8_SB(1, 1), b3 + hstepB, voffB); PG8_STAGE(PG8_SA(1, 0), a3, voffA);
;             PG8_WAIT_V(8); PG8_WAIT_L(0); PG8_BAR; PG8_MMA(1, 0, At, B0); PG8_MMA(1, 1, At, B1); PG8_BAR; PG8_SCHED;
;     ...
;         if constexpr (ALIGN_EPI) { if (wr == 0) PG8_BAR; }
;         { const int l2 = lane_id_opaque(); E(acc, cur, ui, wr, wc, l2 & 15, l2 >> 4); }
;         S.done(cur);
;         if (!has_next) break;
	v_mfma_f32_16x16x32_bf16 v[64:67], v[8:11], v[24:27], v[64:67]
	v_mfma_f32_16x16x32_bf16 v[124:127], v[12:15], v[28:31], v[64:67]
	v_mfma_f32_16x16x32_bf16 v[64:67], v[16:19], v[24:27], v[68:71]
	v_mfma_f32_16x16x32_bf16 v[120:123], v[20:23], v[28:31], v[64:67]
	v_mfma_f32_16x16x32_bf16 v[64:67], v[8:11], v[60:63], v[72:75]
	v_mfma_f32_16x16x32_bf16 v[108:111], v[12:15], v[226:229], v[64:67]
	v_mfma_f32_16x16x32_bf16 v[64:67], v[16:19], v[60:63], v[76:79]
	v_mfma_f32_16x16x32_bf16 v[104:107], v[20:23], v[226:229], v[64:67]
	v_mfma_f32_16x16x32_bf16 v[64:67], v[8:11], v[230:233], v[80:83]
	v_mfma_f32_16x16x32_bf16 v[92:95], v[12:15], v[234:237], v[64:67]
	v_mfma_f32_16x16x32_bf16 v[64:67], v[16:19], v[230:233], v[84:87]
	v_mfma_f32_16x16x32_bf16 v[88:91], v[20:23], v[234:237], v[64:67]
	v_mfma_f32_16x16x32_bf16 v[64:67], v[8:11], v[238:241], v[210:213]
	v_mfma_f32_16x16x32_bf16 v[76:79], v[12:15], v[242:245], v[64:67]
	v_mfma_f32_16x16x32_bf16 v[64:67], v[16:19], v[238:241], v[214:217]
	v_mfma_f32_16x16x32_bf16 v[72:75], v[20:23], v[242:245], v[64:67]
	s_setprio 0
	s_setprio 1
	v_mfma_f32_16x16x32_bf16 v[64:67], v[174:177], v[24:27], v[96:99]
	v_mfma_f32_16x16x32_bf16 v[24:27], v[198:201], v[24:27], v[32:35]
	v_mfma_f32_16x16x32_bf16 v[112:115], v[222:225], v[28:31], v[24:27]
	v_mfma_f32_16x16x32_bf16 v[24:27], v[174:177], v[60:63], v[36:39]
	v_mfma_f32_16x16x32_bf16 v[100:103], v[194:197], v[226:229], v[24:27]
	v_mfma_f32_16x16x32_bf16 v[24:27], v[198:201], v[60:63], v[40:43]
	v_mfma_f32_16x16x32_bf16 v[96:99], v[222:225], v[226:229], v[24:27]
	v_mfma_f32_16x16x32_bf16 v[24:27], v[174:177], v[230:233], v[44:47]
	v_mfma_f32_16x16x32_bf16 v[84:87], v[194:197], v[234:237], v[24:27]
	v_mfma_f32_16x16x32_bf16 v[24:27], v[198:201], v[230:233], v[48:51]
	v_mfma_f32_16x16x32_bf16 v[80:83], v[222:225], v[234:237], v[24:27]
	v_mfma_f32_16x16x32_bf16 v[24:27], v[174:177], v[238:241], v[52:55]
	v_mfma_f32_16x16x32_bf16 v[60:63], v[194:197], v[242:245], v[24:27]
	v_mfma_f32_16x16x32_bf16 v[24:27], v[198:201], v[238:241], v[56:59]
	v_mfma_f32_16x16x32_bf16 v[116:119], v[194:197], v[28:31], v[64:67]
	v_mfma_f32_16x16x32_bf16 v[56:59], v[222:225], v[242:245], v[24:27]
	s_setprio 0
	s_barrier
	s_mov_b32 m0, s53
	s_nop 2
	v_lshl_add_u64 v[24:25], v[246:247], 0, s[12:13]
	s_add_u32 s24, s24, 0x10080
	ds_read_b128 v[32:35], v143 offset:49152
	ds_read_b128 v[36:39], v143 offset:50176
	ds_read_b128 v[210:213], v143 offset:51200
	ds_read_b128 v[214:217], v143 offset:52224
	ds_read_b128 v[226:229], v143 offset:53248
	ds_read_b128 v[230:233], v143 offset:54272
	ds_read_b128 v[234:237], v143 offset:55296
	ds_read_b128 v[238:241], v143 offset:56320
	global_load_lds_dwordx4 v[24:25], off
	v_lshl_add_u64 v[24:25], v[248:249], 0, s[12:13]
	s_mov_b32 m0, s54
	s_addc_u32 s25, s25, 0
	global_load_lds_dwordx4 v[24:25], off
	s_mov_b32 m0, s55
	s_nop 0
	global_load_lds_dwordx4 v132, s[24:25]
	s_mov_b32 m0, s56
	s_nop 0
	global_load_lds_dwordx4 v128, s[24:25]
	s_mov_b32 m0, s42
	s_nop 0
	global_load_lds_dwordx4 v134, s[30:31]
	v_lshl_add_u64 v[24:25], s[30:31], 0, v[130:131]
	s_mov_b32 m0, s43
	s_nop 0
	global_load_lds_dwordx4 v[24:25], off
	s_waitcnt vmcnt(8)
	s_waitcnt lgkmcnt(0)
	s_setprio 1
	s_barrier
	v_mfma_f32_16x16x32_bf16 v[24:27], v[8:11], v[32:35], v[146:149]
	v_mfma_f32_16x16x32_bf16 v[68:71], v[12:15], v[36:39], v[24:27]
	v_mfma_f32_16x16x32_bf16 v[24:27], v[16:19], v[32:35], v[150:153]
	v_mfma_f32_16x16x32_bf16 v[64:67], v[20:23], v[36:39], v[24:27]
	v_mfma_f32_16x16x32_bf16 v[24:27], v[8:11], v[210:213], v[154:157]
	v_mfma_f32_16x16x32_bf16 v[44:47], v[12:15], v[214:217], v[24:27]
	v_mfma_f32_16x16x32_bf16 v[24:27], v[16:19], v[210:213], v[158:161]
	v_mfma_f32_16x16x32_bf16 v[40:43], v[20:23], v[214:217], v[24:27]
	v_mfma_f32_16x16x32_bf16 v[24:27], v[8:11], v[226:229], v[162:165]
	v_mfma_f32_16x16x32_bf16 v[28:31], v[12:15], v[230:233], v[24:27]
	v_mfma_f32_16x16x32_bf16 v[0:3], v[8:11], v[234:237], v[0:3]
	v_mfma_f32_16x16x32_bf16 v[12:15], v[12:15], v[238:241], v[0:3]
	v_mfma_f32_16x16x32_bf16 v[24:27], v[16:19], v[226:229], v[166:169]
	v_mfma_f32_16x16x32_bf16 v[24:27], v[20:23], v[230:233], v[24:27]
	v_mfma_f32_16x16x32_bf16 v[0:3], v[16:19], v[234:237], v[4:7]
	v_mfma_f32_16x16x32_bf16 v[8:11], v[20:23], v[238:241], v[0:3]
	s_setprio 0
	s_setprio 1
	v_mfma_f32_16x16x32_bf16 v[0:3], v[174:177], v[32:35], v[202:205]
	v_mfma_f32_16x16x32_bf16 v[52:55], v[194:197], v[36:39], v[0:3]
	v_mfma_f32_16x16x32_bf16 v[0:3], v[198:201], v[32:35], v[206:209]
	v_mfma_f32_16x16x32_bf16 v[48:51], v[222:225], v[36:39], v[0:3]
	v_mfma_f32_16x16x32_bf16 v[0:3], v[174:177], v[210:213], v[218:221]
	v_mfma_f32_16x16x32_bf16 v[36:39], v[194:197], v[214:217], v[0:3]
	v_mfma_f32_16x16x32_bf16 v[0:3], v[198:201], v[210:213], v[178:181]
	v_mfma_f32_16x16x32_bf16 v[32:35], v[222:225], v[214:217], v[0:3]
	v_mfma_f32_16x16x32_bf16 v[0:3], v[174:177], v[226:229], v[182:185]
	v_mfma_f32_16x16x32_bf16 v[20:23], v[194:197], v[230:233], v[0:3]
	v_mfma_f32_16x16x32_bf16 v[0:3], v[198:201], v[226:229], v[186:189]
	v_mfma_f32_16x16x32_bf16 v[16:19], v[222:225], v[230:233], v[0:3]
	v_mfma_f32_16x16x32_bf16 v[0:3], v[174:177], v[234:237], v[190:193]
	v_mfma_f32_16x16x32_bf16 v[4:7], v[194:197], v[238:241], v[0:3]
	v_mfma_f32_16x16x32_bf16 v[0:3], v[198:201], v[234:237], v[170:173]
	v_mfma_f32_16x16x32_bf16 v[0:3], v[222:225], v[238:241], v[0:3]
	s_setprio 0
	s_barrier
	s_and_b64 vcc, exec, s[0:1]
	s_cbranch_vccnz .LBB0_99
	s_barrier

; #define PG8_STAGE(bufoff, gbase, voff) do { _Pragma("unroll") for (int _i = 0; _i < 2; ++_i) \
;         __builtin_amdgcn_global_load_lds((const unsigned*)((const char*)(gbase) + (voff)[_i]), (PG8_LAS unsigned*)(lds + (bufoff) + ldsw + _i * 8192), 16, 0, 0); } while (0)
; #define PG8_LDA(dst, b, h) do { _Pragma("unroll") for (int m = 0; m < 4; ++m) _Pragma("unroll") for (int k = 0; k < 2; ++k) dst[m][k] = *(const PG8_LAS bf16x8*)(lds + PG8_SA(b, h) + aoff + m * 2048 + k * 1024); } while (0)
; #define PG8_LDB(dst, b, h) do { _Pragma("unroll") for (int n = 0; n < 2; ++n) _Pragma("unroll") for (int k = 0; k < 2; ++k) dst[n][k] = *(const PG8_LAS bf16x8*)(lds + PG8_SB(b, h) + boff + n * 2048 + k * 1024); } while (0)
; #define PG8_MMA(ai, bj, At, Bt) do { __builtin_amdgcn_s_setprio(1); _Pragma("unroll") for (int m = 0; m < 4; ++m) _Pragma("unroll") for (int n = 0; n < 2; ++n) _Pragma("unroll") for (int k = 0; k < 2; ++k) \
;         acc[ai][bj][m][n] = __builtin_amdgcn_mfma_f32_16x16x32_bf16(Bt[n][k], At[m][k], acc[ai][bj][m][n], 0, 0, 0); __builtin_amdgcn_s_setprio(0); } while (0)
; #define PG8_WAIT_V(n) asm volatile("s_waitcnt vmcnt(" #n ")" ::: "memory")
; #define PG8_WAIT_L(n) asm volatile("s_waitcnt lgkmcnt(" #n ")" ::: "memory")
; #define PG8_BAR __builtin_amdgcn_s_barrier()
; #define PG8_SCHED __builtin_amdgcn_sched_barrier(0)
;     ...
;         for (int t = 0; t < nt; t += 2) {
;             const bool last = (t == nt - 2);
;             const char* a1 = cA + (ptrdiff_t)(t + 1) * kstepA;
;             const char* a2 = last ? nA : cA + (ptrdiff_t)(t + 2) * kstepA; const char* b2 = last ? nB : cB + (ptrdiff_t)(t + 2) * kstep;
;             const char* a3 = a2 + kstepA; const char* b3 = b2 + kstep;
;             if (last && has_next) S.a_ready(nxt);
;             if constexpr (SP2) {
;             PG8_LDB(B0, 0, 0); PG8_LDB(B1, 0, 1); PG8_SCHED; PG8_LDA(At, 0, 0); PG8_STAGE(PG8_SA(1, 1), a1 + hstepA, voffA);
;             PG8_WAIT_V(8); PG8_WAIT_L(0); PG8_BAR; PG8_MMA(0, 0, At, B0); PG8_MMA(0, 1, At, B1); PG8_BAR; PG8_SCHED;
;             PG8_LDA(At, 0, 1); PG8_STAGE(PG8_SB(0, 0), b2, voffB); PG8_STAGE(PG8_SB(0, 1), b2 + hstepB, voffB); PG8_STAGE(PG8_SA(0, 0), a2, voffA);
;             PG8_WAIT_V(8); PG8_WAIT_L(0); PG8_BAR; PG8_MMA(1, 0, At, B0); PG8_MMA(1, 1, At, B1); PG8_BAR; PG8_SCHED;
.Lin_nostg:
	s_add_u32 s65, s6, 0x4000
	s_addc_u32 s66, s7, 0
	s_cmp_eq_u32 vcc_lo, 28
	s_cselect_b32 s90, s54, s65
	s_cselect_b32 s91, s29, s66
	s_cselect_b32 s88, s55, s56
	s_cselect_b32 s89, s31, s57
	s_add_u32 s86, s90, 0x8000
	s_addc_u32 s87, s91, 0
	s_add_i32 s65, 0, 0x10000
	s_add_i32 s66, 0, 0x14000
	v_add_u32_e32 v22, s65, v182
	v_add_u32_e32 v54, s66, v182
	ds_read_b128 v[10:13], v22
	ds_read_b128 v[14:17], v22 offset:1024
	ds_read_b128 v[18:21], v22 offset:2048
	ds_read_b128 v[22:25], v22 offset:3072
	ds_read_b128 v[26:29], v54
	ds_read_b128 v[38:41], v54 offset:1024
	ds_read_b128 v[50:53], v54 offset:2048
	ds_read_b128 v[54:57], v54 offset:3072
	s_add_i32 m0, s51, 0xc000
	ds_read_b128 v[172:175], v183
	ds_read_b128 v[176:179], v183 offset:1024
	ds_read_b128 v[184:187], v183 offset:2048
	ds_read_b128 v[188:191], v183 offset:3072
	ds_read_b128 v[192:195], v183 offset:4096
	ds_read_b128 v[196:199], v183 offset:5120
	ds_read_b128 v[200:203], v183 offset:6144
	ds_read_b128 v[204:207], v183 offset:7168
	global_load_lds_dwordx4 v168, s[6:7]
	s_add_i32 m0, s51, 0xe000
	s_nop 0
	global_load_lds_dwordx4 v170, s[6:7]
	s_waitcnt vmcnt(8)
	s_waitcnt lgkmcnt(0)
	s_setprio 1
	s_barrier
	v_mfma_f32_16x16x32_bf16 v[158:161], v[10:13], v[172:175], 0
	v_mfma_f32_16x16x32_bf16 v[158:161], v[14:17], v[176:179], v[158:161]
	v_mfma_f32_16x16x32_bf16 v[154:157], v[22:25], v[176:179], 0
	v_mfma_f32_16x16x32_bf16 v[154:157], v[18:21], v[172:175], v[154:157]
	v_mfma_f32_16x16x32_bf16 v[138:141], v[18:21], v[184:187], 0
	v_mfma_f32_16x16x32_bf16 v[138:141], v[22:25], v[188:191], v[138:141]
	v_mfma_f32_16x16x32_bf16 v[142:145], v[14:17], v[188:191], 0
	v_mfma_f32_16x16x32_bf16 v[142:145], v[10:13], v[184:187], v[142:145]
	v_mfma_f32_16x16x32_bf16 v[126:129], v[10:13], v[192:195], 0
	v_mfma_f32_16x16x32_bf16 v[126:129], v[14:17], v[196:199], v[126:129]
	v_mfma_f32_16x16x32_bf16 v[122:125], v[22:25], v[196:199], 0
	v_mfma_f32_16x16x32_bf16 v[122:125], v[18:21], v[192:195], v[122:125]
	v_mfma_f32_16x16x32_bf16 v[106:109], v[18:21], v[200:203], 0
	v_mfma_f32_16x16x32_bf16 v[106:109], v[22:25], v[204:207], v[106:109]
	v_mfma_f32_16x16x32_bf16 v[110:113], v[14:17], v[204:207], 0
	v_mfma_f32_16x16x32_bf16 v[110:113], v[10:13], v[200:203], v[110:113]
	s_setprio 0
	s_setprio 1
	v_mfma_f32_16x16x32_bf16 v[150:153], v[26:29], v[172:175], 0
	v_mfma_f32_16x16x32_bf16 v[150:153], v[38:41], v[176:179], v[150:153]
	v_mfma_f32_16x16x32_bf16 v[146:149], v[54:57], v[176:179], 0
	v_mfma_f32_16x16x32_bf16 v[146:149], v[50:53], v[172:175], v[146:149]
	v_mfma_f32_16x16x32_bf16 v[130:133], v[50:53], v[184:187], 0
	v_mfma_f32_16x16x32_bf16 v[130:133], v[54:57], v[188:191], v[130:133]
	v_mfma_f32_16x16x32_bf16 v[134:137], v[38:41], v[188:191], 0
	v_mfma_f32_16x16x32_bf16 v[134:137], v[26:29], v[184:187], v[134:137]
	v_mfma_f32_16x16x32_bf16 v[118:121], v[26:29], v[192:195], 0
	v_mfma_f32_16x16x32_bf16 v[118:121], v[38:41], v[196:199], v[118:121]
	v_mfma_f32_16x16x32_bf16 v[114:117], v[54:57], v[196:199], 0
	v_mfma_f32_16x16x32_bf16 v[114:117], v[50:53], v[192:195], v[114:117]
	v_mfma_f32_16x16x32_bf16 v[98:101], v[50:53], v[200:203], 0
	v_mfma_f32_16x16x32_bf16 v[98:101], v[54:57], v[204:207], v[98:101]
	v_mfma_f32_16x16x32_bf16 v[102:105], v[38:41], v[204:207], 0
	v_mfma_f32_16x16x32_bf16 v[102:105], v[26:29], v[200:203], v[102:105]
	s_setprio 0
	s_barrier
	s_add_i32 s65, s65, s2
	s_mov_b32 m0, s65
	ds_read_b128 v[172:175], v183 offset:16384
	ds_read_b128 v[176:179], v183 offset:17408
	ds_read_b128 v[184:187], v183 offset:18432
	ds_read_b128 v[188:191], v183 offset:19456
	ds_read_b128 v[192:195], v183 offset:20480
	ds_read_b128 v[196:199], v183 offset:21504
	ds_read_b128 v[200:203], v183 offset:22528
	ds_read_b128 v[204:207], v183 offset:23552
	global_load_lds_dwordx4 v0, s[88:89]
	s_add_i32 m0, s65, 0x2000
	s_add_u32 s96, s88, 0x4000
	s_addc_u32 s97, s89, 0
	s_add_i32 s65, s66, s2
	global_load_lds_dwordx4 v162, s[88:89]
	s_mov_b32 m0, s65
	s_nop 0
	global_load_lds_dwordx4 v0, s[96:97]
	s_add_i32 m0, s65, 0x2000
	s_nop 0
	global_load_lds_dwordx4 v162, s[96:97]
	s_mov_b32 m0, s51
	s_nop 0
	global_load_lds_dwordx4 v166, s[90:91]
	s_mov_b32 m0, s92
	s_nop 0
	global_load_lds_dwordx4 v164, s[90:91]
	s_waitcnt vmcnt(8)
	s_waitcnt lgkmcnt(0)
	s_setprio 1
	s_barrier
	v_mfma_f32_16x16x32_bf16 v[94:97], v[10:13], v[172:175], 0
	v_mfma_f32_16x16x32_bf16 v[94:97], v[14:17], v[176:179], v[94:97]
	v_mfma_f32_16x16x32_bf16 v[90:93], v[18:21], v[172:175], 0
	v_mfma_f32_16x16x32_bf16 v[90:93], v[22:25], v[176:179], v[90:93]
	v_mfma_f32_16x16x32_bf16 v[78:81], v[10:13], v[184:187], 0
	v_mfma_f32_16x16x32_bf16 v[78:81], v[14:17], v[188:191], v[78:81]
	v_mfma_f32_16x16x32_bf16 v[74:77], v[18:21], v[184:187], 0
	v_mfma_f32_16x16x32_bf16 v[74:77], v[22:25], v[188:191], v[74:77]
	v_mfma_f32_16x16x32_bf16 v[62:65], v[10:13], v[192:195], 0
	v_mfma_f32_16x16x32_bf16 v[62:65], v[14:17], v[196:199], v[62:65]
	v_mfma_f32_16x16x32_bf16 v[58:61], v[18:21], v[192:195], 0
	v_mfma_f32_16x16x32_bf16 v[58:61], v[22:25], v[196:199], v[58:61]
	v_mfma_f32_16x16x32_bf16 v[10:13], v[10:13], v[200:203], 0
	v_mfma_f32_16x16x32_bf16 v[10:13], v[14:17], v[204:207], v[10:13]
	v_mfma_f32_16x16x32_bf16 v[14:17], v[18:21], v[200:203], 0
	v_mfma_f32_16x16x32_bf16 v[14:17], v[22:25], v[204:207], v[14:17]
	s_setprio 0
	s_setprio 1
	v_mfma_f32_16x16x32_bf16 v[30:33], v[26:29], v[184:187], 0
	v_mfma_f32_16x16x32_bf16 v[70:73], v[38:41], v[188:191], v[30:33]
	v_mfma_f32_16x16x32_bf16 v[30:33], v[50:53], v[184:187], 0
	v_mfma_f32_16x16x32_bf16 v[66:69], v[54:57], v[188:191], v[30:33]
	v_mfma_f32_16x16x32_bf16 v[30:33], v[26:29], v[192:195], 0
	v_mfma_f32_16x16x32_bf16 v[46:49], v[38:41], v[196:199], v[30:33]
	v_mfma_f32_16x16x32_bf16 v[30:33], v[50:53], v[192:195], 0
	v_mfma_f32_16x16x32_bf16 v[42:45], v[54:57], v[196:199], v[30:33]
	v_mfma_f32_16x16x32_bf16 v[6:9], v[26:29], v[200:203], 0
	v_mfma_f32_16x16x32_bf16 v[6:9], v[38:41], v[204:207], v[6:9]
	v_mfma_f32_16x16x32_bf16 v[2:5], v[50:53], v[200:203], 0
	v_mfma_f32_16x16x32_bf16 v[2:5], v[54:57], v[204:207], v[2:5]
	v_mfma_f32_16x16x32_bf16 v[18:21], v[26:29], v[172:175], 0
	v_mfma_f32_16x16x32_bf16 v[18:21], v[38:41], v[176:179], v[18:21]
	v_mfma_f32_16x16x32_bf16 v[22:25], v[50:53], v[172:175], 0
	v_mfma_f32_16x16x32_bf16 v[22:25], v[54:57], v[176:179], v[22:25]
	s_setprio 0
	s_barrier
	s_branch .Lin_mid

; #define PG8_STAGE(bufoff, gbase, voff) do { _Pragma("unroll") for (int _i = 0; _i < 2; ++_i) \
;         __builtin_amdgcn_global_load_lds((const unsigned*)((const char*)(gbase) + (voff)[_i]), (PG8_LAS unsigned*)(lds + (bufoff) + ldsw + _i * 8192), 16, 0, 0); } while (0)
; #define PG8_LDA(dst, b, h) do { _Pragma("unroll") for (int m = 0; m < 4; ++m) _Pragma("unroll") for (int k = 0; k < 2; ++k) dst[m][k] = *(const PG8_LAS bf16x8*)(lds + PG8_SA(b, h) + aoff + m * 2048 + k * 1024); } while (0)
; #define PG8_LDB(dst, b, h) do { _Pragma("unroll") for (int n = 0; n < 2; ++n) _Pragma("unroll") for (int k = 0; k < 2; ++k) dst[n][k] = *(const PG8_LAS bf16x8*)(lds + PG8_SB(b, h) + boff + n * 2048 + k * 1024); } while (0)
; #define PG8_MMA(ai, bj, At, Bt) do { __builtin_amdgcn_s_setprio(1); _Pragma("unroll") for (int m = 0; m < 4; ++m) _Pragma("unroll") for (int n = 0; n < 2; ++n) _Pragma("unroll") for (int k = 0; k < 2; ++k) \
;         acc[ai][bj][m][n] = __builtin_amdgcn_mfma_f32_16x16x32_bf16(Bt[n][k], At[m][k], acc[ai][bj][m][n], 0, 0, 0); __builtin_amdgcn_s_setprio(0); } while (0)
; #define PG8_WAIT_V(n) asm volatile("s_waitcnt vmcnt(" #n ")" ::: "memory")
; #define PG8_WAIT_L(n) asm volatile("s_waitcnt lgkmcnt(" #n ")" ::: "memory")
; #define PG8_BAR __builtin_amdgcn_s_barrier()
; #define PG8_SCHED __builtin_amdgcn_sched_barrier(0)
;     ...
;         for (int t = 0; t < nt; t += 2) {
;             const bool last = (t == nt - 2);
;             const char* a1 = cA + (ptrdiff_t)(t + 1) * kstepA;
;             const char* a2 = last ? nA : cA + (ptrdiff_t)(t + 2) * kstepA; const char* b2 = last ? nB : cB + (ptrdiff_t)(t + 2) * kstep;
;             const char* a3 = a2 + kstepA; const char* b3 = b2 + kstep;
;             if (last && has_next) S.a_ready(nxt);
;             if constexpr (SP2) {
;             PG8_LDB(B0, 0, 0); PG8_LDB(B1, 0, 1); PG8_SCHED; PG8_LDA(At, 0, 0); PG8_STAGE(PG8_SA(1, 1), a1 + hstepA, voffA);
;             PG8_WAIT_V(8); PG8_WAIT_L(0); PG8_BAR; PG8_MMA(0, 0, At, B0); PG8_MMA(0, 1, At, B1); PG8_BAR; PG8_SCHED;
;             PG8_LDA(At, 0, 1); PG8_STAGE(PG8_SB(0, 0), b2, voffB); PG8_STAGE(PG8_SB(0, 1), b2 + hstepB, voffB); PG8_STAGE(PG8_SA(0, 0), a2, voffA);
;             PG8_WAIT_V(8); PG8_WAIT_L(0); PG8_BAR; PG8_MMA(1, 0, At, B0); PG8_MMA(1, 1, At, B1); PG8_BAR; PG8_SCHED;
.LBB0_328:
	s_add_u32 s65, s6, 0x4000
	s_addc_u32 s66, s7, 0
	s_cmp_eq_u32 vcc_lo, 28
	s_cselect_b32 s90, s54, s65
	s_cselect_b32 s91, s29, s66
	s_cselect_b32 s88, s55, s56
	s_cselect_b32 s89, s31, s57
	s_add_u32 s86, s90, 0x8000
	s_addc_u32 s87, s91, 0
	s_add_i32 s65, 0, 0x10000
	s_add_i32 s66, 0, 0x14000
	v_add_u32_e32 v22, s65, v182
	v_add_u32_e32 v54, s66, v182
	ds_read_b128 v[10:13], v22
	ds_read_b128 v[14:17], v22 offset:1024
	ds_read_b128 v[18:21], v22 offset:2048
	ds_read_b128 v[22:25], v22 offset:3072
	ds_read_b128 v[26:29], v54
	ds_read_b128 v[38:41], v54 offset:1024
	ds_read_b128 v[50:53], v54 offset:2048
	ds_read_b128 v[54:57], v54 offset:3072
	s_add_i32 m0, s51, 0xc000
	ds_read_b128 v[172:175], v183
	ds_read_b128 v[176:179], v183 offset:1024
	ds_read_b128 v[184:187], v183 offset:2048
	ds_read_b128 v[188:191], v183 offset:3072
	ds_read_b128 v[192:195], v183 offset:4096
	ds_read_b128 v[196:199], v183 offset:5120
	ds_read_b128 v[200:203], v183 offset:6144
	ds_read_b128 v[204:207], v183 offset:7168
	global_load_lds_dwordx4 v168, s[6:7]
	s_add_i32 m0, s51, 0xe000
	s_nop 0
	global_load_lds_dwordx4 v170, s[6:7]
	s_waitcnt vmcnt(8)
	s_waitcnt lgkmcnt(0)
	s_setprio 1
	s_barrier
	v_mfma_f32_16x16x32_bf16 v[158:161], v[10:13], v[172:175], v[158:161]
	v_mfma_f32_16x16x32_bf16 v[158:161], v[14:17], v[176:179], v[158:161]
	v_mfma_f32_16x16x32_bf16 v[154:157], v[22:25], v[176:179], v[154:157]
	v_mfma_f32_16x16x32_bf16 v[154:157], v[18:21], v[172:175], v[154:157]
	v_mfma_f32_16x16x32_bf16 v[138:141], v[18:21], v[184:187], v[138:141]
	v_mfma_f32_16x16x32_bf16 v[138:141], v[22:25], v[188:191], v[138:141]
	v_mfma_f32_16x16x32_bf16 v[142:145], v[14:17], v[188:191], v[142:145]
	v_mfma_f32_16x16x32_bf16 v[142:145], v[10:13], v[184:187], v[142:145]
	v_mfma_f32_16x16x32_bf16 v[126:129], v[10:13], v[192:195], v[126:129]
	v_mfma_f32_16x16x32_bf16 v[126:129], v[14:17], v[196:199], v[126:129]
	v_mfma_f32_16x16x32_bf16 v[122:125], v[22:25], v[196:199], v[122:125]
	v_mfma_f32_16x16x32_bf16 v[122:125], v[18:21], v[192:195], v[122:125]
	v_mfma_f32_16x16x32_bf16 v[106:109], v[18:21], v[200:203], v[106:109]
	v_mfma_f32_16x16x32_bf16 v[106:109], v[22:25], v[204:207], v[106:109]
	v_mfma_f32_16x16x32_bf16 v[110:113], v[14:17], v[204:207], v[110:113]
	v_mfma_f32_16x16x32_bf16 v[110:113], v[10:13], v[200:203], v[110:113]
	s_setprio 0
	s_setprio 1
	v_mfma_f32_16x16x32_bf16 v[150:153], v[26:29], v[172:175], v[150:153]
	v_mfma_f32_16x16x32_bf16 v[150:153], v[38:41], v[176:179], v[150:153]
	v_mfma_f32_16x16x32_bf16 v[146:149], v[54:57], v[176:179], v[146:149]
	v_mfma_f32_16x16x32_bf16 v[146:149], v[50:53], v[172:175], v[146:149]
	v_mfma_f32_16x16x32_bf16 v[130:133], v[50:53], v[184:187], v[130:133]
	v_mfma_f32_16x16x32_bf16 v[130:133], v[54:57], v[188:191], v[130:133]
	v_mfma_f32_16x16x32_bf16 v[134:137], v[38:41], v[188:191], v[134:137]
	v_mfma_f32_16x16x32_bf16 v[134:137], v[26:29], v[184:187], v[134:137]
	v_mfma_f32_16x16x32_bf16 v[118:121], v[26:29], v[192:195], v[118:121]
	v_mfma_f32_16x16x32_bf16 v[118:121], v[38:41], v[196:199], v[118:121]
	v_mfma_f32_16x16x32_bf16 v[114:117], v[54:57], v[196:199], v[114:117]
	v_mfma_f32_16x16x32_bf16 v[114:117], v[50:53], v[192:195], v[114:117]
	v_mfma_f32_16x16x32_bf16 v[98:101], v[50:53], v[200:203], v[98:101]
	v_mfma_f32_16x16x32_bf16 v[98:101], v[54:57], v[204:207], v[98:101]
	v_mfma_f32_16x16x32_bf16 v[102:105], v[38:41], v[204:207], v[102:105]
	v_mfma_f32_16x16x32_bf16 v[102:105], v[26:29], v[200:203], v[102:105]
	s_setprio 0
	s_barrier
	s_add_i32 s65, s65, s2
	s_mov_b32 m0, s65
	ds_read_b128 v[172:175], v183 offset:16384
	ds_read_b128 v[176:179], v183 offset:17408
	ds_read_b128 v[184:187], v183 offset:18432
	ds_read_b128 v[188:191], v183 offset:19456
	ds_read_b128 v[192:195], v183 offset:20480
	ds_read_b128 v[196:199], v183 offset:21504
	ds_read_b128 v[200:203], v183 offset:22528
	ds_read_b128 v[204:207], v183 offset:23552
	global_load_lds_dwordx4 v0, s[88:89]
	s_add_i32 m0, s65, 0x2000
	s_add_u32 s96, s88, 0x4000
	s_addc_u32 s97, s89, 0
	s_add_i32 s65, s66, s2
	global_load_lds_dwordx4 v162, s[88:89]
	s_mov_b32 m0, s65
	s_nop 0
	global_load_lds_dwordx4 v0, s[96:97]
	s_add_i32 m0, s65, 0x2000
	s_nop 0
	global_load_lds_dwordx4 v162, s[96:97]
	s_mov_b32 m0, s51
	s_nop 0
	global_load_lds_dwordx4 v166, s[90:91]
	s_mov_b32 m0, s92
	s_nop 0
	global_load_lds_dwordx4 v164, s[90:91]
	s_waitcnt vmcnt(8)
	s_waitcnt lgkmcnt(0)
	s_setprio 1
	s_barrier
	v_mfma_f32_16x16x32_bf16 v[94:97], v[10:13], v[172:175], v[94:97]
	v_mfma_f32_16x16x32_bf16 v[94:97], v[14:17], v[176:179], v[94:97]
	v_mfma_f32_16x16x32_bf16 v[90:93], v[18:21], v[172:175], v[90:93]
	v_mfma_f32_16x16x32_bf16 v[90:93], v[22:25], v[176:179], v[90:93]
	v_mfma_f32_16x16x32_bf16 v[78:81], v[10:13], v[184:187], v[78:81]
	v_mfma_f32_16x16x32_bf16 v[78:81], v[14:17], v[188:191], v[78:81]
	v_mfma_f32_16x16x32_bf16 v[74:77], v[18:21], v[184:187], v[74:77]
	v_mfma_f32_16x16x32_bf16 v[74:77], v[22:25], v[188:191], v[74:77]
	v_mfma_f32_16x16x32_bf16 v[62:65], v[10:13], v[192:195], v[62:65]
	v_mfma_f32_16x16x32_bf16 v[62:65], v[14:17], v[196:199], v[62:65]
	v_mfma_f32_16x16x32_bf16 v[58:61], v[18:21], v[192:195], v[58:61]
	v_mfma_f32_16x16x32_bf16 v[58:61], v[22:25], v[196:199], v[58:61]
	v_mfma_f32_16x16x32_bf16 v[10:13], v[10:13], v[200:203], v[34:37]
	v_mfma_f32_16x16x32_bf16 v[10:13], v[14:17], v[204:207], v[10:13]
	v_mfma_f32_16x16x32_bf16 v[14:17], v[18:21], v[200:203], v[30:33]
	v_mfma_f32_16x16x32_bf16 v[14:17], v[22:25], v[204:207], v[14:17]
	s_setprio 0
	s_setprio 1
	v_mfma_f32_16x16x32_bf16 v[30:33], v[26:29], v[184:187], v[70:73]
	v_mfma_f32_16x16x32_bf16 v[70:73], v[38:41], v[188:191], v[30:33]
	v_mfma_f32_16x16x32_bf16 v[30:33], v[50:53], v[184:187], v[66:69]
	v_mfma_f32_16x16x32_bf16 v[66:69], v[54:57], v[188:191], v[30:33]
	v_mfma_f32_16x16x32_bf16 v[30:33], v[26:29], v[192:195], v[46:49]
	v_mfma_f32_16x16x32_bf16 v[46:49], v[38:41], v[196:199], v[30:33]
	v_mfma_f32_16x16x32_bf16 v[30:33], v[50:53], v[192:195], v[42:45]
	v_mfma_f32_16x16x32_bf16 v[42:45], v[54:57], v[196:199], v[30:33]
	v_mfma_f32_16x16x32_bf16 v[6:9], v[26:29], v[200:203], v[6:9]
	v_mfma_f32_16x16x32_bf16 v[6:9], v[38:41], v[204:207], v[6:9]
	v_mfma_f32_16x16x32_bf16 v[2:5], v[50:53], v[200:203], v[2:5]
	v_mfma_f32_16x16x32_bf16 v[2:5], v[54:57], v[204:207], v[2:5]
	v_mfma_f32_16x16x32_bf16 v[18:21], v[26:29], v[172:175], v[86:89]
	v_mfma_f32_16x16x32_bf16 v[18:21], v[38:41], v[176:179], v[18:21]
	v_mfma_f32_16x16x32_bf16 v[22:25], v[50:53], v[172:175], v[82:85]
	v_mfma_f32_16x16x32_bf16 v[22:25], v[54:57], v[176:179], v[22:25]
	s_setprio 0
	s_barrier
; #define PG8_STAGE(bufoff, gbase, voff) do { _Pragma("unroll") for (int _i = 0; _i < 2; ++_i) \
;         __builtin_amdgcn_global_load_lds((const unsigned*)((const char*)(gbase) + (voff)[_i]), (PG8_LAS unsigned*)(lds + (bufoff) + ldsw + _i * 8192), 16, 0, 0); } while (0)
; #define PG8_LDA(dst, b, h) do { _Pragma("unroll") for (int m = 0; m < 4; ++m) _Pragma("unroll") for (int k = 0; k < 2; ++k) dst[m][k] = *(const PG8_LAS bf16x8*)(lds + PG8_SA(b, h) + aoff + m * 2048 + k * 1024); } while (0)
; #define PG8_LDB(dst, b, h) do { _Pragma("unroll") for (int n = 0; n < 2; ++n) _Pragma("unroll") for (int k = 0; k < 2; ++k) dst[n][k] = *(const PG8_LAS bf16x8*)(lds + PG8_SB(b, h) + boff + n * 2048 + k * 1024); } while (0)
; #define PG8_MMA(ai, bj, At, Bt) do { __builtin_amdgcn_s_setprio(1); _Pragma("unroll") for (int m = 0; m < 4; ++m) _Pragma("unroll") for (int n = 0; n < 2; ++n) _Pragma("unroll") for (int k = 0; k < 2; ++k) \
;         acc[ai][bj][m][n] = __builtin_amdgcn_mfma_f32_16x16x32_bf16(Bt[n][k], At[m][k], acc[ai][bj][m][n], 0, 0, 0); __builtin_amdgcn_s_setprio(0); } while (0)
; #define PG8_WAIT_V(n) asm volatile("s_waitcnt vmcnt(" #n ")" ::: "memory")
; #define PG8_WAIT_L(n) asm volatile("s_waitcnt lgkmcnt(" #n ")" ::: "memory")
; #define PG8_BAR __builtin_amdgcn_s_barrier()
; #define PG8_SCHED __builtin_amdgcn_sched_barrier(0)
;     ...
;             PG8_LDB(B0, 1, 0); PG8_LDB(B1, 1, 1); PG8_SCHED; PG8_LDA(At, 1, 0); PG8_STAGE(PG8_SA(0, 1), a2 + hstepA, voffA);
;             PG8_WAIT_V(8); PG8_WAIT_L(0); PG8_BAR; PG8_MMA(0, 0, At, B0); PG8_MMA(0, 1, At, B1); PG8_BAR; PG8_SCHED;
;             PG8_LDA(At, 1, 1); PG8_STAGE(PG8_SB(1, 0), b3, voffB); PG8_STAGE(PG8_SB(1, 1), b3 + hstepB, voffB); PG8_STAGE(PG8_SA(1, 0), a3, voffA);
;             PG8_WAIT_V(8); PG8_WAIT_L(0); PG8_BAR; PG8_MMA(1, 0, At, B0); PG8_MMA(1, 1, At, B1); PG8_BAR; PG8_SCHED;
.Lin_mid:
	s_add_i32 s65, 0, 0x18000
	v_add_u32_e32 v34, s65, v182
	s_add_i32 s66, 0, 0x1c000
	ds_read_b128 v[26:29], v34
	ds_read_b128 v[30:33], v34 offset:1024
	ds_read_b128 v[38:41], v34 offset:2048
	ds_read_b128 v[50:53], v34 offset:3072
	v_add_u32_e32 v34, s66, v182
	ds_read_b128 v[54:57], v34
	ds_read_b128 v[172:175], v34 offset:1024
	ds_read_b128 v[176:179], v34 offset:2048
	ds_read_b128 v[184:187], v34 offset:3072
	s_add_u32 s90, s90, 0x4000
	s_addc_u32 s91, s91, 0
	s_mov_b32 m0, s14
	ds_read_b128 v[34:37], v183 offset:32768
	ds_read_b128 v[82:85], v183 offset:33792
	ds_read_b128 v[86:89], v183 offset:34816
	ds_read_b128 v[188:191], v183 offset:35840
	ds_read_b128 v[192:195], v183 offset:36864
	ds_read_b128 v[196:199], v183 offset:37888
	ds_read_b128 v[200:203], v183 offset:38912
	ds_read_b128 v[204:207], v183 offset:39936
	global_load_lds_dwordx4 v166, s[90:91]
	v_lshl_add_u64 v[208:209], s[90:91], 0, v[164:165]
	s_mov_b32 m0, s15
	s_nop 0
	global_load_lds_dwordx4 v[208:209], off
	s_waitcnt vmcnt(8)
	s_waitcnt lgkmcnt(0)
	s_setprio 1
	s_barrier
	v_mfma_f32_16x16x32_bf16 v[158:161], v[26:29], v[34:37], v[158:161]
	v_mfma_f32_16x16x32_bf16 v[158:161], v[30:33], v[82:85], v[158:161]
	v_mfma_f32_16x16x32_bf16 v[154:157], v[50:53], v[82:85], v[154:157]
	v_mfma_f32_16x16x32_bf16 v[154:157], v[38:41], v[34:37], v[154:157]
	v_mfma_f32_16x16x32_bf16 v[138:141], v[38:41], v[86:89], v[138:141]
	v_mfma_f32_16x16x32_bf16 v[138:141], v[50:53], v[188:191], v[138:141]
	v_mfma_f32_16x16x32_bf16 v[142:145], v[30:33], v[188:191], v[142:145]
	v_mfma_f32_16x16x32_bf16 v[142:145], v[26:29], v[86:89], v[142:145]
	v_mfma_f32_16x16x32_bf16 v[126:129], v[26:29], v[192:195], v[126:129]
	v_mfma_f32_16x16x32_bf16 v[126:129], v[30:33], v[196:199], v[126:129]
	v_mfma_f32_16x16x32_bf16 v[122:125], v[50:53], v[196:199], v[122:125]
	v_mfma_f32_16x16x32_bf16 v[122:125], v[38:41], v[192:195], v[122:125]
	v_mfma_f32_16x16x32_bf16 v[106:109], v[38:41], v[200:203], v[106:109]
	v_mfma_f32_16x16x32_bf16 v[106:109], v[50:53], v[204:207], v[106:109]
	v_mfma_f32_16x16x32_bf16 v[110:113], v[30:33], v[204:207], v[110:113]
	v_mfma_f32_16x16x32_bf16 v[110:113], v[26:29], v[200:203], v[110:113]
	s_setprio 0
	s_setprio 1
	v_mfma_f32_16x16x32_bf16 v[150:153], v[54:57], v[34:37], v[150:153]
	v_mfma_f32_16x16x32_bf16 v[150:153], v[172:175], v[82:85], v[150:153]
	v_mfma_f32_16x16x32_bf16 v[34:37], v[176:179], v[34:37], v[146:149]
	v_mfma_f32_16x16x32_bf16 v[146:149], v[184:187], v[82:85], v[34:37]
	v_mfma_f32_16x16x32_bf16 v[34:37], v[54:57], v[86:89], v[134:137]
	v_mfma_f32_16x16x32_bf16 v[134:137], v[172:175], v[188:191], v[34:37]
	v_mfma_f32_16x16x32_bf16 v[34:37], v[176:179], v[86:89], v[130:133]
	v_mfma_f32_16x16x32_bf16 v[130:133], v[184:187], v[188:191], v[34:37]
	v_mfma_f32_16x16x32_bf16 v[34:37], v[54:57], v[192:195], v[118:121]
	v_mfma_f32_16x16x32_bf16 v[118:121], v[172:175], v[196:199], v[34:37]
	v_mfma_f32_16x16x32_bf16 v[34:37], v[176:179], v[192:195], v[114:117]
	v_mfma_f32_16x16x32_bf16 v[114:117], v[184:187], v[196:199], v[34:37]
	v_mfma_f32_16x16x32_bf16 v[34:37], v[54:57], v[200:203], v[102:105]
	v_mfma_f32_16x16x32_bf16 v[102:105], v[172:175], v[204:207], v[34:37]
	v_mfma_f32_16x16x32_bf16 v[34:37], v[176:179], v[200:203], v[98:101]
	v_mfma_f32_16x16x32_bf16 v[98:101], v[184:187], v[204:207], v[34:37]
	s_setprio 0
	s_barrier
	s_add_u32 s90, s88, 0x8000
	s_addc_u32 s91, s89, 0
	s_add_i32 s65, s65, s2
	s_nop 0
	s_mov_b32 m0, s65
	ds_read_b128 v[82:85], v183 offset:49152
	ds_read_b128 v[188:191], v183 offset:50176
	ds_read_b128 v[192:195], v183 offset:51200
	ds_read_b128 v[196:199], v183 offset:52224
	ds_read_b128 v[200:203], v183 offset:53248
	ds_read_b128 v[204:207], v183 offset:54272
	ds_read_b128 v[208:211], v183 offset:55296
	ds_read_b128 v[216:219], v183 offset:56320
	global_load_lds_dwordx4 v0, s[90:91]
	s_add_i32 m0, s65, 0x2000
	s_add_u32 s88, s88, 0xc000
	s_addc_u32 s89, s89, 0
	s_add_i32 s65, s66, s2
	global_load_lds_dwordx4 v162, s[90:91]
	s_mov_b32 m0, s65
	s_nop 0
	global_load_lds_dwordx4 v0, s[88:89]
	s_add_i32 m0, s65, 0x2000
	s_nop 0
	global_load_lds_dwordx4 v162, s[88:89]
	s_mov_b32 m0, s71
	s_nop 0
	global_load_lds_dwordx4 v166, s[86:87]
	v_lshl_add_u64 v[34:35], s[86:87], 0, v[164:165]
	s_mov_b32 m0, s80
	s_nop 0
	global_load_lds_dwordx4 v[34:35], off
	s_waitcnt vmcnt(8)
	s_waitcnt lgkmcnt(0)
	s_setprio 1
	s_barrier
	v_mfma_f32_16x16x32_bf16 v[34:37], v[26:29], v[82:85], v[94:97]
	v_mfma_f32_16x16x32_bf16 v[94:97], v[30:33], v[188:191], v[34:37]
	v_mfma_f32_16x16x32_bf16 v[34:37], v[38:41], v[82:85], v[90:93]
	v_mfma_f32_16x16x32_bf16 v[90:93], v[50:53], v[188:191], v[34:37]
	v_mfma_f32_16x16x32_bf16 v[34:37], v[26:29], v[192:195], v[78:81]
	v_mfma_f32_16x16x32_bf16 v[78:81], v[30:33], v[196:199], v[34:37]
	v_mfma_f32_16x16x32_bf16 v[34:37], v[38:41], v[192:195], v[74:77]
	v_mfma_f32_16x16x32_bf16 v[74:77], v[50:53], v[196:199], v[34:37]
	v_mfma_f32_16x16x32_bf16 v[34:37], v[26:29], v[200:203], v[62:65]
	v_mfma_f32_16x16x32_bf16 v[62:65], v[30:33], v[204:207], v[34:37]
	v_mfma_f32_16x16x32_bf16 v[34:37], v[38:41], v[200:203], v[58:61]
	v_mfma_f32_16x16x32_bf16 v[58:61], v[50:53], v[204:207], v[34:37]
	v_mfma_f32_16x16x32_bf16 v[10:13], v[26:29], v[208:211], v[10:13]
	v_mfma_f32_16x16x32_bf16 v[34:37], v[30:33], v[216:219], v[10:13]
	v_mfma_f32_16x16x32_bf16 v[10:13], v[38:41], v[208:211], v[14:17]
	v_mfma_f32_16x16x32_bf16 v[30:33], v[50:53], v[216:219], v[10:13]
	s_setprio 0
	s_setprio 1
	v_mfma_f32_16x16x32_bf16 v[10:13], v[54:57], v[82:85], v[18:21]
	v_mfma_f32_16x16x32_bf16 v[86:89], v[172:175], v[188:191], v[10:13]
	v_mfma_f32_16x16x32_bf16 v[10:13], v[176:179], v[82:85], v[22:25]
	v_mfma_f32_16x16x32_bf16 v[82:85], v[184:187], v[188:191], v[10:13]
	v_mfma_f32_16x16x32_bf16 v[10:13], v[54:57], v[192:195], v[70:73]
	v_mfma_f32_16x16x32_bf16 v[70:73], v[172:175], v[196:199], v[10:13]
	v_mfma_f32_16x16x32_bf16 v[10:13], v[176:179], v[192:195], v[66:69]
	v_mfma_f32_16x16x32_bf16 v[66:69], v[184:187], v[196:199], v[10:13]
	v_mfma_f32_16x16x32_bf16 v[10:13], v[54:57], v[200:203], v[46:49]
	v_mfma_f32_16x16x32_bf16 v[46:49], v[172:175], v[204:207], v[10:13]
	v_mfma_f32_16x16x32_bf16 v[10:13], v[176:179], v[200:203], v[42:45]
	v_mfma_f32_16x16x32_bf16 v[42:45], v[184:187], v[204:207], v[10:13]
	v_mfma_f32_16x16x32_bf16 v[6:9], v[54:57], v[208:211], v[6:9]
	v_mfma_f32_16x16x32_bf16 v[6:9], v[172:175], v[216:219], v[6:9]
	v_mfma_f32_16x16x32_bf16 v[2:5], v[176:179], v[208:211], v[2:5]
	v_mfma_f32_16x16x32_bf16 v[2:5], v[184:187], v[216:219], v[2:5]
	s_setprio 0
	s_barrier
	s_add_i32 vcc_lo, vcc_lo, 2
	s_add_u32 s6, s6, 0x10000
	s_addc_u32 s7, s7, 0
	s_add_u32 s56, s56, 0x10000
	s_addc_u32 s57, s57, 0
	s_cmp_gt_u32 vcc_lo, 29
	s_cbranch_scc0 .LBB0_328
	s_and_b64 vcc, exec, s[26:27]
	s_cbranch_vccz .LBB0_331
	s_barrier

; #define PG8_STAGE(bufoff, gbase, voff) do { _Pragma("unroll") for (int _i = 0; _i < 2; ++_i) \
;         __builtin_amdgcn_global_load_lds((const unsigned*)((const char*)(gbase) + (voff)[_i]), (PG8_LAS unsigned*)(lds + (bufoff) + ldsw + _i * 8192), 16, 0, 0); } while (0)
; #define PG8_LDA(dst, b, h) do { _Pragma("unroll") for (int m = 0; m < 4; ++m) _Pragma("unroll") for (int k = 0; k < 2; ++k) dst[m][k] = *(const PG8_LAS bf16x8*)(lds + PG8_SA(b, h) + aoff + m * 2048 + k * 1024); } while (0)
; #define PG8_LDB(dst, b, h) do { _Pragma("unroll") for (int n = 0; n < 2; ++n) _Pragma("unroll") for (int k = 0; k < 2; ++k) dst[n][k] = *(const PG8_LAS bf16x8*)(lds + PG8_SB(b, h) + boff + n * 2048 + k * 1024); } while (0)
; #define PG8_MMA(ai, bj, At, Bt) do { __builtin_amdgcn_s_setprio(1); _Pragma("unroll") for (int m = 0; m < 4; ++m) _Pragma("unroll") for (int n = 0; n < 2; ++n) _Pragma("unroll") for (int k = 0; k < 2; ++k) \
;         acc[ai][bj][m][n] = __builtin_amdgcn_mfma_f32_16x16x32_bf16(Bt[n][k], At[m][k], acc[ai][bj][m][n], 0, 0, 0); __builtin_amdgcn_s_setprio(0); } while (0)
; #define PG8_WAIT_V(n) asm volatile("s_waitcnt vmcnt(" #n ")" ::: "memory")
; #define PG8_WAIT_L(n) asm volatile("s_waitcnt lgkmcnt(" #n ")" ::: "memory")
; #define PG8_BAR __builtin_amdgcn_s_barrier()
; #define PG8_SCHED __builtin_amdgcn_sched_barrier(0)
;     ...
;         for (int t = 0; t < nt; t += 2) {
;             const bool last = (t == nt - 2);
;             const char* a1 = cA + (ptrdiff_t)(t + 1) * kstepA;
;             const char* a2 = last ? nA : cA + (ptrdiff_t)(t + 2) * kstepA; const char* b2 = last ? nB : cB + (ptrdiff_t)(t + 2) * kstep;
;             const char* a3 = a2 + kstepA; const char* b3 = b2 + kstep;
;             if (last && has_next) S.a_ready(nxt);
;             if constexpr (SP2) {
;             PG8_LDB(B0, 0, 0); PG8_LDB(B1, 0, 1); PG8_SCHED; PG8_LDA(At, 0, 0); PG8_STAGE(PG8_SA(1, 1), a1 + hstepA, voffA);
;             PG8_WAIT_V(8); PG8_WAIT_L(0); PG8_BAR; PG8_MMA(0, 0, At, B0); PG8_MMA(0, 1, At, B1); PG8_BAR; PG8_SCHED;
;             PG8_LDA(At, 0, 1); PG8_STAGE(PG8_SB(0, 0), b2, voffB); PG8_STAGE(PG8_SB(0, 1), b2 + hstepB, voffB); PG8_STAGE(PG8_SA(0, 0), a2, voffA);
;             PG8_WAIT_V(8); PG8_WAIT_L(0); PG8_BAR; PG8_MMA(1, 0, At, B0); PG8_MMA(1, 1, At, B1); PG8_BAR; PG8_SCHED;
.Lout_nostg:
	s_add_u32 s36, s34, 0x4000
	s_addc_u32 s37, s35, 0
	s_cmp_eq_u32 s57, 28
	s_cselect_b32 s86, s29, s36
	s_cselect_b32 s87, s23, s37
	s_cselect_b32 s46, s31, s44
	s_cselect_b32 s47, s21, s56
	s_add_u32 s36, s86, 0x8000
	s_addc_u32 s37, s87, 0
	s_add_i32 s65, 0, 0x10000
	v_add_u32_e32 v0, s65, v242
	s_add_i32 s66, 0, 0x14000
	s_waitcnt lgkmcnt(0)
	ds_read_b128 v[130:133], v0
	ds_read_b128 v[134:137], v0 offset:1024
	ds_read_b128 v[138:141], v0 offset:2048
	ds_read_b128 v[142:145], v0 offset:3072
	v_add_u32_e32 v0, s66, v242
	ds_read_b128 v[146:149], v0
	ds_read_b128 v[150:153], v0 offset:1024
	ds_read_b128 v[154:157], v0 offset:2048
	ds_read_b128 v[158:161], v0 offset:3072
	s_add_i32 m0, s51, 0xc000
	ds_read_b128 v[162:165], v243
	ds_read_b128 v[166:169], v243 offset:1024
	ds_read_b128 v[170:173], v243 offset:2048
	ds_read_b128 v[174:177], v243 offset:3072
	ds_read_b128 v[178:181], v243 offset:4096
	ds_read_b128 v[182:185], v243 offset:5120
	ds_read_b128 v[198:201], v243 offset:6144
	ds_read_b128 v[202:205], v243 offset:7168
	global_load_lds_dwordx4 v194, s[34:35]
	s_add_i32 m0, s51, 0xe000
	s_nop 0
	global_load_lds_dwordx4 v196, s[34:35]
	s_waitcnt vmcnt(8)
	s_waitcnt lgkmcnt(0)
	s_setprio 1
	s_barrier
	v_mfma_f32_16x16x32_bf16 v[126:129], v[130:133], v[162:165], 0
	v_mfma_f32_16x16x32_bf16 v[126:129], v[134:137], v[166:169], v[126:129]
	v_mfma_f32_16x16x32_bf16 v[122:125], v[142:145], v[166:169], 0
	v_mfma_f32_16x16x32_bf16 v[122:125], v[138:141], v[162:165], v[122:125]
	v_mfma_f32_16x16x32_bf16 v[106:109], v[138:141], v[170:173], 0
	v_mfma_f32_16x16x32_bf16 v[106:109], v[142:145], v[174:177], v[106:109]
	v_mfma_f32_16x16x32_bf16 v[110:113], v[134:137], v[174:177], 0
	v_mfma_f32_16x16x32_bf16 v[110:113], v[130:133], v[170:173], v[110:113]
	v_mfma_f32_16x16x32_bf16 v[94:97], v[130:133], v[178:181], 0
	v_mfma_f32_16x16x32_bf16 v[94:97], v[134:137], v[182:185], v[94:97]
	v_mfma_f32_16x16x32_bf16 v[90:93], v[142:145], v[182:185], 0
	v_mfma_f32_16x16x32_bf16 v[90:93], v[138:141], v[178:181], v[90:93]
	v_mfma_f32_16x16x32_bf16 v[74:77], v[138:141], v[198:201], 0
	v_mfma_f32_16x16x32_bf16 v[74:77], v[142:145], v[202:205], v[74:77]
	v_mfma_f32_16x16x32_bf16 v[78:81], v[134:137], v[202:205], 0
	v_mfma_f32_16x16x32_bf16 v[78:81], v[130:133], v[198:201], v[78:81]
	s_setprio 0
	s_setprio 1
	v_mfma_f32_16x16x32_bf16 v[118:121], v[146:149], v[162:165], 0
	v_mfma_f32_16x16x32_bf16 v[118:121], v[150:153], v[166:169], v[118:121]
	v_mfma_f32_16x16x32_bf16 v[114:117], v[158:161], v[166:169], 0
	v_mfma_f32_16x16x32_bf16 v[114:117], v[154:157], v[162:165], v[114:117]
	v_mfma_f32_16x16x32_bf16 v[98:101], v[154:157], v[170:173], 0
	v_mfma_f32_16x16x32_bf16 v[98:101], v[158:161], v[174:177], v[98:101]
	v_mfma_f32_16x16x32_bf16 v[102:105], v[150:153], v[174:177], 0
	v_mfma_f32_16x16x32_bf16 v[102:105], v[146:149], v[170:173], v[102:105]
	v_mfma_f32_16x16x32_bf16 v[86:89], v[146:149], v[178:181], 0
	v_mfma_f32_16x16x32_bf16 v[86:89], v[150:153], v[182:185], v[86:89]
	v_mfma_f32_16x16x32_bf16 v[82:85], v[158:161], v[182:185], 0
	v_mfma_f32_16x16x32_bf16 v[82:85], v[154:157], v[178:181], v[82:85]
	v_mfma_f32_16x16x32_bf16 v[66:69], v[154:157], v[198:201], 0
	v_mfma_f32_16x16x32_bf16 v[66:69], v[158:161], v[202:205], v[66:69]
	v_mfma_f32_16x16x32_bf16 v[70:73], v[150:153], v[202:205], 0
	v_mfma_f32_16x16x32_bf16 v[70:73], v[146:149], v[198:201], v[70:73]
	s_setprio 0
	s_barrier
	s_add_i32 s65, s65, s49
	s_mov_b32 m0, s65
	ds_read_b128 v[162:165], v243 offset:16384
	ds_read_b128 v[166:169], v243 offset:17408
	ds_read_b128 v[170:173], v243 offset:18432
	ds_read_b128 v[174:177], v243 offset:19456
	ds_read_b128 v[178:181], v243 offset:20480
	ds_read_b128 v[182:185], v243 offset:21504
	ds_read_b128 v[198:201], v243 offset:22528
	ds_read_b128 v[202:205], v243 offset:23552
	global_load_lds_dwordx4 v188, s[46:47]
	s_add_i32 m0, s65, 0x2000
	s_add_u32 s90, s46, 0x4000
	s_addc_u32 s91, s47, 0
	s_add_i32 s65, s66, s49
	global_load_lds_dwordx4 v192, s[46:47]
	s_mov_b32 m0, s65
	s_nop 0
	global_load_lds_dwordx4 v188, s[90:91]
	s_add_i32 m0, s65, 0x2000
	s_nop 0
	global_load_lds_dwordx4 v192, s[90:91]
	s_mov_b32 m0, s51
	s_nop 0
	global_load_lds_dwordx4 v186, s[86:87]
	s_mov_b32 m0, s54
	s_nop 0
	global_load_lds_dwordx4 v190, s[86:87]
	s_waitcnt vmcnt(8)
	s_waitcnt lgkmcnt(0)
	s_setprio 1
	s_barrier
	v_mfma_f32_16x16x32_bf16 v[62:65], v[130:133], v[162:165], 0
	v_mfma_f32_16x16x32_bf16 v[62:65], v[134:137], v[166:169], v[62:65]
	v_mfma_f32_16x16x32_bf16 v[58:61], v[142:145], v[166:169], 0
	v_mfma_f32_16x16x32_bf16 v[58:61], v[138:141], v[162:165], v[58:61]
	v_mfma_f32_16x16x32_bf16 v[42:45], v[138:141], v[170:173], 0
	v_mfma_f32_16x16x32_bf16 v[42:45], v[142:145], v[174:177], v[42:45]
	v_mfma_f32_16x16x32_bf16 v[46:49], v[134:137], v[174:177], 0
	v_mfma_f32_16x16x32_bf16 v[46:49], v[130:133], v[170:173], v[46:49]
	v_mfma_f32_16x16x32_bf16 v[30:33], v[130:133], v[178:181], 0
	v_mfma_f32_16x16x32_bf16 v[30:33], v[134:137], v[182:185], v[30:33]
	v_mfma_f32_16x16x32_bf16 v[26:29], v[142:145], v[182:185], 0
	v_mfma_f32_16x16x32_bf16 v[26:29], v[138:141], v[178:181], v[26:29]
	v_mfma_f32_16x16x32_bf16 v[10:13], v[138:141], v[198:201], 0
	v_mfma_f32_16x16x32_bf16 v[10:13], v[142:145], v[202:205], v[10:13]
	v_mfma_f32_16x16x32_bf16 v[14:17], v[134:137], v[202:205], 0
	v_mfma_f32_16x16x32_bf16 v[14:17], v[130:133], v[198:201], v[14:17]
	s_setprio 0
	s_setprio 1
	v_mfma_f32_16x16x32_bf16 v[54:57], v[146:149], v[162:165], 0
	v_mfma_f32_16x16x32_bf16 v[54:57], v[150:153], v[166:169], v[54:57]
	v_mfma_f32_16x16x32_bf16 v[50:53], v[158:161], v[166:169], 0
	v_mfma_f32_16x16x32_bf16 v[50:53], v[154:157], v[162:165], v[50:53]
	v_mfma_f32_16x16x32_bf16 v[34:37], v[154:157], v[170:173], 0
	v_mfma_f32_16x16x32_bf16 v[34:37], v[158:161], v[174:177], v[34:37]
	v_mfma_f32_16x16x32_bf16 v[38:41], v[150:153], v[174:177], 0
	v_mfma_f32_16x16x32_bf16 v[38:41], v[146:149], v[170:173], v[38:41]
	v_mfma_f32_16x16x32_bf16 v[22:25], v[146:149], v[178:181], 0
	v_mfma_f32_16x16x32_bf16 v[22:25], v[150:153], v[182:185], v[22:25]
	v_mfma_f32_16x16x32_bf16 v[18:21], v[158:161], v[182:185], 0
	v_mfma_f32_16x16x32_bf16 v[18:21], v[154:157], v[178:181], v[18:21]
	v_mfma_f32_16x16x32_bf16 v[2:5], v[154:157], v[198:201], 0
	v_mfma_f32_16x16x32_bf16 v[2:5], v[158:161], v[202:205], v[2:5]
	v_mfma_f32_16x16x32_bf16 v[6:9], v[150:153], v[202:205], 0
	v_mfma_f32_16x16x32_bf16 v[6:9], v[146:149], v[198:201], v[6:9]
	s_setprio 0
	s_barrier
	s_branch .Lout_mid

; #define PG8_STAGE(bufoff, gbase, voff) do { _Pragma("unroll") for (int _i = 0; _i < 2; ++_i) \
;         __builtin_amdgcn_global_load_lds((const unsigned*)((const char*)(gbase) + (voff)[_i]), (PG8_LAS unsigned*)(lds + (bufoff) + ldsw + _i * 8192), 16, 0, 0); } while (0)
; #define PG8_LDA(dst, b, h) do { _Pragma("unroll") for (int m = 0; m < 4; ++m) _Pragma("unroll") for (int k = 0; k < 2; ++k) dst[m][k] = *(const PG8_LAS bf16x8*)(lds + PG8_SA(b, h) + aoff + m * 2048 + k * 1024); } while (0)
; #define PG8_LDB(dst, b, h) do { _Pragma("unroll") for (int n = 0; n < 2; ++n) _Pragma("unroll") for (int k = 0; k < 2; ++k) dst[n][k] = *(const PG8_LAS bf16x8*)(lds + PG8_SB(b, h) + boff + n * 2048 + k * 1024); } while (0)
; #define PG8_MMA(ai, bj, At, Bt) do { __builtin_amdgcn_s_setprio(1); _Pragma("unroll") for (int m = 0; m < 4; ++m) _Pragma("unroll") for (int n = 0; n < 2; ++n) _Pragma("unroll") for (int k = 0; k < 2; ++k) \
;         acc[ai][bj][m][n] = __builtin_amdgcn_mfma_f32_16x16x32_bf16(Bt[n][k], At[m][k], acc[ai][bj][m][n], 0, 0, 0); __builtin_amdgcn_s_setprio(0); } while (0)
; #define PG8_WAIT_V(n) asm volatile("s_waitcnt vmcnt(" #n ")" ::: "memory")
; #define PG8_WAIT_L(n) asm volatile("s_waitcnt lgkmcnt(" #n ")" ::: "memory")
; #define PG8_BAR __builtin_amdgcn_s_barrier()
; #define PG8_SCHED __builtin_amdgcn_sched_barrier(0)
;     ...
;         for (int t = 0; t < nt; t += 2) {
;             const bool last = (t == nt - 2);
;             const char* a1 = cA + (ptrdiff_t)(t + 1) * kstepA;
;             const char* a2 = last ? nA : cA + (ptrdiff_t)(t + 2) * kstepA; const char* b2 = last ? nB : cB + (ptrdiff_t)(t + 2) * kstep;
;             const char* a3 = a2 + kstepA; const char* b3 = b2 + kstep;
;             if (last && has_next) S.a_ready(nxt);
;             if constexpr (SP2) {
;             PG8_LDB(B0, 0, 0); PG8_LDB(B1, 0, 1); PG8_SCHED; PG8_LDA(At, 0, 0); PG8_STAGE(PG8_SA(1, 1), a1 + hstepA, voffA);
;             PG8_WAIT_V(8); PG8_WAIT_L(0); PG8_BAR; PG8_MMA(0, 0, At, B0); PG8_MMA(0, 1, At, B1); PG8_BAR; PG8_SCHED;
;             PG8_LDA(At, 0, 1); PG8_STAGE(PG8_SB(0, 0), b2, voffB); PG8_STAGE(PG8_SB(0, 1), b2 + hstepB, voffB); PG8_STAGE(PG8_SA(0, 0), a2, voffA);
;             PG8_WAIT_V(8); PG8_WAIT_L(0); PG8_BAR; PG8_MMA(1, 0, At, B0); PG8_MMA(1, 1, At, B1); PG8_BAR; PG8_SCHED;
.LBB0_1128:
	s_add_u32 s36, s34, 0x4000
	s_addc_u32 s37, s35, 0
	s_cmp_eq_u32 s57, 28
	s_cselect_b32 s86, s29, s36
	s_cselect_b32 s87, s23, s37
	s_cselect_b32 s46, s31, s44
	s_cselect_b32 s47, s21, s56
	s_add_u32 s36, s86, 0x8000
	s_addc_u32 s37, s87, 0
	s_add_i32 s65, 0, 0x10000
	v_add_u32_e32 v0, s65, v242
	s_add_i32 s66, 0, 0x14000
	s_waitcnt lgkmcnt(0)
	ds_read_b128 v[130:133], v0
	ds_read_b128 v[134:137], v0 offset:1024
	ds_read_b128 v[138:141], v0 offset:2048
	ds_read_b128 v[142:145], v0 offset:3072
	v_add_u32_e32 v0, s66, v242
	ds_read_b128 v[146:149], v0
	ds_read_b128 v[150:153], v0 offset:1024
	ds_read_b128 v[154:157], v0 offset:2048
	ds_read_b128 v[158:161], v0 offset:3072
	s_add_i32 m0, s51, 0xc000
	ds_read_b128 v[162:165], v243
	ds_read_b128 v[166:169], v243 offset:1024
	ds_read_b128 v[170:173], v243 offset:2048
	ds_read_b128 v[174:177], v243 offset:3072
	ds_read_b128 v[178:181], v243 offset:4096
	ds_read_b128 v[182:185], v243 offset:5120
	ds_read_b128 v[198:201], v243 offset:6144
	ds_read_b128 v[202:205], v243 offset:7168
	global_load_lds_dwordx4 v194, s[34:35]
	s_add_i32 m0, s51, 0xe000
	s_nop 0
	global_load_lds_dwordx4 v196, s[34:35]
	s_waitcnt vmcnt(8)
	s_waitcnt lgkmcnt(0)
	s_setprio 1
	s_barrier
	v_mfma_f32_16x16x32_bf16 v[126:129], v[130:133], v[162:165], v[126:129]
	v_mfma_f32_16x16x32_bf16 v[126:129], v[134:137], v[166:169], v[126:129]
	v_mfma_f32_16x16x32_bf16 v[122:125], v[142:145], v[166:169], v[122:125]
	v_mfma_f32_16x16x32_bf16 v[122:125], v[138:141], v[162:165], v[122:125]
	v_mfma_f32_16x16x32_bf16 v[106:109], v[138:141], v[170:173], v[106:109]
	v_mfma_f32_16x16x32_bf16 v[106:109], v[142:145], v[174:177], v[106:109]
	v_mfma_f32_16x16x32_bf16 v[110:113], v[134:137], v[174:177], v[110:113]
	v_mfma_f32_16x16x32_bf16 v[110:113], v[130:133], v[170:173], v[110:113]
	v_mfma_f32_16x16x32_bf16 v[94:97], v[130:133], v[178:181], v[94:97]
	v_mfma_f32_16x16x32_bf16 v[94:97], v[134:137], v[182:185], v[94:97]
	v_mfma_f32_16x16x32_bf16 v[90:93], v[142:145], v[182:185], v[90:93]
	v_mfma_f32_16x16x32_bf16 v[90:93], v[138:141], v[178:181], v[90:93]
	v_mfma_f32_16x16x32_bf16 v[74:77], v[138:141], v[198:201], v[74:77]
	v_mfma_f32_16x16x32_bf16 v[74:77], v[142:145], v[202:205], v[74:77]
	v_mfma_f32_16x16x32_bf16 v[78:81], v[134:137], v[202:205], v[78:81]
	v_mfma_f32_16x16x32_bf16 v[78:81], v[130:133], v[198:201], v[78:81]
	s_setprio 0
	s_setprio 1
	v_mfma_f32_16x16x32_bf16 v[118:121], v[146:149], v[162:165], v[118:121]
	v_mfma_f32_16x16x32_bf16 v[118:121], v[150:153], v[166:169], v[118:121]
	v_mfma_f32_16x16x32_bf16 v[114:117], v[158:161], v[166:169], v[114:117]
	v_mfma_f32_16x16x32_bf16 v[114:117], v[154:157], v[162:165], v[114:117]
	v_mfma_f32_16x16x32_bf16 v[98:101], v[154:157], v[170:173], v[98:101]
	v_mfma_f32_16x16x32_bf16 v[98:101], v[158:161], v[174:177], v[98:101]
	v_mfma_f32_16x16x32_bf16 v[102:105], v[150:153], v[174:177], v[102:105]
	v_mfma_f32_16x16x32_bf16 v[102:105], v[146:149], v[170:173], v[102:105]
	v_mfma_f32_16x16x32_bf16 v[86:89], v[146:149], v[178:181], v[86:89]
	v_mfma_f32_16x16x32_bf16 v[86:89], v[150:153], v[182:185], v[86:89]
	v_mfma_f32_16x16x32_bf16 v[82:85], v[158:161], v[182:185], v[82:85]
	v_mfma_f32_16x16x32_bf16 v[82:85], v[154:157], v[178:181], v[82:85]
	v_mfma_f32_16x16x32_bf16 v[66:69], v[154:157], v[198:201], v[66:69]
	v_mfma_f32_16x16x32_bf16 v[66:69], v[158:161], v[202:205], v[66:69]
	v_mfma_f32_16x16x32_bf16 v[70:73], v[150:153], v[202:205], v[70:73]
	v_mfma_f32_16x16x32_bf16 v[70:73], v[146:149], v[198:201], v[70:73]
	s_setprio 0
	s_barrier
	s_add_i32 s65, s65, s49
	s_mov_b32 m0, s65
	ds_read_b128 v[162:165], v243 offset:16384
	ds_read_b128 v[166:169], v243 offset:17408
	ds_read_b128 v[170:173], v243 offset:18432
	ds_read_b128 v[174:177], v243 offset:19456
	ds_read_b128 v[178:181], v243 offset:20480
	ds_read_b128 v[182:185], v243 offset:21504
	ds_read_b128 v[198:201], v243 offset:22528
	ds_read_b128 v[202:205], v243 offset:23552
	global_load_lds_dwordx4 v188, s[46:47]
	s_add_i32 m0, s65, 0x2000
	s_add_u32 s90, s46, 0x4000
	s_addc_u32 s91, s47, 0
	s_add_i32 s65, s66, s49
	global_load_lds_dwordx4 v192, s[46:47]
	s_mov_b32 m0, s65
	s_nop 0
	global_load_lds_dwordx4 v188, s[90:91]
	s_add_i32 m0, s65, 0x2000
	s_nop 0
	global_load_lds_dwordx4 v192, s[90:91]
	s_mov_b32 m0, s51
	s_nop 0
	global_load_lds_dwordx4 v186, s[86:87]
	s_mov_b32 m0, s54
	s_nop 0
	global_load_lds_dwordx4 v190, s[86:87]
	s_waitcnt vmcnt(8)
	s_waitcnt lgkmcnt(0)
	s_setprio 1
	s_barrier
	v_mfma_f32_16x16x32_bf16 v[62:65], v[130:133], v[162:165], v[62:65]
	v_mfma_f32_16x16x32_bf16 v[62:65], v[134:137], v[166:169], v[62:65]
	v_mfma_f32_16x16x32_bf16 v[58:61], v[142:145], v[166:169], v[58:61]
	v_mfma_f32_16x16x32_bf16 v[58:61], v[138:141], v[162:165], v[58:61]
	v_mfma_f32_16x16x32_bf16 v[42:45], v[138:141], v[170:173], v[42:45]
	v_mfma_f32_16x16x32_bf16 v[42:45], v[142:145], v[174:177], v[42:45]
	v_mfma_f32_16x16x32_bf16 v[46:49], v[134:137], v[174:177], v[46:49]
	v_mfma_f32_16x16x32_bf16 v[46:49], v[130:133], v[170:173], v[46:49]
	v_mfma_f32_16x16x32_bf16 v[30:33], v[130:133], v[178:181], v[30:33]
	v_mfma_f32_16x16x32_bf16 v[30:33], v[134:137], v[182:185], v[30:33]
	v_mfma_f32_16x16x32_bf16 v[26:29], v[142:145], v[182:185], v[26:29]
	v_mfma_f32_16x16x32_bf16 v[26:29], v[138:141], v[178:181], v[26:29]
	v_mfma_f32_16x16x32_bf16 v[10:13], v[138:141], v[198:201], v[10:13]
	v_mfma_f32_16x16x32_bf16 v[10:13], v[142:145], v[202:205], v[10:13]
	v_mfma_f32_16x16x32_bf16 v[14:17], v[134:137], v[202:205], v[14:17]
	v_mfma_f32_16x16x32_bf16 v[14:17], v[130:133], v[198:201], v[14:17]
	s_setprio 0
	s_setprio 1
	v_mfma_f32_16x16x32_bf16 v[54:57], v[146:149], v[162:165], v[54:57]
	v_mfma_f32_16x16x32_bf16 v[54:57], v[150:153], v[166:169], v[54:57]
	v_mfma_f32_16x16x32_bf16 v[50:53], v[158:161], v[166:169], v[50:53]
	v_mfma_f32_16x16x32_bf16 v[50:53], v[154:157], v[162:165], v[50:53]
	v_mfma_f32_16x16x32_bf16 v[34:37], v[154:157], v[170:173], v[34:37]
	v_mfma_f32_16x16x32_bf16 v[34:37], v[158:161], v[174:177], v[34:37]
	v_mfma_f32_16x16x32_bf16 v[38:41], v[150:153], v[174:177], v[38:41]
	v_mfma_f32_16x16x32_bf16 v[38:41], v[146:149], v[170:173], v[38:41]
	v_mfma_f32_16x16x32_bf16 v[22:25], v[146:149], v[178:181], v[22:25]
	v_mfma_f32_16x16x32_bf16 v[22:25], v[150:153], v[182:185], v[22:25]
	v_mfma_f32_16x16x32_bf16 v[18:21], v[158:161], v[182:185], v[18:21]
	v_mfma_f32_16x16x32_bf16 v[18:21], v[154:157], v[178:181], v[18:21]
	v_mfma_f32_16x16x32_bf16 v[2:5], v[154:157], v[198:201], v[2:5]
	v_mfma_f32_16x16x32_bf16 v[2:5], v[158:161], v[202:205], v[2:5]
	v_mfma_f32_16x16x32_bf16 v[6:9], v[150:153], v[202:205], v[6:9]
	v_mfma_f32_16x16x32_bf16 v[6:9], v[146:149], v[198:201], v[6:9]
	s_setprio 0
	s_barrier
; #define PG8_STAGE(bufoff, gbase, voff) do { _Pragma("unroll") for (int _i = 0; _i < 2; ++_i) \
;         __builtin_amdgcn_global_load_lds((const unsigned*)((const char*)(gbase) + (voff)[_i]), (PG8_LAS unsigned*)(lds + (bufoff) + ldsw + _i * 8192), 16, 0, 0); } while (0)
; #define PG8_LDA(dst, b, h) do { _Pragma("unroll") for (int m = 0; m < 4; ++m) _Pragma("unroll") for (int k = 0; k < 2; ++k) dst[m][k] = *(const PG8_LAS bf16x8*)(lds + PG8_SA(b, h) + aoff + m * 2048 + k * 1024); } while (0)
; #define PG8_LDB(dst, b, h) do { _Pragma("unroll") for (int n = 0; n < 2; ++n) _Pragma("unroll") for (int k = 0; k < 2; ++k) dst[n][k] = *(const PG8_LAS bf16x8*)(lds + PG8_SB(b, h) + boff + n * 2048 + k * 1024); } while (0)
; #define PG8_MMA(ai, bj, At, Bt) do { __builtin_amdgcn_s_setprio(1); _Pragma("unroll") for (int m = 0; m < 4; ++m) _Pragma("unroll") for (int n = 0; n < 2; ++n) _Pragma("unroll") for (int k = 0; k < 2; ++k) \
;         acc[ai][bj][m][n] = __builtin_amdgcn_mfma_f32_16x16x32_bf16(Bt[n][k], At[m][k], acc[ai][bj][m][n], 0, 0, 0); __builtin_amdgcn_s_setprio(0); } while (0)
; #define PG8_WAIT_V(n) asm volatile("s_waitcnt vmcnt(" #n ")" ::: "memory")
; #define PG8_WAIT_L(n) asm volatile("s_waitcnt lgkmcnt(" #n ")" ::: "memory")
; #define PG8_BAR __builtin_amdgcn_s_barrier()
; #define PG8_SCHED __builtin_amdgcn_sched_barrier(0)
;     ...
;             PG8_LDB(B0, 1, 0); PG8_LDB(B1, 1, 1); PG8_SCHED; PG8_LDA(At, 1, 0); PG8_STAGE(PG8_SA(0, 1), a2 + hstepA, voffA);
;             PG8_WAIT_V(8); PG8_WAIT_L(0); PG8_BAR; PG8_MMA(0, 0, At, B0); PG8_MMA(0, 1, At, B1); PG8_BAR; PG8_SCHED;
;             PG8_LDA(At, 1, 1); PG8_STAGE(PG8_SB(1, 0), b3, voffB); PG8_STAGE(PG8_SB(1, 1), b3 + hstepB, voffB); PG8_STAGE(PG8_SA(1, 0), a3, voffA);
;             PG8_WAIT_V(8); PG8_WAIT_L(0); PG8_BAR; PG8_MMA(1, 0, At, B0); PG8_MMA(1, 1, At, B1); PG8_BAR; PG8_SCHED;
.Lout_mid:
	s_add_i32 s65, 0, 0x18000
	v_add_u32_e32 v0, s65, v242
	s_add_i32 s66, 0, 0x1c000
	ds_read_b128 v[130:133], v0
	ds_read_b128 v[134:137], v0 offset:1024
	ds_read_b128 v[138:141], v0 offset:2048
	ds_read_b128 v[142:145], v0 offset:3072
	v_add_u32_e32 v0, s66, v242
	ds_read_b128 v[146:149], v0
	ds_read_b128 v[150:153], v0 offset:1024
	ds_read_b128 v[154:157], v0 offset:2048
	ds_read_b128 v[158:161], v0 offset:3072
	s_add_u32 s86, s86, 0x4000
	s_addc_u32 s87, s87, 0
	s_mov_b32 m0, s55
	ds_read_b128 v[162:165], v243 offset:32768
	ds_read_b128 v[166:169], v243 offset:33792
	ds_read_b128 v[170:173], v243 offset:34816
	ds_read_b128 v[174:177], v243 offset:35840
	ds_read_b128 v[178:181], v243 offset:36864
	ds_read_b128 v[182:185], v243 offset:37888
	ds_read_b128 v[198:201], v243 offset:38912
	ds_read_b128 v[202:205], v243 offset:39936
	global_load_lds_dwordx4 v186, s[86:87]
	s_mov_b32 m0, s61
	s_nop 0
	global_load_lds_dwordx4 v190, s[86:87]
	s_waitcnt vmcnt(8)
	s_waitcnt lgkmcnt(0)
	s_setprio 1
	s_barrier
	v_mfma_f32_16x16x32_bf16 v[126:129], v[130:133], v[162:165], v[126:129]
	v_mfma_f32_16x16x32_bf16 v[126:129], v[134:137], v[166:169], v[126:129]
	v_mfma_f32_16x16x32_bf16 v[122:125], v[142:145], v[166:169], v[122:125]
	v_mfma_f32_16x16x32_bf16 v[122:125], v[138:141], v[162:165], v[122:125]
	v_mfma_f32_16x16x32_bf16 v[106:109], v[138:141], v[170:173], v[106:109]
	v_mfma_f32_16x16x32_bf16 v[106:109], v[142:145], v[174:177], v[106:109]
	v_mfma_f32_16x16x32_bf16 v[110:113], v[134:137], v[174:177], v[110:113]
	v_mfma_f32_16x16x32_bf16 v[110:113], v[130:133], v[170:173], v[110:113]
	v_mfma_f32_16x16x32_bf16 v[94:97], v[130:133], v[178:181], v[94:97]
	v_mfma_f32_16x16x32_bf16 v[94:97], v[134:137], v[182:185], v[94:97]
	v_mfma_f32_16x16x32_bf16 v[90:93], v[142:145], v[182:185], v[90:93]
	v_mfma_f32_16x16x32_bf16 v[90:93], v[138:141], v[178:181], v[90:93]
	v_mfma_f32_16x16x32_bf16 v[74:77], v[138:141], v[198:201], v[74:77]
	v_mfma_f32_16x16x32_bf16 v[74:77], v[142:145], v[202:205], v[74:77]
	v_mfma_f32_16x16x32_bf16 v[78:81], v[134:137], v[202:205], v[78:81]
	v_mfma_f32_16x16x32_bf16 v[78:81], v[130:133], v[198:201], v[78:81]
	s_setprio 0
	s_setprio 1
	v_mfma_f32_16x16x32_bf16 v[118:121], v[146:149], v[162:165], v[118:121]
	v_mfma_f32_16x16x32_bf16 v[118:121], v[150:153], v[166:169], v[118:121]
	v_mfma_f32_16x16x32_bf16 v[114:117], v[158:161], v[166:169], v[114:117]
	v_mfma_f32_16x16x32_bf16 v[114:117], v[154:157], v[162:165], v[114:117]
	v_mfma_f32_16x16x32_bf16 v[98:101], v[154:157], v[170:173], v[98:101]
	v_mfma_f32_16x16x32_bf16 v[98:101], v[158:161], v[174:177], v[98:101]
	v_mfma_f32_16x16x32_bf16 v[102:105], v[150:153], v[174:177], v[102:105]
	v_mfma_f32_16x16x32_bf16 v[102:105], v[146:149], v[170:173], v[102:105]
	v_mfma_f32_16x16x32_bf16 v[86:89], v[146:149], v[178:181], v[86:89]
	v_mfma_f32_16x16x32_bf16 v[86:89], v[150:153], v[182:185], v[86:89]
	v_mfma_f32_16x16x32_bf16 v[82:85], v[158:161], v[182:185], v[82:85]
	v_mfma_f32_16x16x32_bf16 v[82:85], v[154:157], v[178:181], v[82:85]
	v_mfma_f32_16x16x32_bf16 v[66:69], v[154:157], v[198:201], v[66:69]
	v_mfma_f32_16x16x32_bf16 v[66:69], v[158:161], v[202:205], v[66:69]
	v_mfma_f32_16x16x32_bf16 v[70:73], v[150:153], v[202:205], v[70:73]
	v_mfma_f32_16x16x32_bf16 v[70:73], v[146:149], v[198:201], v[70:73]
	s_setprio 0
	s_barrier
	s_add_u32 s86, s46, 0x8000
	s_addc_u32 s87, s47, 0
	s_add_i32 s65, s65, s49
	s_mov_b32 m0, s65
	ds_read_b128 v[162:165], v243 offset:49152
	ds_read_b128 v[166:169], v243 offset:50176
	ds_read_b128 v[170:173], v243 offset:51200
	ds_read_b128 v[174:177], v243 offset:52224
	ds_read_b128 v[178:181], v243 offset:53248
	ds_read_b128 v[182:185], v243 offset:54272
	ds_read_b128 v[198:201], v243 offset:55296
	ds_read_b128 v[202:205], v243 offset:56320
	global_load_lds_dwordx4 v188, s[86:87]
	s_add_i32 m0, s65, 0x2000
	s_add_u32 s46, s46, 0xc000
	s_addc_u32 s47, s47, 0
	s_add_i32 s65, s66, s49
	global_load_lds_dwordx4 v192, s[86:87]
	s_mov_b32 m0, s65
	s_nop 0
	global_load_lds_dwordx4 v188, s[46:47]
	s_add_i32 m0, s65, 0x2000
	s_nop 0
	global_load_lds_dwordx4 v192, s[46:47]
	s_mov_b32 m0, s83
	s_nop 0
	global_load_lds_dwordx4 v186, s[36:37]
	v_lshl_add_u64 v[206:207], s[36:37], 0, v[190:191]
	s_mov_b32 m0, s85
	s_nop 0
	global_load_lds_dwordx4 v[206:207], off
	s_waitcnt vmcnt(8)
	s_waitcnt lgkmcnt(0)
	s_setprio 1
	s_barrier
	v_mfma_f32_16x16x32_bf16 v[62:65], v[130:133], v[162:165], v[62:65]
	v_mfma_f32_16x16x32_bf16 v[62:65], v[134:137], v[166:169], v[62:65]
	v_mfma_f32_16x16x32_bf16 v[58:61], v[142:145], v[166:169], v[58:61]
	v_mfma_f32_16x16x32_bf16 v[58:61], v[138:141], v[162:165], v[58:61]
	v_mfma_f32_16x16x32_bf16 v[42:45], v[138:141], v[170:173], v[42:45]
	v_mfma_f32_16x16x32_bf16 v[42:45], v[142:145], v[174:177], v[42:45]
	v_mfma_f32_16x16x32_bf16 v[46:49], v[134:137], v[174:177], v[46:49]
	v_mfma_f32_16x16x32_bf16 v[46:49], v[130:133], v[170:173], v[46:49]
	v_mfma_f32_16x16x32_bf16 v[30:33], v[130:133], v[178:181], v[30:33]
	v_mfma_f32_16x16x32_bf16 v[30:33], v[134:137], v[182:185], v[30:33]
	v_mfma_f32_16x16x32_bf16 v[26:29], v[142:145], v[182:185], v[26:29]
	v_mfma_f32_16x16x32_bf16 v[26:29], v[138:141], v[178:181], v[26:29]
	v_mfma_f32_16x16x32_bf16 v[10:13], v[138:141], v[198:201], v[10:13]
	v_mfma_f32_16x16x32_bf16 v[10:13], v[142:145], v[202:205], v[10:13]
	v_mfma_f32_16x16x32_bf16 v[14:17], v[134:137], v[202:205], v[14:17]
	v_mfma_f32_16x16x32_bf16 v[14:17], v[130:133], v[198:201], v[14:17]
	s_setprio 0
	s_setprio 1
	v_mfma_f32_16x16x32_bf16 v[54:57], v[146:149], v[162:165], v[54:57]
	v_mfma_f32_16x16x32_bf16 v[54:57], v[150:153], v[166:169], v[54:57]
	v_mfma_f32_16x16x32_bf16 v[50:53], v[158:161], v[166:169], v[50:53]
	v_mfma_f32_16x16x32_bf16 v[50:53], v[154:157], v[162:165], v[50:53]
	v_mfma_f32_16x16x32_bf16 v[34:37], v[154:157], v[170:173], v[34:37]
	v_mfma_f32_16x16x32_bf16 v[34:37], v[158:161], v[174:177], v[34:37]
	v_mfma_f32_16x16x32_bf16 v[38:41], v[150:153], v[174:177], v[38:41]
	v_mfma_f32_16x16x32_bf16 v[38:41], v[146:149], v[170:173], v[38:41]
	v_mfma_f32_16x16x32_bf16 v[22:25], v[146:149], v[178:181], v[22:25]
	v_mfma_f32_16x16x32_bf16 v[22:25], v[150:153], v[182:185], v[22:25]
	v_mfma_f32_16x16x32_bf16 v[18:21], v[158:161], v[182:185], v[18:21]
	v_mfma_f32_16x16x32_bf16 v[18:21], v[154:157], v[178:181], v[18:21]
	v_mfma_f32_16x16x32_bf16 v[2:5], v[154:157], v[198:201], v[2:5]
	v_mfma_f32_16x16x32_bf16 v[2:5], v[158:161], v[202:205], v[2:5]
	v_mfma_f32_16x16x32_bf16 v[6:9], v[150:153], v[202:205], v[6:9]
	v_mfma_f32_16x16x32_bf16 v[6:9], v[146:149], v[198:201], v[6:9]
	s_setprio 0
	s_barrier
	s_add_i32 s57, s57, 2
	s_add_u32 s34, s34, 0x10000
	s_addc_u32 s35, s35, 0
	s_add_u32 s44, s44, 0x10000
	s_addc_u32 s56, s56, 0
	s_cmp_gt_u32 s57, 29
	s_cbranch_scc0 .LBB0_1128
	s_and_b64 vcc, exec, s[92:93]
	s_cbranch_vccz .LBB0_1131
	s_barrier

; #define PG8_STAGE(bufoff, gbase, voff) do { _Pragma("unroll") for (int _i = 0; _i < 2; ++_i) \
;         __builtin_amdgcn_global_load_lds((const unsigned*)((const char*)(gbase) + (voff)[_i]), (PG8_LAS unsigned*)(lds + (bufoff) + ldsw + _i * 8192), 16, 0, 0); } while (0)
; #define PG8_LDA(dst, b, h) do { _Pragma("unroll") for (int m = 0; m < 4; ++m) _Pragma("unroll") for (int k = 0; k < 2; ++k) dst[m][k] = *(const PG8_LAS bf16x8*)(lds + PG8_SA(b, h) + aoff + m * 2048 + k * 1024); } while (0)
; #define PG8_LDB(dst, b, h) do { _Pragma("unroll") for (int n = 0; n < 2; ++n) _Pragma("unroll") for (int k = 0; k < 2; ++k) dst[n][k] = *(const PG8_LAS bf16x8*)(lds + PG8_SB(b, h) + boff + n * 2048 + k * 1024); } while (0)
; #define PG8_MMA(ai, bj, At, Bt) do { __builtin_amdgcn_s_setprio(1); _Pragma("unroll") for (int m = 0; m < 4; ++m) _Pragma("unroll") for (int n = 0; n < 2; ++n) _Pragma("unroll") for (int k = 0; k < 2; ++k) \
;         acc[ai][bj][m][n] = __builtin_amdgcn_mfma_f32_16x16x32_bf16(Bt[n][k], At[m][k], acc[ai][bj][m][n], 0, 0, 0); __builtin_amdgcn_s_setprio(0); } while (0)
; #define PG8_WAIT_V(n) asm volatile("s_waitcnt vmcnt(" #n ")" ::: "memory")
; #define PG8_WAIT_L(n) asm volatile("s_waitcnt lgkmcnt(" #n ")" ::: "memory")
; #define PG8_BAR __builtin_amdgcn_s_barrier()
; #define PG8_SCHED __builtin_amdgcn_sched_barrier(0)
;     ...
;         for (int t = 0; t < nt; t += 2) {
;             const bool last = (t == nt - 2);
;             const char* a1 = cA + (ptrdiff_t)(t + 1) * kstepA;
;             const char* a2 = last ? nA : cA + (ptrdiff_t)(t + 2) * kstepA; const char* b2 = last ? nB : cB + (ptrdiff_t)(t + 2) * kstep;
;             const char* a3 = a2 + kstepA; const char* b3 = b2 + kstep;
;             if (last && has_next) S.a_ready(nxt);
;             if constexpr (SP2) {
;             PG8_LDB(B0, 0, 0); PG8_LDB(B1, 0, 1); PG8_SCHED; PG8_LDA(At, 0, 0); PG8_STAGE(PG8_SA(1, 1), a1 + hstepA, voffA);
;             PG8_WAIT_V(8); PG8_WAIT_L(0); PG8_BAR; PG8_MMA(0, 0, At, B0); PG8_MMA(0, 1, At, B1); PG8_BAR; PG8_SCHED;
;             PG8_LDA(At, 0, 1); PG8_STAGE(PG8_SB(0, 0), b2, voffB); PG8_STAGE(PG8_SB(0, 1), b2 + hstepB, voffB); PG8_STAGE(PG8_SA(0, 0), a2, voffA);
;             PG8_WAIT_V(8); PG8_WAIT_L(0); PG8_BAR; PG8_MMA(1, 0, At, B0); PG8_MMA(1, 1, At, B1); PG8_BAR; PG8_SCHED;
.Lup_nostg:
	s_add_u32 s36, s34, 0x10000
	s_addc_u32 s37, s35, 0
	s_cmp_eq_u32 s66, 28
	s_cselect_b32 s88, s57, s36
	s_cselect_b32 s89, s27, s37
	s_cselect_b32 s86, vcc_lo, vcc_hi
	s_cselect_b32 s87, s25, s65
	s_add_u32 s46, s88, 0x8000
	s_addc_u32 s47, s89, 0
	s_add_i32 s96, 0, 0x10000
	v_add_u32_e32 v0, s96, v192
	s_add_i32 s97, 0, 0x14000
	ds_read_b128 v[130:133], v0
	ds_read_b128 v[134:137], v0 offset:1024
	ds_read_b128 v[138:141], v0 offset:2048
	ds_read_b128 v[142:145], v0 offset:3072
	v_add_u32_e32 v0, s97, v192
	ds_read_b128 v[146:149], v0
	ds_read_b128 v[150:153], v0 offset:1024
	ds_read_b128 v[154:157], v0 offset:2048
	ds_read_b128 v[170:173], v0 offset:3072
	s_add_i32 m0, s48, 0xc000
	ds_read_b128 v[174:177], v193
	ds_read_b128 v[178:181], v193 offset:1024
	ds_read_b128 v[182:185], v193 offset:2048
	ds_read_b128 v[186:189], v193 offset:3072
	ds_read_b128 v[194:197], v193 offset:4096
	ds_read_b128 v[198:201], v193 offset:5120
	ds_read_b128 v[202:205], v193 offset:6144
	ds_read_b128 v[206:209], v193 offset:7168
	global_load_lds_dwordx4 v166, s[34:35]
	s_add_i32 m0, s48, 0xe000
	s_nop 0
	global_load_lds_dwordx4 v168, s[34:35]
	s_waitcnt vmcnt(8)
	s_waitcnt lgkmcnt(0)
	s_setprio 1
	s_barrier
	v_mfma_f32_16x16x32_bf16 v[126:129], v[130:133], v[174:177], 0
	v_mfma_f32_16x16x32_bf16 v[126:129], v[134:137], v[178:181], v[126:129]
	v_mfma_f32_16x16x32_bf16 v[122:125], v[142:145], v[178:181], 0
	v_mfma_f32_16x16x32_bf16 v[122:125], v[138:141], v[174:177], v[122:125]
	v_mfma_f32_16x16x32_bf16 v[114:117], v[138:141], v[182:185], 0
	v_mfma_f32_16x16x32_bf16 v[114:117], v[142:145], v[186:189], v[114:117]
	v_mfma_f32_16x16x32_bf16 v[118:121], v[134:137], v[186:189], 0
	v_mfma_f32_16x16x32_bf16 v[118:121], v[130:133], v[182:185], v[118:121]
	v_mfma_f32_16x16x32_bf16 v[110:113], v[130:133], v[194:197], 0
	v_mfma_f32_16x16x32_bf16 v[110:113], v[134:137], v[198:201], v[110:113]
	v_mfma_f32_16x16x32_bf16 v[106:109], v[142:145], v[198:201], 0
	v_mfma_f32_16x16x32_bf16 v[106:109], v[138:141], v[194:197], v[106:109]
	v_mfma_f32_16x16x32_bf16 v[98:101], v[138:141], v[202:205], 0
	v_mfma_f32_16x16x32_bf16 v[98:101], v[142:145], v[206:209], v[98:101]
	v_mfma_f32_16x16x32_bf16 v[102:105], v[134:137], v[206:209], 0
	v_mfma_f32_16x16x32_bf16 v[102:105], v[130:133], v[202:205], v[102:105]
	s_setprio 0
	s_setprio 1
	v_mfma_f32_16x16x32_bf16 v[30:33], v[146:149], v[174:177], 0
	v_mfma_f32_16x16x32_bf16 v[30:33], v[150:153], v[178:181], v[30:33]
	v_mfma_f32_16x16x32_bf16 v[46:49], v[170:173], v[178:181], 0
	v_mfma_f32_16x16x32_bf16 v[46:49], v[154:157], v[174:177], v[46:49]
	v_mfma_f32_16x16x32_bf16 v[34:37], v[154:157], v[182:185], 0
	v_mfma_f32_16x16x32_bf16 v[34:37], v[170:173], v[186:189], v[34:37]
	v_mfma_f32_16x16x32_bf16 v[26:29], v[150:153], v[186:189], 0
	v_mfma_f32_16x16x32_bf16 v[26:29], v[146:149], v[182:185], v[26:29]
	v_mfma_f32_16x16x32_bf16 v[94:97], v[146:149], v[194:197], 0
	v_mfma_f32_16x16x32_bf16 v[94:97], v[150:153], v[198:201], v[94:97]
	v_mfma_f32_16x16x32_bf16 v[90:93], v[170:173], v[198:201], 0
	v_mfma_f32_16x16x32_bf16 v[90:93], v[154:157], v[194:197], v[90:93]
	v_mfma_f32_16x16x32_bf16 v[82:85], v[154:157], v[202:205], 0
	v_mfma_f32_16x16x32_bf16 v[82:85], v[170:173], v[206:209], v[82:85]
	v_mfma_f32_16x16x32_bf16 v[86:89], v[150:153], v[206:209], 0
	v_mfma_f32_16x16x32_bf16 v[86:89], v[146:149], v[202:205], v[86:89]
	s_setprio 0
	s_barrier
	s_add_i32 s34, s96, s44
	s_mov_b32 m0, s34
	ds_read_b128 v[174:177], v193 offset:16384
	ds_read_b128 v[178:181], v193 offset:17408
	ds_read_b128 v[182:185], v193 offset:18432
	ds_read_b128 v[186:189], v193 offset:19456
	ds_read_b128 v[194:197], v193 offset:20480
	ds_read_b128 v[198:201], v193 offset:21504
	ds_read_b128 v[202:205], v193 offset:22528
	ds_read_b128 v[206:209], v193 offset:23552
	global_load_lds_dwordx4 v162, s[86:87]
	s_add_i32 m0, s34, 0x2000
	s_add_u32 s34, s86, 0x4000
	s_addc_u32 s35, s87, 0
	s_add_i32 s96, s97, s44
	global_load_lds_dwordx4 v158, s[86:87]
	s_mov_b32 m0, s96
	v_lshl_add_u64 v[210:211], s[88:89], 0, v[160:161]
	global_load_lds_dwordx4 v162, s[34:35]
	s_add_i32 m0, s96, 0x2000
	s_nop 0
	global_load_lds_dwordx4 v158, s[34:35]
	v_lshl_add_u64 v[190:191], s[88:89], 0, v[164:165]
	s_mov_b32 m0, s48
	s_nop 0
	global_load_lds_dwordx4 v[190:191], off
	s_mov_b32 m0, s49
	s_nop 0
	global_load_lds_dwordx4 v[210:211], off
	s_waitcnt vmcnt(8)
	s_waitcnt lgkmcnt(0)
	s_setprio 1
	s_barrier
	v_mfma_f32_16x16x32_bf16 v[78:81], v[130:133], v[174:177], 0
	v_mfma_f32_16x16x32_bf16 v[78:81], v[134:137], v[178:181], v[78:81]
	v_mfma_f32_16x16x32_bf16 v[74:77], v[142:145], v[178:181], 0
	v_mfma_f32_16x16x32_bf16 v[74:77], v[138:141], v[174:177], v[74:77]
	v_mfma_f32_16x16x32_bf16 v[66:69], v[138:141], v[182:185], 0
	v_mfma_f32_16x16x32_bf16 v[66:69], v[142:145], v[186:189], v[66:69]
	v_mfma_f32_16x16x32_bf16 v[70:73], v[134:137], v[186:189], 0
	v_mfma_f32_16x16x32_bf16 v[70:73], v[130:133], v[182:185], v[70:73]
	v_mfma_f32_16x16x32_bf16 v[42:45], v[130:133], v[194:197], 0
	v_mfma_f32_16x16x32_bf16 v[42:45], v[134:137], v[198:201], v[42:45]
	v_mfma_f32_16x16x32_bf16 v[6:9], v[142:145], v[198:201], 0
	v_mfma_f32_16x16x32_bf16 v[6:9], v[138:141], v[194:197], v[6:9]
	v_mfma_f32_16x16x32_bf16 v[2:5], v[138:141], v[202:205], 0
	v_mfma_f32_16x16x32_bf16 v[2:5], v[142:145], v[206:209], v[2:5]
	v_mfma_f32_16x16x32_bf16 v[38:41], v[134:137], v[206:209], 0
	v_mfma_f32_16x16x32_bf16 v[38:41], v[130:133], v[202:205], v[38:41]
	s_setprio 0
	s_setprio 1
	v_mfma_f32_16x16x32_bf16 v[62:65], v[146:149], v[174:177], 0
	v_mfma_f32_16x16x32_bf16 v[62:65], v[150:153], v[178:181], v[62:65]
	v_mfma_f32_16x16x32_bf16 v[58:61], v[170:173], v[178:181], 0
	v_mfma_f32_16x16x32_bf16 v[58:61], v[154:157], v[174:177], v[58:61]
	v_mfma_f32_16x16x32_bf16 v[50:53], v[154:157], v[182:185], 0
	v_mfma_f32_16x16x32_bf16 v[50:53], v[170:173], v[186:189], v[50:53]
	v_mfma_f32_16x16x32_bf16 v[54:57], v[150:153], v[186:189], 0
	v_mfma_f32_16x16x32_bf16 v[54:57], v[146:149], v[182:185], v[54:57]
	v_mfma_f32_16x16x32_bf16 v[22:25], v[146:149], v[194:197], 0
	v_mfma_f32_16x16x32_bf16 v[22:25], v[150:153], v[198:201], v[22:25]
	v_mfma_f32_16x16x32_bf16 v[18:21], v[170:173], v[198:201], 0
	v_mfma_f32_16x16x32_bf16 v[18:21], v[154:157], v[194:197], v[18:21]
	v_mfma_f32_16x16x32_bf16 v[10:13], v[154:157], v[202:205], 0
	v_mfma_f32_16x16x32_bf16 v[10:13], v[170:173], v[206:209], v[10:13]
	v_mfma_f32_16x16x32_bf16 v[14:17], v[150:153], v[206:209], 0
	v_mfma_f32_16x16x32_bf16 v[14:17], v[146:149], v[202:205], v[14:17]
	s_setprio 0
	s_barrier
	s_branch .Lup_mid

; #define PG8_STAGE(bufoff, gbase, voff) do { _Pragma("unroll") for (int _i = 0; _i < 2; ++_i) \
;         __builtin_amdgcn_global_load_lds((const unsigned*)((const char*)(gbase) + (voff)[_i]), (PG8_LAS unsigned*)(lds + (bufoff) + ldsw + _i * 8192), 16, 0, 0); } while (0)
; #define PG8_LDA(dst, b, h) do { _Pragma("unroll") for (int m = 0; m < 4; ++m) _Pragma("unroll") for (int k = 0; k < 2; ++k) dst[m][k] = *(const PG8_LAS bf16x8*)(lds + PG8_SA(b, h) + aoff + m * 2048 + k * 1024); } while (0)
; #define PG8_LDB(dst, b, h) do { _Pragma("unroll") for (int n = 0; n < 2; ++n) _Pragma("unroll") for (int k = 0; k < 2; ++k) dst[n][k] = *(const PG8_LAS bf16x8*)(lds + PG8_SB(b, h) + boff + n * 2048 + k * 1024); } while (0)
; #define PG8_MMA(ai, bj, At, Bt) do { __builtin_amdgcn_s_setprio(1); _Pragma("unroll") for (int m = 0; m < 4; ++m) _Pragma("unroll") for (int n = 0; n < 2; ++n) _Pragma("unroll") for (int k = 0; k < 2; ++k) \
;         acc[ai][bj][m][n] = __builtin_amdgcn_mfma_f32_16x16x32_bf16(Bt[n][k], At[m][k], acc[ai][bj][m][n], 0, 0, 0); __builtin_amdgcn_s_setprio(0); } while (0)
; #define PG8_WAIT_V(n) asm volatile("s_waitcnt vmcnt(" #n ")" ::: "memory")
; #define PG8_WAIT_L(n) asm volatile("s_waitcnt lgkmcnt(" #n ")" ::: "memory")
; #define PG8_BAR __builtin_amdgcn_s_barrier()
; #define PG8_SCHED __builtin_amdgcn_sched_barrier(0)
;     ...
;         for (int t = 0; t < nt; t += 2) {
;             const bool last = (t == nt - 2);
;             const char* a1 = cA + (ptrdiff_t)(t + 1) * kstepA;
;             const char* a2 = last ? nA : cA + (ptrdiff_t)(t + 2) * kstepA; const char* b2 = last ? nB : cB + (ptrdiff_t)(t + 2) * kstep;
;             const char* a3 = a2 + kstepA; const char* b3 = b2 + kstep;
;             if (last && has_next) S.a_ready(nxt);
;             if constexpr (SP2) {
;             PG8_LDB(B0, 0, 0); PG8_LDB(B1, 0, 1); PG8_SCHED; PG8_LDA(At, 0, 0); PG8_STAGE(PG8_SA(1, 1), a1 + hstepA, voffA);
;             PG8_WAIT_V(8); PG8_WAIT_L(0); PG8_BAR; PG8_MMA(0, 0, At, B0); PG8_MMA(0, 1, At, B1); PG8_BAR; PG8_SCHED;
;             PG8_LDA(At, 0, 1); PG8_STAGE(PG8_SB(0, 0), b2, voffB); PG8_STAGE(PG8_SB(0, 1), b2 + hstepB, voffB); PG8_STAGE(PG8_SA(0, 0), a2, voffA);
;             PG8_WAIT_V(8); PG8_WAIT_L(0); PG8_BAR; PG8_MMA(1, 0, At, B0); PG8_MMA(1, 1, At, B1); PG8_BAR; PG8_SCHED;
.LBB0_1256:
	s_add_u32 s36, s34, 0x10000
	s_addc_u32 s37, s35, 0
	s_cmp_eq_u32 s66, 28
	s_cselect_b32 s88, s57, s36
	s_cselect_b32 s89, s27, s37
	s_cselect_b32 s86, vcc_lo, vcc_hi
	s_cselect_b32 s87, s25, s65
	s_add_u32 s46, s88, 0x8000
	s_addc_u32 s47, s89, 0
	s_add_i32 s96, 0, 0x10000
	v_add_u32_e32 v0, s96, v192
	s_add_i32 s97, 0, 0x14000
	ds_read_b128 v[130:133], v0
	ds_read_b128 v[134:137], v0 offset:1024
	ds_read_b128 v[138:141], v0 offset:2048
	ds_read_b128 v[142:145], v0 offset:3072
	v_add_u32_e32 v0, s97, v192
	ds_read_b128 v[146:149], v0
	ds_read_b128 v[150:153], v0 offset:1024
	ds_read_b128 v[154:157], v0 offset:2048
	ds_read_b128 v[170:173], v0 offset:3072
	s_add_i32 m0, s48, 0xc000
	ds_read_b128 v[174:177], v193
	ds_read_b128 v[178:181], v193 offset:1024
	ds_read_b128 v[182:185], v193 offset:2048
	ds_read_b128 v[186:189], v193 offset:3072
	ds_read_b128 v[194:197], v193 offset:4096
	ds_read_b128 v[198:201], v193 offset:5120
	ds_read_b128 v[202:205], v193 offset:6144
	ds_read_b128 v[206:209], v193 offset:7168
	global_load_lds_dwordx4 v166, s[34:35]
	s_add_i32 m0, s48, 0xe000
	s_nop 0
	global_load_lds_dwordx4 v168, s[34:35]
	s_waitcnt vmcnt(8)
	s_waitcnt lgkmcnt(0)
	s_setprio 1
	s_barrier
	v_mfma_f32_16x16x32_bf16 v[126:129], v[130:133], v[174:177], v[126:129]
	v_mfma_f32_16x16x32_bf16 v[126:129], v[134:137], v[178:181], v[126:129]
	v_mfma_f32_16x16x32_bf16 v[122:125], v[142:145], v[178:181], v[122:125]
	v_mfma_f32_16x16x32_bf16 v[122:125], v[138:141], v[174:177], v[122:125]
	v_mfma_f32_16x16x32_bf16 v[114:117], v[138:141], v[182:185], v[114:117]
	v_mfma_f32_16x16x32_bf16 v[114:117], v[142:145], v[186:189], v[114:117]
	v_mfma_f32_16x16x32_bf16 v[118:121], v[134:137], v[186:189], v[118:121]
	v_mfma_f32_16x16x32_bf16 v[118:121], v[130:133], v[182:185], v[118:121]
	v_mfma_f32_16x16x32_bf16 v[110:113], v[130:133], v[194:197], v[110:113]
	v_mfma_f32_16x16x32_bf16 v[110:113], v[134:137], v[198:201], v[110:113]
	v_mfma_f32_16x16x32_bf16 v[106:109], v[142:145], v[198:201], v[106:109]
	v_mfma_f32_16x16x32_bf16 v[106:109], v[138:141], v[194:197], v[106:109]
	v_mfma_f32_16x16x32_bf16 v[98:101], v[138:141], v[202:205], v[98:101]
	v_mfma_f32_16x16x32_bf16 v[98:101], v[142:145], v[206:209], v[98:101]
	v_mfma_f32_16x16x32_bf16 v[102:105], v[134:137], v[206:209], v[102:105]
	v_mfma_f32_16x16x32_bf16 v[102:105], v[130:133], v[202:205], v[102:105]
	s_setprio 0
	s_setprio 1
	v_mfma_f32_16x16x32_bf16 v[30:33], v[146:149], v[174:177], v[30:33]
	v_mfma_f32_16x16x32_bf16 v[30:33], v[150:153], v[178:181], v[30:33]
	v_mfma_f32_16x16x32_bf16 v[46:49], v[170:173], v[178:181], v[46:49]
	v_mfma_f32_16x16x32_bf16 v[46:49], v[154:157], v[174:177], v[46:49]
	v_mfma_f32_16x16x32_bf16 v[34:37], v[154:157], v[182:185], v[34:37]
	v_mfma_f32_16x16x32_bf16 v[34:37], v[170:173], v[186:189], v[34:37]
	v_mfma_f32_16x16x32_bf16 v[26:29], v[150:153], v[186:189], v[26:29]
	v_mfma_f32_16x16x32_bf16 v[26:29], v[146:149], v[182:185], v[26:29]
	v_mfma_f32_16x16x32_bf16 v[94:97], v[146:149], v[194:197], v[94:97]
	v_mfma_f32_16x16x32_bf16 v[94:97], v[150:153], v[198:201], v[94:97]
	v_mfma_f32_16x16x32_bf16 v[90:93], v[170:173], v[198:201], v[90:93]
	v_mfma_f32_16x16x32_bf16 v[90:93], v[154:157], v[194:197], v[90:93]
	v_mfma_f32_16x16x32_bf16 v[82:85], v[154:157], v[202:205], v[82:85]
	v_mfma_f32_16x16x32_bf16 v[82:85], v[170:173], v[206:209], v[82:85]
	v_mfma_f32_16x16x32_bf16 v[86:89], v[150:153], v[206:209], v[86:89]
	v_mfma_f32_16x16x32_bf16 v[86:89], v[146:149], v[202:205], v[86:89]
	s_setprio 0
	s_barrier
	s_add_i32 s34, s96, s44
	s_mov_b32 m0, s34
	ds_read_b128 v[174:177], v193 offset:16384
	ds_read_b128 v[178:181], v193 offset:17408
	ds_read_b128 v[182:185], v193 offset:18432
	ds_read_b128 v[186:189], v193 offset:19456
	ds_read_b128 v[194:197], v193 offset:20480
	ds_read_b128 v[198:201], v193 offset:21504
	ds_read_b128 v[202:205], v193 offset:22528
	ds_read_b128 v[206:209], v193 offset:23552
	global_load_lds_dwordx4 v162, s[86:87]
	s_add_i32 m0, s34, 0x2000
	s_add_u32 s34, s86, 0x4000
	s_addc_u32 s35, s87, 0
	s_add_i32 s96, s97, s44
	global_load_lds_dwordx4 v158, s[86:87]
	s_mov_b32 m0, s96
	v_lshl_add_u64 v[210:211], s[88:89], 0, v[160:161]
	global_load_lds_dwordx4 v162, s[34:35]
	s_add_i32 m0, s96, 0x2000
	s_nop 0
	global_load_lds_dwordx4 v158, s[34:35]
	v_lshl_add_u64 v[190:191], s[88:89], 0, v[164:165]
	s_mov_b32 m0, s48
	s_nop 0
	global_load_lds_dwordx4 v[190:191], off
	s_mov_b32 m0, s49
	s_nop 0
	global_load_lds_dwordx4 v[210:211], off
	s_waitcnt vmcnt(8)
	s_waitcnt lgkmcnt(0)
	s_setprio 1
	s_barrier
	v_mfma_f32_16x16x32_bf16 v[78:81], v[130:133], v[174:177], v[78:81]
	v_mfma_f32_16x16x32_bf16 v[78:81], v[134:137], v[178:181], v[78:81]
	v_mfma_f32_16x16x32_bf16 v[74:77], v[142:145], v[178:181], v[74:77]
	v_mfma_f32_16x16x32_bf16 v[74:77], v[138:141], v[174:177], v[74:77]
	v_mfma_f32_16x16x32_bf16 v[66:69], v[138:141], v[182:185], v[66:69]
	v_mfma_f32_16x16x32_bf16 v[66:69], v[142:145], v[186:189], v[66:69]
	v_mfma_f32_16x16x32_bf16 v[70:73], v[134:137], v[186:189], v[70:73]
	v_mfma_f32_16x16x32_bf16 v[70:73], v[130:133], v[182:185], v[70:73]
	v_mfma_f32_16x16x32_bf16 v[42:45], v[130:133], v[194:197], v[42:45]
	v_mfma_f32_16x16x32_bf16 v[42:45], v[134:137], v[198:201], v[42:45]
	v_mfma_f32_16x16x32_bf16 v[6:9], v[142:145], v[198:201], v[6:9]
	v_mfma_f32_16x16x32_bf16 v[6:9], v[138:141], v[194:197], v[6:9]
	v_mfma_f32_16x16x32_bf16 v[2:5], v[138:141], v[202:205], v[2:5]
	v_mfma_f32_16x16x32_bf16 v[2:5], v[142:145], v[206:209], v[2:5]
	v_mfma_f32_16x16x32_bf16 v[38:41], v[134:137], v[206:209], v[38:41]
	v_mfma_f32_16x16x32_bf16 v[38:41], v[130:133], v[202:205], v[38:41]
	s_setprio 0
	s_setprio 1
	v_mfma_f32_16x16x32_bf16 v[62:65], v[146:149], v[174:177], v[62:65]
	v_mfma_f32_16x16x32_bf16 v[62:65], v[150:153], v[178:181], v[62:65]
	v_mfma_f32_16x16x32_bf16 v[58:61], v[170:173], v[178:181], v[58:61]
	v_mfma_f32_16x16x32_bf16 v[58:61], v[154:157], v[174:177], v[58:61]
	v_mfma_f32_16x16x32_bf16 v[50:53], v[154:157], v[182:185], v[50:53]
	v_mfma_f32_16x16x32_bf16 v[50:53], v[170:173], v[186:189], v[50:53]
	v_mfma_f32_16x16x32_bf16 v[54:57], v[150:153], v[186:189], v[54:57]
	v_mfma_f32_16x16x32_bf16 v[54:57], v[146:149], v[182:185], v[54:57]
	v_mfma_f32_16x16x32_bf16 v[22:25], v[146:149], v[194:197], v[22:25]
	v_mfma_f32_16x16x32_bf16 v[22:25], v[150:153], v[198:201], v[22:25]
	v_mfma_f32_16x16x32_bf16 v[18:21], v[170:173], v[198:201], v[18:21]
	v_mfma_f32_16x16x32_bf16 v[18:21], v[154:157], v[194:197], v[18:21]
	v_mfma_f32_16x16x32_bf16 v[10:13], v[154:157], v[202:205], v[10:13]
	v_mfma_f32_16x16x32_bf16 v[10:13], v[170:173], v[206:209], v[10:13]
	v_mfma_f32_16x16x32_bf16 v[14:17], v[150:153], v[206:209], v[14:17]
	v_mfma_f32_16x16x32_bf16 v[14:17], v[146:149], v[202:205], v[14:17]
	s_setprio 0
	s_barrier
; #define PG8_STAGE(bufoff, gbase, voff) do { _Pragma("unroll") for (int _i = 0; _i < 2; ++_i) \
;         __builtin_amdgcn_global_load_lds((const unsigned*)((const char*)(gbase) + (voff)[_i]), (PG8_LAS unsigned*)(lds + (bufoff) + ldsw + _i * 8192), 16, 0, 0); } while (0)
; #define PG8_LDA(dst, b, h) do { _Pragma("unroll") for (int m = 0; m < 4; ++m) _Pragma("unroll") for (int k = 0; k < 2; ++k) dst[m][k] = *(const PG8_LAS bf16x8*)(lds + PG8_SA(b, h) + aoff + m * 2048 + k * 1024); } while (0)
; #define PG8_LDB(dst, b, h) do { _Pragma("unroll") for (int n = 0; n < 2; ++n) _Pragma("unroll") for (int k = 0; k < 2; ++k) dst[n][k] = *(const PG8_LAS bf16x8*)(lds + PG8_SB(b, h) + boff + n * 2048 + k * 1024); } while (0)
; #define PG8_WAIT_V(n) asm volatile("s_waitcnt vmcnt(" #n ")" ::: "memory")
; #define PG8_WAIT_L(n) asm volatile("s_waitcnt lgkmcnt(" #n ")" ::: "memory")
; #define PG8_BAR __builtin_amdgcn_s_barrier()
; #define PG8_SCHED __builtin_amdgcn_sched_barrier(0)
;     ...
;             const char* a2 = last ? nA : cA + (ptrdiff_t)(t + 2) * kstepA; const char* b2 = last ? nB : cB + (ptrdiff_t)(t + 2) * kstep;
;             const char* a3 = a2 + kstepA; const char* b3 = b2 + kstep;
;             if (last && has_next) S.a_ready(nxt);
;             if constexpr (SP2) {
;             PG8_LDB(B0, 0, 0); PG8_LDB(B1, 0, 1); PG8_SCHED; PG8_LDA(At, 0, 0); PG8_STAGE(PG8_SA(1, 1), a1 + hstepA, voffA);
;             PG8_WAIT_V(8); PG8_WAIT_L(0); PG8_BAR; PG8_MMA(0, 0, At, B0); PG8_MMA(0, 1, At, B1); PG8_BAR; PG8_SCHED;
;             PG8_LDA(At, 0, 1); PG8_STAGE(PG8_SB(0, 0), b2, voffB); PG8_STAGE(PG8_SB(0, 1), b2 + hstepB, voffB); PG8_STAGE(PG8_SA(0, 0), a2, voffA);
;             PG8_WAIT_V(8); PG8_WAIT_L(0); PG8_BAR; PG8_MMA(1, 0, At, B0); PG8_MMA(1, 1, At, B1); PG8_BAR; PG8_SCHED;
;             PG8_LDB(B0, 1, 0); PG8_LDB(B1, 1, 1); PG8_SCHED; PG8_LDA(At, 1, 0); PG8_STAGE(PG8_SA(0, 1), a2 + hstepA, voffA);
;             PG8_WAIT_V(8); PG8_WAIT_L(0); PG8_BAR; PG8_MMA(0, 0, At, B0); PG8_MMA(0, 1, At, B1); PG8_BAR; PG8_SCHED;
;             PG8_LDA(At, 1, 1); PG8_STAGE(PG8_SB(1, 0), b3, voffB); PG8_STAGE(PG8_SB(1, 1), b3 + hstepB, voffB); PG8_STAGE(PG8_SA(1, 0), a3, voffA);
;             PG8_WAIT_V(8); PG8_WAIT_L(0); PG8_BAR; PG8_MMA(1, 0, At, B0); PG8_MMA(1, 1, At, B1); PG8_BAR; PG8_SCHED;
;     ...
;         if constexpr (ALIGN_EPI) { if (wr == 0) PG8_BAR; }
.Lup_mid:
	s_add_i32 s88, 0, 0x18000
	v_add_u32_e32 v0, s88, v192
	s_add_i32 s89, 0, 0x1c000
	ds_read_b128 v[130:133], v0
	ds_read_b128 v[134:137], v0 offset:1024
	ds_read_b128 v[138:141], v0 offset:2048
	ds_read_b128 v[142:145], v0 offset:3072
	v_add_u32_e32 v0, s89, v192
	ds_read_b128 v[146:149], v0
	ds_read_b128 v[150:153], v0 offset:1024
	ds_read_b128 v[154:157], v0 offset:2048
	ds_read_b128 v[170:173], v0 offset:3072
	s_mov_b32 m0, s51
	v_lshl_add_u64 v[190:191], v[190:191], 0, s[58:59]
	ds_read_b128 v[174:177], v193 offset:32768
	ds_read_b128 v[178:181], v193 offset:33792
	ds_read_b128 v[182:185], v193 offset:34816
	ds_read_b128 v[186:189], v193 offset:35840
	ds_read_b128 v[194:197], v193 offset:36864
	ds_read_b128 v[198:201], v193 offset:37888
	ds_read_b128 v[202:205], v193 offset:38912
	ds_read_b128 v[206:209], v193 offset:39936
	global_load_lds_dwordx4 v[190:191], off
	v_lshl_add_u64 v[190:191], v[210:211], 0, s[58:59]
	s_mov_b32 m0, s54
	s_nop 0
	global_load_lds_dwordx4 v[190:191], off
	s_waitcnt vmcnt(8)
	s_waitcnt lgkmcnt(0)
	s_setprio 1
	s_barrier
	v_mfma_f32_16x16x32_bf16 v[126:129], v[130:133], v[174:177], v[126:129]
	v_mfma_f32_16x16x32_bf16 v[126:129], v[134:137], v[178:181], v[126:129]
	v_mfma_f32_16x16x32_bf16 v[122:125], v[142:145], v[178:181], v[122:125]
	v_mfma_f32_16x16x32_bf16 v[122:125], v[138:141], v[174:177], v[122:125]
	v_mfma_f32_16x16x32_bf16 v[114:117], v[138:141], v[182:185], v[114:117]
	v_mfma_f32_16x16x32_bf16 v[114:117], v[142:145], v[186:189], v[114:117]
	v_mfma_f32_16x16x32_bf16 v[118:121], v[134:137], v[186:189], v[118:121]
	v_mfma_f32_16x16x32_bf16 v[118:121], v[130:133], v[182:185], v[118:121]
	v_mfma_f32_16x16x32_bf16 v[110:113], v[130:133], v[194:197], v[110:113]
	v_mfma_f32_16x16x32_bf16 v[110:113], v[134:137], v[198:201], v[110:113]
	v_mfma_f32_16x16x32_bf16 v[106:109], v[142:145], v[198:201], v[106:109]
	v_mfma_f32_16x16x32_bf16 v[106:109], v[138:141], v[194:197], v[106:109]
	v_mfma_f32_16x16x32_bf16 v[98:101], v[138:141], v[202:205], v[98:101]
	v_mfma_f32_16x16x32_bf16 v[98:101], v[142:145], v[206:209], v[98:101]
	v_mfma_f32_16x16x32_bf16 v[102:105], v[134:137], v[206:209], v[102:105]
	v_mfma_f32_16x16x32_bf16 v[102:105], v[130:133], v[202:205], v[102:105]
	s_setprio 0
	s_setprio 1
	v_mfma_f32_16x16x32_bf16 v[30:33], v[146:149], v[174:177], v[30:33]
	v_mfma_f32_16x16x32_bf16 v[30:33], v[150:153], v[178:181], v[30:33]
	v_mfma_f32_16x16x32_bf16 v[46:49], v[170:173], v[178:181], v[46:49]
	v_mfma_f32_16x16x32_bf16 v[46:49], v[154:157], v[174:177], v[46:49]
	v_mfma_f32_16x16x32_bf16 v[34:37], v[154:157], v[182:185], v[34:37]
	v_mfma_f32_16x16x32_bf16 v[34:37], v[170:173], v[186:189], v[34:37]
	v_mfma_f32_16x16x32_bf16 v[26:29], v[150:153], v[186:189], v[26:29]
	v_mfma_f32_16x16x32_bf16 v[26:29], v[146:149], v[182:185], v[26:29]
	v_mfma_f32_16x16x32_bf16 v[94:97], v[146:149], v[194:197], v[94:97]
	v_mfma_f32_16x16x32_bf16 v[94:97], v[150:153], v[198:201], v[94:97]
	v_mfma_f32_16x16x32_bf16 v[90:93], v[170:173], v[198:201], v[90:93]
	v_mfma_f32_16x16x32_bf16 v[90:93], v[154:157], v[194:197], v[90:93]
	v_mfma_f32_16x16x32_bf16 v[82:85], v[154:157], v[202:205], v[82:85]
	v_mfma_f32_16x16x32_bf16 v[82:85], v[170:173], v[206:209], v[82:85]
	v_mfma_f32_16x16x32_bf16 v[86:89], v[150:153], v[206:209], v[86:89]
	v_mfma_f32_16x16x32_bf16 v[86:89], v[146:149], v[202:205], v[86:89]
	s_setprio 0
	s_barrier
	s_add_u32 s34, s86, 0x8000
	s_addc_u32 s35, s87, 0
	s_add_i32 s88, s88, s44
	s_mov_b32 m0, s88
	ds_read_b128 v[174:177], v193 offset:49152
	ds_read_b128 v[178:181], v193 offset:50176
	ds_read_b128 v[182:185], v193 offset:51200
	ds_read_b128 v[186:189], v193 offset:52224
	ds_read_b128 v[194:197], v193 offset:53248
	ds_read_b128 v[198:201], v193 offset:54272
	ds_read_b128 v[202:205], v193 offset:55296
	ds_read_b128 v[206:209], v193 offset:56320
	global_load_lds_dwordx4 v162, s[34:35]
	s_add_i32 m0, s88, 0x2000
	v_lshl_add_u64 v[190:191], s[34:35], 0, v[158:159]
	s_add_u32 s34, s86, 0xc000
	s_addc_u32 s35, s87, 0
	s_add_i32 s86, s89, s44
	global_load_lds_dwordx4 v[190:191], off
	s_mov_b32 m0, s86
	s_nop 0
	global_load_lds_dwordx4 v162, s[34:35]
	s_add_i32 m0, s86, 0x2000
	s_nop 0
	global_load_lds_dwordx4 v158, s[34:35]
	s_mov_b32 m0, s85
	s_nop 0
	global_load_lds_dwordx4 v164, s[46:47]
	v_lshl_add_u64 v[190:191], s[46:47], 0, v[160:161]
	s_mov_b32 m0, s90
	s_nop 0
	global_load_lds_dwordx4 v[190:191], off
	s_waitcnt vmcnt(8)
	s_waitcnt lgkmcnt(0)
	s_setprio 1
	s_barrier
	v_mfma_f32_16x16x32_bf16 v[78:81], v[130:133], v[174:177], v[78:81]
	v_mfma_f32_16x16x32_bf16 v[78:81], v[134:137], v[178:181], v[78:81]
	v_mfma_f32_16x16x32_bf16 v[74:77], v[142:145], v[178:181], v[74:77]
	v_mfma_f32_16x16x32_bf16 v[74:77], v[138:141], v[174:177], v[74:77]
	v_mfma_f32_16x16x32_bf16 v[66:69], v[138:141], v[182:185], v[66:69]
	v_mfma_f32_16x16x32_bf16 v[66:69], v[142:145], v[186:189], v[66:69]
	v_mfma_f32_16x16x32_bf16 v[70:73], v[134:137], v[186:189], v[70:73]
	v_mfma_f32_16x16x32_bf16 v[70:73], v[130:133], v[182:185], v[70:73]
	v_mfma_f32_16x16x32_bf16 v[42:45], v[130:133], v[194:197], v[42:45]
	v_mfma_f32_16x16x32_bf16 v[42:45], v[134:137], v[198:201], v[42:45]
	v_mfma_f32_16x16x32_bf16 v[6:9], v[142:145], v[198:201], v[6:9]
	v_mfma_f32_16x16x32_bf16 v[6:9], v[138:141], v[194:197], v[6:9]
	v_mfma_f32_16x16x32_bf16 v[2:5], v[138:141], v[202:205], v[2:5]
	v_mfma_f32_16x16x32_bf16 v[2:5], v[142:145], v[206:209], v[2:5]
	v_mfma_f32_16x16x32_bf16 v[38:41], v[134:137], v[206:209], v[38:41]
	v_mfma_f32_16x16x32_bf16 v[38:41], v[130:133], v[202:205], v[38:41]
	s_setprio 0
	s_setprio 1
	v_mfma_f32_16x16x32_bf16 v[62:65], v[146:149], v[174:177], v[62:65]
	v_mfma_f32_16x16x32_bf16 v[62:65], v[150:153], v[178:181], v[62:65]
	v_mfma_f32_16x16x32_bf16 v[58:61], v[170:173], v[178:181], v[58:61]
	v_mfma_f32_16x16x32_bf16 v[58:61], v[154:157], v[174:177], v[58:61]
	v_mfma_f32_16x16x32_bf16 v[50:53], v[154:157], v[182:185], v[50:53]
	v_mfma_f32_16x16x32_bf16 v[50:53], v[170:173], v[186:189], v[50:53]
	v_mfma_f32_16x16x32_bf16 v[54:57], v[150:153], v[186:189], v[54:57]
	v_mfma_f32_16x16x32_bf16 v[54:57], v[146:149], v[182:185], v[54:57]
	v_mfma_f32_16x16x32_bf16 v[22:25], v[146:149], v[194:197], v[22:25]
	v_mfma_f32_16x16x32_bf16 v[22:25], v[150:153], v[198:201], v[22:25]
	v_mfma_f32_16x16x32_bf16 v[18:21], v[170:173], v[198:201], v[18:21]
	v_mfma_f32_16x16x32_bf16 v[18:21], v[154:157], v[194:197], v[18:21]
	v_mfma_f32_16x16x32_bf16 v[10:13], v[154:157], v[202:205], v[10:13]
	v_mfma_f32_16x16x32_bf16 v[10:13], v[170:173], v[206:209], v[10:13]
	v_mfma_f32_16x16x32_bf16 v[14:17], v[150:153], v[206:209], v[14:17]
	v_mfma_f32_16x16x32_bf16 v[14:17], v[146:149], v[202:205], v[14:17]
	s_setprio 0
	s_barrier
	s_add_i32 s66, s66, 2
	s_add_u32 vcc_hi, vcc_hi, 0x10000
	s_addc_u32 s65, s65, 0
	s_cmp_gt_u32 s66, 29
	s_mov_b64 s[34:35], s[36:37]
	s_cbranch_scc0 .LBB0_1256
	s_and_b64 vcc, exec, s[18:19]
	s_cbranch_vccz .LBB0_1259
	s_barrier

;     __host__ __device__ __forceinline__ bool next(int i, Unit& u) const { const int vv = vid + (i / 5) * G; if (vv >= 256) return false; u.pm = vv >> 2; u.pn = (vv & 3) + 4 * (i % 5); return true; }
; #define PG8_STAGE(bufoff, gbase, voff) do { _Pragma("unroll") for (int _i = 0; _i < 2; ++_i) \
;         __builtin_amdgcn_global_load_lds((const unsigned*)((const char*)(gbase) + (voff)[_i]), (PG8_LAS unsigned*)(lds + (bufoff) + ldsw + _i * 8192), 16, 0, 0); } while (0)
; #define PG8_LDA(dst, b, h) do { _Pragma("unroll") for (int m = 0; m < 4; ++m) _Pragma("unroll") for (int k = 0; k < 2; ++k) dst[m][k] = *(const PG8_LAS bf16x8*)(lds + PG8_SA(b, h) + aoff + m * 2048 + k * 1024); } while (0)
; #define PG8_LDB(dst, b, h) do { _Pragma("unroll") for (int n = 0; n < 2; ++n) _Pragma("unroll") for (int k = 0; k < 2; ++k) dst[n][k] = *(const PG8_LAS bf16x8*)(lds + PG8_SB(b, h) + boff + n * 2048 + k * 1024); } while (0)
; #define PG8_WAIT_V(n) asm volatile("s_waitcnt vmcnt(" #n ")" ::: "memory")
; #define PG8_WAIT_L(n) asm volatile("s_waitcnt lgkmcnt(" #n ")" ::: "memory")
; #define PG8_BAR __builtin_amdgcn_s_barrier()
;     ...
;         const bool has_next = S.next(ui + 1, nxt);
;         const char* nA = has_next ? (const char*)g.A + (size_t)nxt.pm * tstepA + (size_t)nxt.pn * APN + kofA : cA; const char* nB = has_next ? (const char*)g.Bt + (size_t)nxt.pn * tstepB + S.b_off(nxt) + kofB : cB;
;         for (int t = 0; t < nt; t += 2) {
;             const bool last = (t == nt - 2);
;             const char* a1 = cA + (ptrdiff_t)(t + 1) * kstepA;
;             const char* a2 = last ? nA : cA + (ptrdiff_t)(t + 2) * kstepA; const char* b2 = last ? nB : cB + (ptrdiff_t)(t + 2) * kstep;
;             const char* a3 = a2 + kstepA; const char* b3 = b2 + kstep;
;             if (last && has_next) S.a_ready(nxt);
;             if constexpr (SP2) {
;             PG8_LDB(B0, 0, 0); PG8_LDB(B1, 0, 1); PG8_SCHED; PG8_LDA(At, 0, 0); PG8_STAGE(PG8_SA(1, 1), a1 + hstepA, voffA);
;             PG8_WAIT_V(8); PG8_WAIT_L(0); PG8_BAR; PG8_MMA(0, 0, At, B0); PG8_MMA(0, 1, At, B1); PG8_BAR; PG8_SCHED;
;             PG8_LDA(At, 0, 1); PG8_STAGE(PG8_SB(0, 0), b2, voffB); PG8_STAGE(PG8_SB(0, 1), b2 + hstepB, voffB); PG8_STAGE(PG8_SA(0, 0), a2, voffA);
;             PG8_WAIT_V(8); PG8_WAIT_L(0); PG8_BAR; PG8_MMA(1, 0, At, B0); PG8_MMA(1, 1, At, B1); PG8_BAR; PG8_SCHED;
.Ldn_nostg:
	s_or_b32 s44, s56, 1
	s_lshl_b64 s[34:35], s[44:45], 15
	s_sub_u32 s34, 0, s34
	s_subb_u32 s35, 0, s35
	s_add_u32 s44, s28, s34
	s_addc_u32 s65, s29, s35
	s_add_u32 s34, s30, 0xffff8000
	s_addc_u32 s35, s31, -1
	s_add_i32 s66, 0, 0x10000
	v_add_u32_e32 v0, s66, v230
	s_add_i32 s90, 0, 0x14000
	s_waitcnt lgkmcnt(0)
	ds_read_b128 v[130:133], v0
	ds_read_b128 v[134:137], v0 offset:1024
	ds_read_b128 v[138:141], v0 offset:2048
	ds_read_b128 v[142:145], v0 offset:3072
	v_add_u32_e32 v0, s90, v230
	ds_read_b128 v[146:149], v0
	ds_read_b128 v[150:153], v0 offset:1024
	ds_read_b128 v[154:157], v0 offset:2048
	ds_read_b128 v[158:161], v0 offset:3072
	s_add_u32 s88, s44, 0x4000
	s_addc_u32 s89, s65, 0
	s_add_i32 m0, s46, 0xc000
	ds_read_b128 v[162:165], v231
	ds_read_b128 v[166:169], v231 offset:1024
	ds_read_b128 v[170:173], v231 offset:2048
	ds_read_b128 v[174:177], v231 offset:3072
	ds_read_b128 v[178:181], v231 offset:4096
	ds_read_b128 v[182:185], v231 offset:5120
	ds_read_b128 v[186:189], v231 offset:6144
	ds_read_b128 v[190:193], v231 offset:7168
	global_load_lds_dwordx4 v194, s[88:89]
	s_add_i32 m0, s46, 0xe000
	s_nop 0
	global_load_lds_dwordx4 v198, s[88:89]
	s_waitcnt vmcnt(8)
	s_waitcnt lgkmcnt(0)
	s_setprio 1
	s_barrier
	v_mfma_f32_16x16x32_bf16 v[126:129], v[130:133], v[162:165], 0
	v_mfma_f32_16x16x32_bf16 v[126:129], v[134:137], v[166:169], v[126:129]
	v_mfma_f32_16x16x32_bf16 v[122:125], v[142:145], v[166:169], 0
	v_mfma_f32_16x16x32_bf16 v[122:125], v[138:141], v[162:165], v[122:125]
	v_mfma_f32_16x16x32_bf16 v[106:109], v[138:141], v[170:173], 0
	v_mfma_f32_16x16x32_bf16 v[106:109], v[142:145], v[174:177], v[106:109]
	v_mfma_f32_16x16x32_bf16 v[110:113], v[134:137], v[174:177], 0
	v_mfma_f32_16x16x32_bf16 v[110:113], v[130:133], v[170:173], v[110:113]
	v_mfma_f32_16x16x32_bf16 v[94:97], v[130:133], v[178:181], 0
	v_mfma_f32_16x16x32_bf16 v[94:97], v[134:137], v[182:185], v[94:97]
	v_mfma_f32_16x16x32_bf16 v[90:93], v[142:145], v[182:185], 0
	v_mfma_f32_16x16x32_bf16 v[90:93], v[138:141], v[178:181], v[90:93]
	v_mfma_f32_16x16x32_bf16 v[74:77], v[138:141], v[186:189], 0
	v_mfma_f32_16x16x32_bf16 v[74:77], v[142:145], v[190:193], v[74:77]
	v_mfma_f32_16x16x32_bf16 v[78:81], v[134:137], v[190:193], 0
	v_mfma_f32_16x16x32_bf16 v[78:81], v[130:133], v[186:189], v[78:81]
	s_setprio 0
	s_setprio 1
	v_mfma_f32_16x16x32_bf16 v[118:121], v[146:149], v[162:165], 0
	v_mfma_f32_16x16x32_bf16 v[118:121], v[150:153], v[166:169], v[118:121]
	v_mfma_f32_16x16x32_bf16 v[114:117], v[158:161], v[166:169], 0
	v_mfma_f32_16x16x32_bf16 v[114:117], v[154:157], v[162:165], v[114:117]
	v_mfma_f32_16x16x32_bf16 v[98:101], v[154:157], v[170:173], 0
	v_mfma_f32_16x16x32_bf16 v[98:101], v[158:161], v[174:177], v[98:101]
	v_mfma_f32_16x16x32_bf16 v[102:105], v[150:153], v[174:177], 0
	v_mfma_f32_16x16x32_bf16 v[102:105], v[146:149], v[170:173], v[102:105]
	v_mfma_f32_16x16x32_bf16 v[86:89], v[146:149], v[178:181], 0
	v_mfma_f32_16x16x32_bf16 v[86:89], v[150:153], v[182:185], v[86:89]
	v_mfma_f32_16x16x32_bf16 v[82:85], v[158:161], v[182:185], 0
	v_mfma_f32_16x16x32_bf16 v[82:85], v[154:157], v[178:181], v[82:85]
	v_mfma_f32_16x16x32_bf16 v[66:69], v[154:157], v[186:189], 0
	v_mfma_f32_16x16x32_bf16 v[66:69], v[158:161], v[190:193], v[66:69]
	v_mfma_f32_16x16x32_bf16 v[70:73], v[150:153], v[190:193], 0
	v_mfma_f32_16x16x32_bf16 v[70:73], v[146:149], v[186:189], v[70:73]
	s_setprio 0
	s_barrier
	s_add_i32 s44, s66, s41
	s_mov_b32 m0, s44
	ds_read_b128 v[162:165], v231 offset:16384
	ds_read_b128 v[166:169], v231 offset:17408
	ds_read_b128 v[170:173], v231 offset:18432
	ds_read_b128 v[174:177], v231 offset:19456
	ds_read_b128 v[178:181], v231 offset:20480
	ds_read_b128 v[182:185], v231 offset:21504
	ds_read_b128 v[186:189], v231 offset:22528
	ds_read_b128 v[190:193], v231 offset:23552
	global_load_lds_dwordx4 v196, s[8:9]
	s_add_i32 m0, s44, 0x2000
	s_add_u32 s88, s8, 0x4000
	s_addc_u32 s89, s9, 0
	s_add_i32 s44, s90, s41
	global_load_lds_dwordx4 v200, s[8:9]
	s_mov_b32 m0, s44
	s_nop 0
	global_load_lds_dwordx4 v196, s[88:89]
	s_add_i32 m0, s44, 0x2000
	s_nop 0
	global_load_lds_dwordx4 v200, s[88:89]
	s_mov_b32 m0, s46
	s_nop 0
	global_load_lds_dwordx4 v194, s[30:31]
	s_mov_b32 m0, s47
	s_nop 0
	global_load_lds_dwordx4 v198, s[30:31]
	s_waitcnt vmcnt(8)
	s_waitcnt lgkmcnt(0)
	s_setprio 1
	s_barrier
	v_mfma_f32_16x16x32_bf16 v[62:65], v[130:133], v[162:165], 0
	v_mfma_f32_16x16x32_bf16 v[62:65], v[134:137], v[166:169], v[62:65]
	v_mfma_f32_16x16x32_bf16 v[58:61], v[142:145], v[166:169], 0
	v_mfma_f32_16x16x32_bf16 v[58:61], v[138:141], v[162:165], v[58:61]
	v_mfma_f32_16x16x32_bf16 v[42:45], v[138:141], v[170:173], 0
	v_mfma_f32_16x16x32_bf16 v[42:45], v[142:145], v[174:177], v[42:45]
	v_mfma_f32_16x16x32_bf16 v[46:49], v[134:137], v[174:177], 0
	v_mfma_f32_16x16x32_bf16 v[46:49], v[130:133], v[170:173], v[46:49]
	v_mfma_f32_16x16x32_bf16 v[30:33], v[130:133], v[178:181], 0
	v_mfma_f32_16x16x32_bf16 v[30:33], v[134:137], v[182:185], v[30:33]
	v_mfma_f32_16x16x32_bf16 v[26:29], v[142:145], v[182:185], 0
	v_mfma_f32_16x16x32_bf16 v[26:29], v[138:141], v[178:181], v[26:29]
	v_mfma_f32_16x16x32_bf16 v[10:13], v[138:141], v[186:189], 0
	v_mfma_f32_16x16x32_bf16 v[10:13], v[142:145], v[190:193], v[10:13]
	v_mfma_f32_16x16x32_bf16 v[14:17], v[134:137], v[190:193], 0
	v_mfma_f32_16x16x32_bf16 v[14:17], v[130:133], v[186:189], v[14:17]
	s_setprio 0
	s_setprio 1
	v_mfma_f32_16x16x32_bf16 v[54:57], v[146:149], v[162:165], 0
	v_mfma_f32_16x16x32_bf16 v[54:57], v[150:153], v[166:169], v[54:57]
	v_mfma_f32_16x16x32_bf16 v[50:53], v[158:161], v[166:169], 0
	v_mfma_f32_16x16x32_bf16 v[50:53], v[154:157], v[162:165], v[50:53]
	v_mfma_f32_16x16x32_bf16 v[34:37], v[154:157], v[170:173], 0
	v_mfma_f32_16x16x32_bf16 v[34:37], v[158:161], v[174:177], v[34:37]
	v_mfma_f32_16x16x32_bf16 v[38:41], v[150:153], v[174:177], 0
	v_mfma_f32_16x16x32_bf16 v[38:41], v[146:149], v[170:173], v[38:41]
	v_mfma_f32_16x16x32_bf16 v[22:25], v[146:149], v[178:181], 0
	v_mfma_f32_16x16x32_bf16 v[22:25], v[150:153], v[182:185], v[22:25]
	v_mfma_f32_16x16x32_bf16 v[18:21], v[158:161], v[182:185], 0
	v_mfma_f32_16x16x32_bf16 v[18:21], v[154:157], v[178:181], v[18:21]
	v_mfma_f32_16x16x32_bf16 v[2:5], v[154:157], v[186:189], 0
	v_mfma_f32_16x16x32_bf16 v[2:5], v[158:161], v[190:193], v[2:5]
	v_mfma_f32_16x16x32_bf16 v[6:9], v[150:153], v[190:193], 0
	v_mfma_f32_16x16x32_bf16 v[6:9], v[146:149], v[186:189], v[6:9]
	s_setprio 0
	s_barrier
	s_branch .Ldn_mid

; #define PG8_STAGE(bufoff, gbase, voff) do { _Pragma("unroll") for (int _i = 0; _i < 2; ++_i) \
;         __builtin_amdgcn_global_load_lds((const unsigned*)((const char*)(gbase) + (voff)[_i]), (PG8_LAS unsigned*)(lds + (bufoff) + ldsw + _i * 8192), 16, 0, 0); } while (0)
; #define PG8_LDA(dst, b, h) do { _Pragma("unroll") for (int m = 0; m < 4; ++m) _Pragma("unroll") for (int k = 0; k < 2; ++k) dst[m][k] = *(const PG8_LAS bf16x8*)(lds + PG8_SA(b, h) + aoff + m * 2048 + k * 1024); } while (0)
; #define PG8_LDB(dst, b, h) do { _Pragma("unroll") for (int n = 0; n < 2; ++n) _Pragma("unroll") for (int k = 0; k < 2; ++k) dst[n][k] = *(const PG8_LAS bf16x8*)(lds + PG8_SB(b, h) + boff + n * 2048 + k * 1024); } while (0)
; #define PG8_MMA(ai, bj, At, Bt) do { __builtin_amdgcn_s_setprio(1); _Pragma("unroll") for (int m = 0; m < 4; ++m) _Pragma("unroll") for (int n = 0; n < 2; ++n) _Pragma("unroll") for (int k = 0; k < 2; ++k) \
;         acc[ai][bj][m][n] = __builtin_amdgcn_mfma_f32_16x16x32_bf16(Bt[n][k], At[m][k], acc[ai][bj][m][n], 0, 0, 0); __builtin_amdgcn_s_setprio(0); } while (0)
; #define PG8_WAIT_V(n) asm volatile("s_waitcnt vmcnt(" #n ")" ::: "memory")
; #define PG8_WAIT_L(n) asm volatile("s_waitcnt lgkmcnt(" #n ")" ::: "memory")
; #define PG8_BAR __builtin_amdgcn_s_barrier()
; #define PG8_SCHED __builtin_amdgcn_sched_barrier(0)
;     ...
;             const bool last = (t == nt - 2);
;             const char* a1 = cA + (ptrdiff_t)(t + 1) * kstepA;
;             const char* a2 = last ? nA : cA + (ptrdiff_t)(t + 2) * kstepA; const char* b2 = last ? nB : cB + (ptrdiff_t)(t + 2) * kstep;
;             const char* a3 = a2 + kstepA; const char* b3 = b2 + kstep;
;             if (last && has_next) S.a_ready(nxt);
;             if constexpr (SP2) {
;             PG8_LDB(B0, 0, 0); PG8_LDB(B1, 0, 1); PG8_SCHED; PG8_LDA(At, 0, 0); PG8_STAGE(PG8_SA(1, 1), a1 + hstepA, voffA);
;             PG8_WAIT_V(8); PG8_WAIT_L(0); PG8_BAR; PG8_MMA(0, 0, At, B0); PG8_MMA(0, 1, At, B1); PG8_BAR; PG8_SCHED;
;             PG8_LDA(At, 0, 1); PG8_STAGE(PG8_SB(0, 0), b2, voffB); PG8_STAGE(PG8_SB(0, 1), b2 + hstepB, voffB); PG8_STAGE(PG8_SA(0, 0), a2, voffA);
;             PG8_WAIT_V(8); PG8_WAIT_L(0); PG8_BAR; PG8_MMA(1, 0, At, B0); PG8_MMA(1, 1, At, B1); PG8_BAR; PG8_SCHED;
.LBB0_1444:
	s_or_b32 s44, s56, 1
	s_lshl_b64 s[34:35], s[44:45], 15
	s_sub_u32 s34, 0, s34
	s_subb_u32 s35, 0, s35
	s_add_u32 s44, s28, s34
	s_addc_u32 s65, s29, s35
	s_add_u32 s34, s30, 0xffff8000
	s_addc_u32 s35, s31, -1
	s_add_i32 s66, 0, 0x10000
	v_add_u32_e32 v0, s66, v230
	s_add_i32 s90, 0, 0x14000
	s_waitcnt lgkmcnt(0)
	ds_read_b128 v[130:133], v0
	ds_read_b128 v[134:137], v0 offset:1024
	ds_read_b128 v[138:141], v0 offset:2048
	ds_read_b128 v[142:145], v0 offset:3072
	v_add_u32_e32 v0, s90, v230
	ds_read_b128 v[146:149], v0
	ds_read_b128 v[150:153], v0 offset:1024
	ds_read_b128 v[154:157], v0 offset:2048
	ds_read_b128 v[158:161], v0 offset:3072
	s_add_u32 s88, s44, 0x4000
	s_addc_u32 s89, s65, 0
	s_add_i32 m0, s46, 0xc000
	ds_read_b128 v[162:165], v231
	ds_read_b128 v[166:169], v231 offset:1024
	ds_read_b128 v[170:173], v231 offset:2048
	ds_read_b128 v[174:177], v231 offset:3072
	ds_read_b128 v[178:181], v231 offset:4096
	ds_read_b128 v[182:185], v231 offset:5120
	ds_read_b128 v[186:189], v231 offset:6144
	ds_read_b128 v[190:193], v231 offset:7168
	global_load_lds_dwordx4 v194, s[88:89]
	s_add_i32 m0, s46, 0xe000
	s_nop 0
	global_load_lds_dwordx4 v198, s[88:89]
	s_waitcnt vmcnt(8)
	s_waitcnt lgkmcnt(0)
	s_setprio 1
	s_barrier
	v_mfma_f32_16x16x32_bf16 v[126:129], v[130:133], v[162:165], v[126:129]
	v_mfma_f32_16x16x32_bf16 v[126:129], v[134:137], v[166:169], v[126:129]
	v_mfma_f32_16x16x32_bf16 v[122:125], v[142:145], v[166:169], v[122:125]
	v_mfma_f32_16x16x32_bf16 v[122:125], v[138:141], v[162:165], v[122:125]
	v_mfma_f32_16x16x32_bf16 v[106:109], v[138:141], v[170:173], v[106:109]
	v_mfma_f32_16x16x32_bf16 v[106:109], v[142:145], v[174:177], v[106:109]
	v_mfma_f32_16x16x32_bf16 v[110:113], v[134:137], v[174:177], v[110:113]
	v_mfma_f32_16x16x32_bf16 v[110:113], v[130:133], v[170:173], v[110:113]
	v_mfma_f32_16x16x32_bf16 v[94:97], v[130:133], v[178:181], v[94:97]
	v_mfma_f32_16x16x32_bf16 v[94:97], v[134:137], v[182:185], v[94:97]
	v_mfma_f32_16x16x32_bf16 v[90:93], v[142:145], v[182:185], v[90:93]
	v_mfma_f32_16x16x32_bf16 v[90:93], v[138:141], v[178:181], v[90:93]
	v_mfma_f32_16x16x32_bf16 v[74:77], v[138:141], v[186:189], v[74:77]
	v_mfma_f32_16x16x32_bf16 v[74:77], v[142:145], v[190:193], v[74:77]
	v_mfma_f32_16x16x32_bf16 v[78:81], v[134:137], v[190:193], v[78:81]
	v_mfma_f32_16x16x32_bf16 v[78:81], v[130:133], v[186:189], v[78:81]
	s_setprio 0
	s_setprio 1
	v_mfma_f32_16x16x32_bf16 v[118:121], v[146:149], v[162:165], v[118:121]
	v_mfma_f32_16x16x32_bf16 v[118:121], v[150:153], v[166:169], v[118:121]
	v_mfma_f32_16x16x32_bf16 v[114:117], v[158:161], v[166:169], v[114:117]
	v_mfma_f32_16x16x32_bf16 v[114:117], v[154:157], v[162:165], v[114:117]
	v_mfma_f32_16x16x32_bf16 v[98:101], v[154:157], v[170:173], v[98:101]
	v_mfma_f32_16x16x32_bf16 v[98:101], v[158:161], v[174:177], v[98:101]
	v_mfma_f32_16x16x32_bf16 v[102:105], v[150:153], v[174:177], v[102:105]
	v_mfma_f32_16x16x32_bf16 v[102:105], v[146:149], v[170:173], v[102:105]
	v_mfma_f32_16x16x32_bf16 v[86:89], v[146:149], v[178:181], v[86:89]
	v_mfma_f32_16x16x32_bf16 v[86:89], v[150:153], v[182:185], v[86:89]
	v_mfma_f32_16x16x32_bf16 v[82:85], v[158:161], v[182:185], v[82:85]
	v_mfma_f32_16x16x32_bf16 v[82:85], v[154:157], v[178:181], v[82:85]
	v_mfma_f32_16x16x32_bf16 v[66:69], v[154:157], v[186:189], v[66:69]
	v_mfma_f32_16x16x32_bf16 v[66:69], v[158:161], v[190:193], v[66:69]
	v_mfma_f32_16x16x32_bf16 v[70:73], v[150:153], v[190:193], v[70:73]
	v_mfma_f32_16x16x32_bf16 v[70:73], v[146:149], v[186:189], v[70:73]
	s_setprio 0
	s_barrier
	s_add_i32 s44, s66, s41
	s_mov_b32 m0, s44
	ds_read_b128 v[162:165], v231 offset:16384
	ds_read_b128 v[166:169], v231 offset:17408
	ds_read_b128 v[170:173], v231 offset:18432
	ds_read_b128 v[174:177], v231 offset:19456
	ds_read_b128 v[178:181], v231 offset:20480
	ds_read_b128 v[182:185], v231 offset:21504
	ds_read_b128 v[186:189], v231 offset:22528
	ds_read_b128 v[190:193], v231 offset:23552
	global_load_lds_dwordx4 v196, s[8:9]
	s_add_i32 m0, s44, 0x2000
	s_add_u32 s88, s8, 0x4000
	s_addc_u32 s89, s9, 0
	s_add_i32 s44, s90, s41
	global_load_lds_dwordx4 v200, s[8:9]
	s_mov_b32 m0, s44
	s_nop 0
	global_load_lds_dwordx4 v196, s[88:89]
	s_add_i32 m0, s44, 0x2000
	s_nop 0
	global_load_lds_dwordx4 v200, s[88:89]
	s_mov_b32 m0, s46
	s_nop 0
	global_load_lds_dwordx4 v194, s[30:31]
	s_mov_b32 m0, s47
	s_nop 0
	global_load_lds_dwordx4 v198, s[30:31]
	s_waitcnt vmcnt(8)
	s_waitcnt lgkmcnt(0)
	s_setprio 1
	s_barrier
	v_mfma_f32_16x16x32_bf16 v[62:65], v[130:133], v[162:165], v[62:65]
	v_mfma_f32_16x16x32_bf16 v[62:65], v[134:137], v[166:169], v[62:65]
	v_mfma_f32_16x16x32_bf16 v[58:61], v[142:145], v[166:169], v[58:61]
	v_mfma_f32_16x16x32_bf16 v[58:61], v[138:141], v[162:165], v[58:61]
	v_mfma_f32_16x16x32_bf16 v[42:45], v[138:141], v[170:173], v[42:45]
	v_mfma_f32_16x16x32_bf16 v[42:45], v[142:145], v[174:177], v[42:45]
	v_mfma_f32_16x16x32_bf16 v[46:49], v[134:137], v[174:177], v[46:49]
	v_mfma_f32_16x16x32_bf16 v[46:49], v[130:133], v[170:173], v[46:49]
	v_mfma_f32_16x16x32_bf16 v[30:33], v[130:133], v[178:181], v[30:33]
	v_mfma_f32_16x16x32_bf16 v[30:33], v[134:137], v[182:185], v[30:33]
	v_mfma_f32_16x16x32_bf16 v[26:29], v[142:145], v[182:185], v[26:29]
	v_mfma_f32_16x16x32_bf16 v[26:29], v[138:141], v[178:181], v[26:29]
	v_mfma_f32_16x16x32_bf16 v[10:13], v[138:141], v[186:189], v[10:13]
	v_mfma_f32_16x16x32_bf16 v[10:13], v[142:145], v[190:193], v[10:13]
	v_mfma_f32_16x16x32_bf16 v[14:17], v[134:137], v[190:193], v[14:17]
	v_mfma_f32_16x16x32_bf16 v[14:17], v[130:133], v[186:189], v[14:17]
	s_setprio 0
	s_setprio 1
	v_mfma_f32_16x16x32_bf16 v[54:57], v[146:149], v[162:165], v[54:57]
	v_mfma_f32_16x16x32_bf16 v[54:57], v[150:153], v[166:169], v[54:57]
	v_mfma_f32_16x16x32_bf16 v[50:53], v[158:161], v[166:169], v[50:53]
	v_mfma_f32_16x16x32_bf16 v[50:53], v[154:157], v[162:165], v[50:53]
	v_mfma_f32_16x16x32_bf16 v[34:37], v[154:157], v[170:173], v[34:37]
	v_mfma_f32_16x16x32_bf16 v[34:37], v[158:161], v[174:177], v[34:37]
	v_mfma_f32_16x16x32_bf16 v[38:41], v[150:153], v[174:177], v[38:41]
	v_mfma_f32_16x16x32_bf16 v[38:41], v[146:149], v[170:173], v[38:41]
	v_mfma_f32_16x16x32_bf16 v[22:25], v[146:149], v[178:181], v[22:25]
	v_mfma_f32_16x16x32_bf16 v[22:25], v[150:153], v[182:185], v[22:25]
	v_mfma_f32_16x16x32_bf16 v[18:21], v[158:161], v[182:185], v[18:21]
	v_mfma_f32_16x16x32_bf16 v[18:21], v[154:157], v[178:181], v[18:21]
	v_mfma_f32_16x16x32_bf16 v[2:5], v[154:157], v[186:189], v[2:5]
	v_mfma_f32_16x16x32_bf16 v[2:5], v[158:161], v[190:193], v[2:5]
	v_mfma_f32_16x16x32_bf16 v[6:9], v[150:153], v[190:193], v[6:9]
	v_mfma_f32_16x16x32_bf16 v[6:9], v[146:149], v[186:189], v[6:9]
	s_setprio 0
	s_barrier
; #define PG8_STAGE(bufoff, gbase, voff) do { _Pragma("unroll") for (int _i = 0; _i < 2; ++_i) \
;         __builtin_amdgcn_global_load_lds((const unsigned*)((const char*)(gbase) + (voff)[_i]), (PG8_LAS unsigned*)(lds + (bufoff) + ldsw + _i * 8192), 16, 0, 0); } while (0)
; #define PG8_LDA(dst, b, h) do { _Pragma("unroll") for (int m = 0; m < 4; ++m) _Pragma("unroll") for (int k = 0; k < 2; ++k) dst[m][k] = *(const PG8_LAS bf16x8*)(lds + PG8_SA(b, h) + aoff + m * 2048 + k * 1024); } while (0)
; #define PG8_LDB(dst, b, h) do { _Pragma("unroll") for (int n = 0; n < 2; ++n) _Pragma("unroll") for (int k = 0; k < 2; ++k) dst[n][k] = *(const PG8_LAS bf16x8*)(lds + PG8_SB(b, h) + boff + n * 2048 + k * 1024); } while (0)
; #define PG8_WAIT_V(n) asm volatile("s_waitcnt vmcnt(" #n ")" ::: "memory")
; #define PG8_WAIT_L(n) asm volatile("s_waitcnt lgkmcnt(" #n ")" ::: "memory")
; #define PG8_BAR __builtin_amdgcn_s_barrier()
; #define PG8_SCHED __builtin_amdgcn_sched_barrier(0)
;     ...
;             const char* a2 = last ? nA : cA + (ptrdiff_t)(t + 2) * kstepA; const char* b2 = last ? nB : cB + (ptrdiff_t)(t + 2) * kstep;
;             const char* a3 = a2 + kstepA; const char* b3 = b2 + kstep;
;             if (last && has_next) S.a_ready(nxt);
;             if constexpr (SP2) {
;             PG8_LDB(B0, 0, 0); PG8_LDB(B1, 0, 1); PG8_SCHED; PG8_LDA(At, 0, 0); PG8_STAGE(PG8_SA(1, 1), a1 + hstepA, voffA);
;             PG8_WAIT_V(8); PG8_WAIT_L(0); PG8_BAR; PG8_MMA(0, 0, At, B0); PG8_MMA(0, 1, At, B1); PG8_BAR; PG8_SCHED;
;             PG8_LDA(At, 0, 1); PG8_STAGE(PG8_SB(0, 0), b2, voffB); PG8_STAGE(PG8_SB(0, 1), b2 + hstepB, voffB); PG8_STAGE(PG8_SA(0, 0), a2, voffA);
;             PG8_WAIT_V(8); PG8_WAIT_L(0); PG8_BAR; PG8_MMA(1, 0, At, B0); PG8_MMA(1, 1, At, B1); PG8_BAR; PG8_SCHED;
;             PG8_LDB(B0, 1, 0); PG8_LDB(B1, 1, 1); PG8_SCHED; PG8_LDA(At, 1, 0); PG8_STAGE(PG8_SA(0, 1), a2 + hstepA, voffA);
;             PG8_WAIT_V(8); PG8_WAIT_L(0); PG8_BAR; PG8_MMA(0, 0, At, B0); PG8_MMA(0, 1, At, B1); PG8_BAR; PG8_SCHED;
;             PG8_LDA(At, 1, 1); PG8_STAGE(PG8_SB(1, 0), b3, voffB); PG8_STAGE(PG8_SB(1, 1), b3 + hstepB, voffB); PG8_STAGE(PG8_SA(1, 0), a3, voffA);
;             PG8_WAIT_V(8); PG8_WAIT_L(0); PG8_BAR; PG8_MMA(1, 0, At, B0); PG8_MMA(1, 1, At, B1); PG8_BAR; PG8_SCHED;
.Ldn_mid:
	s_add_i32 s44, 0, 0x18000
	v_add_u32_e32 v0, s44, v230
	s_add_i32 s65, 0, 0x1c000
	ds_read_b128 v[130:133], v0
	ds_read_b128 v[134:137], v0 offset:1024
	ds_read_b128 v[138:141], v0 offset:2048
	ds_read_b128 v[142:145], v0 offset:3072
	v_add_u32_e32 v0, s65, v230
	ds_read_b128 v[146:149], v0
	ds_read_b128 v[150:153], v0 offset:1024
	ds_read_b128 v[154:157], v0 offset:2048
	ds_read_b128 v[158:161], v0 offset:3072
	s_add_u32 s30, s30, 0x4000
	s_addc_u32 s31, s31, 0
	s_mov_b32 m0, s48
	ds_read_b128 v[162:165], v231 offset:32768
	ds_read_b128 v[166:169], v231 offset:33792
	ds_read_b128 v[170:173], v231 offset:34816
	ds_read_b128 v[174:177], v231 offset:35840
	ds_read_b128 v[178:181], v231 offset:36864
	ds_read_b128 v[182:185], v231 offset:37888
	ds_read_b128 v[186:189], v231 offset:38912
	ds_read_b128 v[190:193], v231 offset:39936
	global_load_lds_dwordx4 v194, s[30:31]
	s_mov_b32 m0, s49
	s_nop 0
	global_load_lds_dwordx4 v198, s[30:31]
	s_waitcnt vmcnt(8)
	s_waitcnt lgkmcnt(0)
	s_setprio 1
	s_barrier
	v_mfma_f32_16x16x32_bf16 v[126:129], v[130:133], v[162:165], v[126:129]
	v_mfma_f32_16x16x32_bf16 v[126:129], v[134:137], v[166:169], v[126:129]
	v_mfma_f32_16x16x32_bf16 v[122:125], v[142:145], v[166:169], v[122:125]
	v_mfma_f32_16x16x32_bf16 v[122:125], v[138:141], v[162:165], v[122:125]
	v_mfma_f32_16x16x32_bf16 v[106:109], v[138:141], v[170:173], v[106:109]
	v_mfma_f32_16x16x32_bf16 v[106:109], v[142:145], v[174:177], v[106:109]
	v_mfma_f32_16x16x32_bf16 v[110:113], v[134:137], v[174:177], v[110:113]
	v_mfma_f32_16x16x32_bf16 v[110:113], v[130:133], v[170:173], v[110:113]
	v_mfma_f32_16x16x32_bf16 v[94:97], v[130:133], v[178:181], v[94:97]
	v_mfma_f32_16x16x32_bf16 v[94:97], v[134:137], v[182:185], v[94:97]
	v_mfma_f32_16x16x32_bf16 v[90:93], v[142:145], v[182:185], v[90:93]
	v_mfma_f32_16x16x32_bf16 v[90:93], v[138:141], v[178:181], v[90:93]
	v_mfma_f32_16x16x32_bf16 v[74:77], v[138:141], v[186:189], v[74:77]
	v_mfma_f32_16x16x32_bf16 v[74:77], v[142:145], v[190:193], v[74:77]
	v_mfma_f32_16x16x32_bf16 v[78:81], v[134:137], v[190:193], v[78:81]
	v_mfma_f32_16x16x32_bf16 v[78:81], v[130:133], v[186:189], v[78:81]
	s_setprio 0
	s_setprio 1
	v_mfma_f32_16x16x32_bf16 v[118:121], v[146:149], v[162:165], v[118:121]
	v_mfma_f32_16x16x32_bf16 v[118:121], v[150:153], v[166:169], v[118:121]
	v_mfma_f32_16x16x32_bf16 v[114:117], v[158:161], v[166:169], v[114:117]
	v_mfma_f32_16x16x32_bf16 v[114:117], v[154:157], v[162:165], v[114:117]
	v_mfma_f32_16x16x32_bf16 v[98:101], v[154:157], v[170:173], v[98:101]
	v_mfma_f32_16x16x32_bf16 v[98:101], v[158:161], v[174:177], v[98:101]
	v_mfma_f32_16x16x32_bf16 v[102:105], v[150:153], v[174:177], v[102:105]
	v_mfma_f32_16x16x32_bf16 v[102:105], v[146:149], v[170:173], v[102:105]
	v_mfma_f32_16x16x32_bf16 v[86:89], v[146:149], v[178:181], v[86:89]
	v_mfma_f32_16x16x32_bf16 v[86:89], v[150:153], v[182:185], v[86:89]
	v_mfma_f32_16x16x32_bf16 v[82:85], v[158:161], v[182:185], v[82:85]
	v_mfma_f32_16x16x32_bf16 v[82:85], v[154:157], v[178:181], v[82:85]
	v_mfma_f32_16x16x32_bf16 v[66:69], v[154:157], v[186:189], v[66:69]
	v_mfma_f32_16x16x32_bf16 v[66:69], v[158:161], v[190:193], v[66:69]
	v_mfma_f32_16x16x32_bf16 v[70:73], v[150:153], v[190:193], v[70:73]
	v_mfma_f32_16x16x32_bf16 v[70:73], v[146:149], v[186:189], v[70:73]
	s_setprio 0
	s_barrier
	s_add_u32 s30, s8, 0xffff8000
	s_addc_u32 s31, s9, -1
	s_add_i32 s44, s44, s41
	s_mov_b32 m0, s44
	ds_read_b128 v[162:165], v231 offset:49152
	ds_read_b128 v[166:169], v231 offset:50176
	ds_read_b128 v[170:173], v231 offset:51200
	ds_read_b128 v[174:177], v231 offset:52224
	ds_read_b128 v[178:181], v231 offset:53248
	ds_read_b128 v[182:185], v231 offset:54272
	ds_read_b128 v[186:189], v231 offset:55296
	ds_read_b128 v[190:193], v231 offset:56320
	global_load_lds_dwordx4 v196, s[30:31]
	s_add_i32 m0, s44, 0x2000
	s_add_u32 s8, s8, 0xffffc000
	v_lshl_add_u64 v[202:203], s[30:31], 0, v[200:201]
	s_addc_u32 s9, s9, -1
	s_add_i32 s30, s65, s41
	global_load_lds_dwordx4 v[202:203], off
	s_mov_b32 m0, s30
	s_nop 0
	global_load_lds_dwordx4 v196, s[8:9]
	s_add_i32 m0, s30, 0x2000
	s_nop 0
	global_load_lds_dwordx4 v200, s[8:9]
	s_mov_b32 m0, s71
	s_nop 0
	global_load_lds_dwordx4 v194, s[34:35]
	v_lshl_add_u64 v[202:203], s[34:35], 0, v[198:199]
	s_mov_b32 m0, s80
	s_nop 0
	global_load_lds_dwordx4 v[202:203], off
	s_waitcnt vmcnt(8)
	s_waitcnt lgkmcnt(0)
	s_setprio 1
	s_barrier
	v_mfma_f32_16x16x32_bf16 v[62:65], v[130:133], v[162:165], v[62:65]
	v_mfma_f32_16x16x32_bf16 v[62:65], v[134:137], v[166:169], v[62:65]
	v_mfma_f32_16x16x32_bf16 v[58:61], v[142:145], v[166:169], v[58:61]
	v_mfma_f32_16x16x32_bf16 v[58:61], v[138:141], v[162:165], v[58:61]
	v_mfma_f32_16x16x32_bf16 v[42:45], v[138:141], v[170:173], v[42:45]
	v_mfma_f32_16x16x32_bf16 v[42:45], v[142:145], v[174:177], v[42:45]
	v_mfma_f32_16x16x32_bf16 v[46:49], v[134:137], v[174:177], v[46:49]
	v_mfma_f32_16x16x32_bf16 v[46:49], v[130:133], v[170:173], v[46:49]
	v_mfma_f32_16x16x32_bf16 v[30:33], v[130:133], v[178:181], v[30:33]
	v_mfma_f32_16x16x32_bf16 v[30:33], v[134:137], v[182:185], v[30:33]
	v_mfma_f32_16x16x32_bf16 v[26:29], v[142:145], v[182:185], v[26:29]
	v_mfma_f32_16x16x32_bf16 v[26:29], v[138:141], v[178:181], v[26:29]
	v_mfma_f32_16x16x32_bf16 v[10:13], v[138:141], v[186:189], v[10:13]
	v_mfma_f32_16x16x32_bf16 v[10:13], v[142:145], v[190:193], v[10:13]
	v_mfma_f32_16x16x32_bf16 v[14:17], v[134:137], v[190:193], v[14:17]
	v_mfma_f32_16x16x32_bf16 v[14:17], v[130:133], v[186:189], v[14:17]
	s_setprio 0
	s_setprio 1
	v_mfma_f32_16x16x32_bf16 v[54:57], v[146:149], v[162:165], v[54:57]
	v_mfma_f32_16x16x32_bf16 v[54:57], v[150:153], v[166:169], v[54:57]
	v_mfma_f32_16x16x32_bf16 v[50:53], v[158:161], v[166:169], v[50:53]
	v_mfma_f32_16x16x32_bf16 v[50:53], v[154:157], v[162:165], v[50:53]
	v_mfma_f32_16x16x32_bf16 v[34:37], v[154:157], v[170:173], v[34:37]
	v_mfma_f32_16x16x32_bf16 v[34:37], v[158:161], v[174:177], v[34:37]
	v_mfma_f32_16x16x32_bf16 v[38:41], v[150:153], v[174:177], v[38:41]
	v_mfma_f32_16x16x32_bf16 v[38:41], v[146:149], v[170:173], v[38:41]
	v_mfma_f32_16x16x32_bf16 v[22:25], v[146:149], v[178:181], v[22:25]
	v_mfma_f32_16x16x32_bf16 v[22:25], v[150:153], v[182:185], v[22:25]
	v_mfma_f32_16x16x32_bf16 v[18:21], v[158:161], v[182:185], v[18:21]
	v_mfma_f32_16x16x32_bf16 v[18:21], v[154:157], v[178:181], v[18:21]
	v_mfma_f32_16x16x32_bf16 v[2:5], v[154:157], v[186:189], v[2:5]
	v_mfma_f32_16x16x32_bf16 v[2:5], v[158:161], v[190:193], v[2:5]
	v_mfma_f32_16x16x32_bf16 v[6:9], v[150:153], v[190:193], v[6:9]
	v_mfma_f32_16x16x32_bf16 v[6:9], v[146:149], v[186:189], v[6:9]
	s_setprio 0
	s_barrier
	s_cmpk_gt_u32 s56, 0x55
	s_mov_b32 s56, s57
	s_cbranch_scc1 .LBB0_1449
